# CAT/W_out K-block swap so the out-projection consumes the P5 output last; P5->P6 seam split-phase: nobody waits, wave 0 checks the generation word and acquires before K-tile 24
# speedup vs baseline: 1.0066x; 1.0037x over previous
; __device__ __forceinline__ TPItem tp_decode(const Params& p, int it, int tid) {
;     constexpr int T_IN = 32 * 96, T_OUT = 32 * 32, T_S = 64, T_L = T_IN + T_OUT + T_S;
;     const int l = it / T_L; int r = it % T_L; const float* W; bf16* WT; int K, N, kb, nb;
;     if (r < T_IN) { W = p.w_in + (size_t)l * DM * DIN; WT = (bf16*)(p.ws + WS_WIN) + (size_t)l * WROWS * DM; K = DM; N = DIN; kb = r / 96; nb = 8 + r % 96; }
;     else if (r < T_IN + T_OUT) { r -= T_IN; W = p.w_out + (size_t)l * DM * DM; WT = (bf16*)(p.ws + WS_WOUT) + (size_t)l * DM * DM; K = DM; N = DM; kb = r >> 5; nb = r & 31; }
;     else { r -= T_IN + T_OUT; W = p.w_pw + (size_t)l * DG * DG; WT = (bf16*)(p.ws + WS_WPW) + (size_t)l * DG * DG; K = DG; N = DG; kb = r >> 3; nb = r & 7; }
;     TPItem t; t.N = N; t.K = K;
;     t.src = W + (size_t)(kb * 64 + (tid >> 4)) * N + nb * 64 + (tid & 15) * 4;
;     t.dst = WT + (size_t)(nb * 64 + (tid >> 3)) * K + kb * 64 + (tid & 7) * 8;
.LBB0_32:
	s_andn2_b64 vcc, exec, s[40:41]
	s_mov_b64 s[40:41], 0x200
	s_cbranch_vccnz .LBB0_34
	s_add_i32 s40, s50, 0xfffff400
	s_lshl_b64 s[28:29], s[38:39], 24
	s_add_u32 s36, s6, s28
	s_addc_u32 s37, s7, s29
	s_lshl_b64 s[28:29], s[38:39], 23
	s_add_u32 s28, s48, s28
	s_addc_u32 s29, s49, s29
	s_lshr_b32 s52, s40, 5
	s_lshr_b32 s38, s52, 3
	s_cmp_eq_u32 s38, 0
	s_cselect_b32 s39, 0xc00, 0
	s_add_u32 s28, s28, s39
	s_addc_u32 s29, s29, 0
	s_cmp_eq_u32 s38, 3
	s_cselect_b32 s39, 0xc00, 0
	s_sub_u32 s28, s28, s39
	s_subb_u32 s29, s29, 0
	s_and_b32 s51, s50, 31
	s_mov_b64 s[40:41], 0x800

; __device__ __forceinline__ TPItem tp_decode(const Params& p, int it, int tid) {
;     constexpr int T_IN = 32 * 96, T_OUT = 32 * 32, T_S = 64, T_L = T_IN + T_OUT + T_S;
;     const int l = it / T_L; int r = it % T_L; const float* W; bf16* WT; int K, N, kb, nb;
;     if (r < T_IN) { W = p.w_in + (size_t)l * DM * DIN; WT = (bf16*)(p.ws + WS_WIN) + (size_t)l * WROWS * DM; K = DM; N = DIN; kb = r / 96; nb = 8 + r % 96; }
;     else if (r < T_IN + T_OUT) { r -= T_IN; W = p.w_out + (size_t)l * DM * DM; WT = (bf16*)(p.ws + WS_WOUT) + (size_t)l * DM * DM; K = DM; N = DM; kb = r >> 5; nb = r & 31; }
;     else { r -= T_IN + T_OUT; W = p.w_pw + (size_t)l * DG * DG; WT = (bf16*)(p.ws + WS_WPW) + (size_t)l * DG * DG; K = DG; N = DG; kb = r >> 3; nb = r & 7; }
;     TPItem t; t.N = N; t.K = K;
;     t.src = W + (size_t)(kb * 64 + (tid >> 4)) * N + nb * 64 + (tid & 15) * 4;
;     t.dst = WT + (size_t)(nb * 64 + (tid >> 3)) * K + kb * 64 + (tid & 7) * 8;
.LBB0_113:
.LBB0_114:
	s_add_i32 s28, s30, 0xfffff400
	s_lshl_b64 s[8:9], s[38:39], 24
	s_waitcnt lgkmcnt(0)
	s_add_u32 s36, s6, s8
	s_addc_u32 s37, s7, s9
	s_lshl_b64 s[8:9], s[38:39], 23
	s_add_u32 s8, s26, s8
	s_addc_u32 s9, s27, s9
	s_add_u32 s8, s8, 0x3c00000
	s_addc_u32 s9, s9, 0
	s_lshr_b32 s43, s28, 5
	s_lshr_b32 s40, s43, 3
	s_cmp_eq_u32 s40, 0
	s_cselect_b32 s41, 0xc00, 0
	s_add_u32 s8, s8, s41
	s_addc_u32 s9, s9, 0
	s_cmp_eq_u32 s40, 3
	s_cselect_b32 s41, 0xc00, 0
	s_sub_u32 s8, s8, s41
	s_subb_u32 s9, s9, 0
	s_and_b32 s42, s30, 31
	s_mov_b64 s[28:29], 0x800
	s_movk_i32 s39, 0x800
	s_cbranch_execz .LBB0_24
	s_branch .LBB0_25

; __device__ __forceinline__ unsigned cvt_pk_bf16(float lo, float hi) { unsigned r; asm volatile("v_cvt_pk_bf16_f32 %0, %1, %2" : "=v"(r) : "v"(lo), "v"(hi)); return r; }
; __device__ __forceinline__ float bflo(unsigned u) { return __uint_as_float(u << 16); }
; __device__ __forceinline__ float bfhi(unsigned u) { return __uint_as_float(u & 0xffff0000u); }
; __device__ __forceinline__ float silu_f(float v) { return v / (1.f + __expf(-v)); }
;     __device__ __forceinline__ void operator()(const pg8::f32x4 (&acc)[2][2][4][2], const pg8::Unit& u, int wr, int wc, int fr, int fq) const {
;     ...
;             for (int m = 0; m < 4; ++m) { const size_t row = (size_t)(row0 + ai * 128 + m * 16);
; #pragma unroll
;                 for (int bj = 0; bj < 2; ++bj) { const pg8::f32x4 v0 = acc[ai][bj][m][0], v1 = acc[ai][bj][m][1];
;                     const u32x4 gz = *(const u32x4*)(Z + row * DIN + goff + col0 + bj * 128); u32x4 w;
;                     w.x = pg8::cvt_pk_bf16(v0[0] * silu_f(bflo(gz.x)), v0[1] * silu_f(bfhi(gz.x))); w.y = pg8::cvt_pk_bf16(v0[2] * silu_f(bflo(gz.y)), v0[3] * silu_f(bfhi(gz.y)));
;                     w.z = pg8::cvt_pk_bf16(v1[0] * silu_f(bflo(gz.z)), v1[1] * silu_f(bfhi(gz.z))); w.w = pg8::cvt_pk_bf16(v1[2] * silu_f(bflo(gz.w)), v1[3] * silu_f(bfhi(gz.w)));
;                     *(u32x4*)(O + row * DM + coff + col0 + bj * 128) = w; } }
.LBB0_555:
	v_readlane_b32 s12, v254, 0
	v_lshl_or_b32 v130, s50, 8, v170
	v_readlane_b32 s13, v254, 1
	v_lshl_add_u32 v160, s52, 8, v168
	v_ashrrev_i32_e32 v131, 31, v130
	v_mov_b64_e32 v[162:163], s[12:13]
	v_mad_i64_i32 v[132:133], s[12:13], v160, s75, v[162:163]
	v_lshlrev_b64 v[144:145], 1, v[130:131]
	v_lshl_add_u64 v[130:131], v[132:133], 0, v[144:145]
	s_mov_b64 s[26:27], 0x3000
	v_lshl_add_u64 v[166:167], v[130:131], 0, s[26:27]
	v_add_co_u32_e32 v130, vcc, 0x3000, v130
	v_ashrrev_i32_e32 v161, 31, v160
	s_nop 0
	v_addc_co_u32_e32 v131, vcc, 0, v131, vcc
	global_load_dwordx4 v[130:133], v[130:131], off
	v_lshlrev_b64 v[164:165], 12, v[160:161]
	s_mov_b64 s[50:51], -1
	s_waitcnt vmcnt(0)
	v_lshlrev_b32_e32 v161, 16, v130
	v_mul_f32_e32 v172, 0xbfb8aa3b, v161
	v_exp_f32_e32 v172, v172
	v_and_b32_e32 v130, 0xffff0000, v130
	v_add_f32_e32 v172, 1.0, v172
	v_div_scale_f32 v173, s[12:13], v172, v172, v161
	v_rcp_f32_e32 v174, v173
	s_nop 0
	v_fma_f32 v175, -v173, v174, 1.0
	v_fmac_f32_e32 v174, v175, v174
	v_div_scale_f32 v175, vcc, v161, v172, v161
	v_mul_f32_e32 v176, v175, v174
	v_fma_f32 v177, -v173, v176, v175
	v_fmac_f32_e32 v176, v177, v174
	v_fma_f32 v173, -v173, v176, v175
	v_div_fmas_f32 v173, v173, v174, v176
	v_div_fixup_f32 v161, v173, v172, v161
	v_mul_f32_e32 v126, v126, v161
	v_mul_f32_e32 v161, 0xbfb8aa3b, v130
	v_exp_f32_e32 v161, v161
	s_nop 0
	v_add_f32_e32 v161, 1.0, v161
	v_div_scale_f32 v172, s[12:13], v161, v161, v130
	v_rcp_f32_e32 v173, v172
	s_nop 0
	v_fma_f32 v174, -v172, v173, 1.0
	v_fmac_f32_e32 v173, v174, v173
	v_div_scale_f32 v174, vcc, v130, v161, v130
	v_mul_f32_e32 v175, v174, v173
	v_fma_f32 v176, -v172, v175, v174
	v_fmac_f32_e32 v175, v176, v173
	v_fma_f32 v172, -v172, v175, v174
	v_div_fmas_f32 v172, v172, v173, v175
	v_div_fixup_f32 v130, v172, v161, v130
	v_mul_f32_e32 v127, v127, v130
	v_cvt_pk_bf16_f32 v126, v126, v127
	v_lshlrev_b32_e32 v127, 16, v131
	v_mul_f32_e32 v130, 0xbfb8aa3b, v127
	v_exp_f32_e32 v130, v130
	s_nop 0
	v_add_f32_e32 v130, 1.0, v130
	v_div_scale_f32 v161, s[12:13], v130, v130, v127
	v_rcp_f32_e32 v172, v161
	s_nop 0
	v_fma_f32 v173, -v161, v172, 1.0
	v_fmac_f32_e32 v172, v173, v172
	v_div_scale_f32 v173, vcc, v127, v130, v127
	v_mul_f32_e32 v174, v173, v172
	v_fma_f32 v175, -v161, v174, v173
	v_fmac_f32_e32 v174, v175, v172
	v_fma_f32 v161, -v161, v174, v173
	v_div_fmas_f32 v161, v161, v172, v174
	v_div_fixup_f32 v127, v161, v130, v127
	v_mul_f32_e32 v127, v128, v127
	v_and_b32_e32 v128, 0xffff0000, v131
	v_mul_f32_e32 v130, 0xbfb8aa3b, v128
	v_exp_f32_e32 v130, v130
	s_nop 0
	v_add_f32_e32 v130, 1.0, v130
	v_div_scale_f32 v131, s[12:13], v130, v130, v128
	v_rcp_f32_e32 v161, v131
	s_nop 0
	v_fma_f32 v172, -v131, v161, 1.0
	v_fmac_f32_e32 v161, v172, v161
	v_div_scale_f32 v172, vcc, v128, v130, v128
	v_mul_f32_e32 v173, v172, v161
	v_fma_f32 v174, -v131, v173, v172
	v_fmac_f32_e32 v173, v174, v161
	v_fma_f32 v131, -v131, v173, v172
	v_div_fmas_f32 v131, v131, v161, v173
	v_div_fixup_f32 v128, v131, v130, v128
	v_mul_f32_e32 v128, v129, v128
	v_cvt_pk_bf16_f32 v127, v127, v128
	v_lshlrev_b32_e32 v128, 16, v132
	v_mul_f32_e32 v129, 0xbfb8aa3b, v128
	v_exp_f32_e32 v129, v129
	s_nop 0
	v_add_f32_e32 v129, 1.0, v129
	v_div_scale_f32 v130, s[12:13], v129, v129, v128
	v_rcp_f32_e32 v131, v130
	s_nop 0
	v_fma_f32 v161, -v130, v131, 1.0
	v_fmac_f32_e32 v131, v161, v131
	v_div_scale_f32 v161, vcc, v128, v129, v128
	v_mul_f32_e32 v172, v161, v131
	v_fma_f32 v173, -v130, v172, v161
	v_fmac_f32_e32 v172, v173, v131
	v_fma_f32 v130, -v130, v172, v161
	v_div_fmas_f32 v130, v130, v131, v172
	v_div_fixup_f32 v128, v130, v129, v128
	v_mul_f32_e32 v122, v122, v128
	v_and_b32_e32 v128, 0xffff0000, v132
	v_mul_f32_e32 v129, 0xbfb8aa3b, v128
	v_exp_f32_e32 v129, v129
	s_nop 0
	v_add_f32_e32 v129, 1.0, v129
	v_div_scale_f32 v130, s[12:13], v129, v129, v128
	v_rcp_f32_e32 v131, v130
	s_nop 0
	v_fma_f32 v132, -v130, v131, 1.0
	v_fmac_f32_e32 v131, v132, v131
	v_div_scale_f32 v132, vcc, v128, v129, v128
	v_mul_f32_e32 v161, v132, v131
	v_fma_f32 v172, -v130, v161, v132
	v_fmac_f32_e32 v161, v172, v131
	v_fma_f32 v130, -v130, v161, v132
	v_div_fmas_f32 v130, v130, v131, v161
	v_div_fixup_f32 v128, v130, v129, v128
	v_mul_f32_e32 v123, v123, v128
	v_cvt_pk_bf16_f32 v128, v122, v123
	v_lshlrev_b32_e32 v122, 16, v133
	v_mul_f32_e32 v123, 0xbfb8aa3b, v122
	v_exp_f32_e32 v123, v123
	s_nop 0
	v_add_f32_e32 v123, 1.0, v123
	v_div_scale_f32 v129, s[12:13], v123, v123, v122
	v_rcp_f32_e32 v130, v129
	s_nop 0
	v_fma_f32 v131, -v129, v130, 1.0
	v_fmac_f32_e32 v130, v131, v130
	v_div_scale_f32 v131, vcc, v122, v123, v122
	v_mul_f32_e32 v132, v131, v130
	v_fma_f32 v161, -v129, v132, v131
	v_fmac_f32_e32 v132, v161, v130
	v_fma_f32 v129, -v129, v132, v131
	v_div_fmas_f32 v129, v129, v130, v132
	v_div_fixup_f32 v122, v129, v123, v122
	v_and_b32_e32 v123, 0xffff0000, v133
	v_mul_f32_e32 v122, v124, v122
	v_mul_f32_e32 v124, 0xbfb8aa3b, v123
	v_exp_f32_e32 v124, v124
	s_nop 0
	v_add_f32_e32 v124, 1.0, v124
	v_div_scale_f32 v129, s[12:13], v124, v124, v123
	v_rcp_f32_e32 v130, v129
	s_nop 0
	v_fma_f32 v131, -v129, v130, 1.0
	v_fmac_f32_e32 v130, v131, v130
	v_div_scale_f32 v131, vcc, v123, v124, v123
	v_mul_f32_e32 v132, v131, v130
	v_fma_f32 v133, -v129, v132, v131
	v_fmac_f32_e32 v132, v133, v130
	v_fma_f32 v129, -v129, v132, v131
	v_div_fmas_f32 v129, v129, v130, v132
	v_div_fixup_f32 v123, v129, v124, v123
	v_mul_f32_e32 v123, v125, v123
	v_cvt_pk_bf16_f32 v129, v122, v123
	v_lshl_add_u64 v[122:123], s[72:73], 0, v[164:165]
	v_lshl_add_u64 v[130:131], v[122:123], 0, v[144:145]
	global_store_dwordx4 v[130:131], v[126:129], off
	global_load_dwordx4 v[122:125], v[166:167], off offset:256
	s_waitcnt vmcnt(0)
; __device__ __forceinline__ unsigned cvt_pk_bf16(float lo, float hi) { unsigned r; asm volatile("v_cvt_pk_bf16_f32 %0, %1, %2" : "=v"(r) : "v"(lo), "v"(hi)); return r; }
; __device__ __forceinline__ float bflo(unsigned u) { return __uint_as_float(u << 16); }
; __device__ __forceinline__ float bfhi(unsigned u) { return __uint_as_float(u & 0xffff0000u); }
; __device__ __forceinline__ float silu_f(float v) { return v / (1.f + __expf(-v)); }
;     __device__ __forceinline__ void operator()(const pg8::f32x4 (&acc)[2][2][4][2], const pg8::Unit& u, int wr, int wc, int fr, int fq) const {
;     ...
;             for (int m = 0; m < 4; ++m) { const size_t row = (size_t)(row0 + ai * 128 + m * 16);
; #pragma unroll
;                 for (int bj = 0; bj < 2; ++bj) { const pg8::f32x4 v0 = acc[ai][bj][m][0], v1 = acc[ai][bj][m][1];
;                     const u32x4 gz = *(const u32x4*)(Z + row * DIN + goff + col0 + bj * 128); u32x4 w;
;                     w.x = pg8::cvt_pk_bf16(v0[0] * silu_f(bflo(gz.x)), v0[1] * silu_f(bfhi(gz.x))); w.y = pg8::cvt_pk_bf16(v0[2] * silu_f(bflo(gz.y)), v0[3] * silu_f(bfhi(gz.y)));
;                     w.z = pg8::cvt_pk_bf16(v1[0] * silu_f(bflo(gz.z)), v1[1] * silu_f(bfhi(gz.z))); w.w = pg8::cvt_pk_bf16(v1[2] * silu_f(bflo(gz.w)), v1[3] * silu_f(bfhi(gz.w)));
;                     *(u32x4*)(O + row * DM + coff + col0 + bj * 128) = w; } }
	v_lshlrev_b32_e32 v126, 16, v122
	v_mul_f32_e32 v127, 0xbfb8aa3b, v126
	v_exp_f32_e32 v127, v127
	v_and_b32_e32 v122, 0xffff0000, v122
	v_add_f32_e32 v127, 1.0, v127
	v_div_scale_f32 v128, s[12:13], v127, v127, v126
	v_rcp_f32_e32 v129, v128
	s_nop 0
	v_fma_f32 v132, -v128, v129, 1.0
	v_fmac_f32_e32 v129, v132, v129
	v_div_scale_f32 v132, vcc, v126, v127, v126
	v_mul_f32_e32 v133, v132, v129
	v_fma_f32 v161, -v128, v133, v132
	v_fmac_f32_e32 v133, v161, v129
	v_fma_f32 v128, -v128, v133, v132
	v_div_fmas_f32 v128, v128, v129, v133
	v_div_fixup_f32 v126, v128, v127, v126
	v_mul_f32_e32 v118, v118, v126
	v_mul_f32_e32 v126, 0xbfb8aa3b, v122
	v_exp_f32_e32 v126, v126
	s_nop 0
	v_add_f32_e32 v126, 1.0, v126
	v_div_scale_f32 v127, s[12:13], v126, v126, v122
	v_rcp_f32_e32 v128, v127
	s_nop 0
	v_fma_f32 v129, -v127, v128, 1.0
	v_fmac_f32_e32 v128, v129, v128
	v_div_scale_f32 v129, vcc, v122, v126, v122
	v_mul_f32_e32 v132, v129, v128
	v_fma_f32 v133, -v127, v132, v129
	v_fmac_f32_e32 v132, v133, v128
	v_fma_f32 v127, -v127, v132, v129
	v_div_fmas_f32 v127, v127, v128, v132
	v_div_fixup_f32 v122, v127, v126, v122
	v_mul_f32_e32 v119, v119, v122
	v_cvt_pk_bf16_f32 v118, v118, v119
	v_lshlrev_b32_e32 v119, 16, v123
	v_mul_f32_e32 v122, 0xbfb8aa3b, v119
	v_exp_f32_e32 v122, v122
	s_nop 0
	v_add_f32_e32 v122, 1.0, v122
	v_div_scale_f32 v126, s[12:13], v122, v122, v119
	v_rcp_f32_e32 v127, v126
	s_nop 0
	v_fma_f32 v128, -v126, v127, 1.0
	v_fmac_f32_e32 v127, v128, v127
	v_div_scale_f32 v128, vcc, v119, v122, v119
	v_mul_f32_e32 v129, v128, v127
	v_fma_f32 v132, -v126, v129, v128
	v_fmac_f32_e32 v129, v132, v127
	v_fma_f32 v126, -v126, v129, v128
	v_div_fmas_f32 v126, v126, v127, v129
	v_div_fixup_f32 v119, v126, v122, v119
	v_mul_f32_e32 v119, v120, v119
	v_and_b32_e32 v120, 0xffff0000, v123
	v_mul_f32_e32 v122, 0xbfb8aa3b, v120
	v_exp_f32_e32 v122, v122
	s_nop 0
	v_add_f32_e32 v122, 1.0, v122
	v_div_scale_f32 v123, s[12:13], v122, v122, v120
	v_rcp_f32_e32 v126, v123
	s_nop 0
	v_fma_f32 v127, -v123, v126, 1.0
	v_fmac_f32_e32 v126, v127, v126
	v_div_scale_f32 v127, vcc, v120, v122, v120
	v_mul_f32_e32 v128, v127, v126
	v_fma_f32 v129, -v123, v128, v127
	v_fmac_f32_e32 v128, v129, v126
	v_fma_f32 v123, -v123, v128, v127
	v_div_fmas_f32 v123, v123, v126, v128
	v_div_fixup_f32 v120, v123, v122, v120
	v_mul_f32_e32 v120, v121, v120
	v_cvt_pk_bf16_f32 v119, v119, v120
	v_lshlrev_b32_e32 v120, 16, v124
	v_mul_f32_e32 v121, 0xbfb8aa3b, v120
	v_exp_f32_e32 v121, v121
	s_nop 0
	v_add_f32_e32 v121, 1.0, v121
	v_div_scale_f32 v122, s[12:13], v121, v121, v120
	v_rcp_f32_e32 v123, v122
	s_nop 0
	v_fma_f32 v126, -v122, v123, 1.0
	v_fmac_f32_e32 v123, v126, v123
	v_div_scale_f32 v126, vcc, v120, v121, v120
	v_mul_f32_e32 v127, v126, v123
	v_fma_f32 v128, -v122, v127, v126
	v_fmac_f32_e32 v127, v128, v123
	v_fma_f32 v122, -v122, v127, v126
	v_div_fmas_f32 v122, v122, v123, v127
	v_div_fixup_f32 v120, v122, v121, v120
	v_mul_f32_e32 v114, v114, v120
	v_and_b32_e32 v120, 0xffff0000, v124
	v_mul_f32_e32 v121, 0xbfb8aa3b, v120
	v_exp_f32_e32 v121, v121
	s_nop 0
	v_add_f32_e32 v121, 1.0, v121
	v_div_scale_f32 v122, s[12:13], v121, v121, v120
	v_rcp_f32_e32 v123, v122
	s_nop 0
	v_fma_f32 v124, -v122, v123, 1.0
	v_fmac_f32_e32 v123, v124, v123
	v_div_scale_f32 v124, vcc, v120, v121, v120
	v_mul_f32_e32 v126, v124, v123
	v_fma_f32 v127, -v122, v126, v124
	v_fmac_f32_e32 v126, v127, v123
	v_fma_f32 v122, -v122, v126, v124
	v_div_fmas_f32 v122, v122, v123, v126
	v_div_fixup_f32 v120, v122, v121, v120
	v_mul_f32_e32 v115, v115, v120
	v_cvt_pk_bf16_f32 v120, v114, v115
	v_lshlrev_b32_e32 v114, 16, v125
	v_mul_f32_e32 v115, 0xbfb8aa3b, v114
	v_exp_f32_e32 v115, v115
	s_nop 0
	v_add_f32_e32 v115, 1.0, v115
	v_div_scale_f32 v121, s[12:13], v115, v115, v114
	v_rcp_f32_e32 v122, v121
	s_nop 0
	v_fma_f32 v123, -v121, v122, 1.0
	v_fmac_f32_e32 v122, v123, v122
	v_div_scale_f32 v123, vcc, v114, v115, v114
	v_mul_f32_e32 v124, v123, v122
	v_fma_f32 v126, -v121, v124, v123
	v_fmac_f32_e32 v124, v126, v122
	v_fma_f32 v121, -v121, v124, v123
	v_div_fmas_f32 v121, v121, v122, v124
	v_div_fixup_f32 v114, v121, v115, v114
	v_and_b32_e32 v115, 0xffff0000, v125
	v_mul_f32_e32 v114, v116, v114
	v_mul_f32_e32 v116, 0xbfb8aa3b, v115
	v_exp_f32_e32 v116, v116
	s_nop 0
	v_add_f32_e32 v116, 1.0, v116
	v_div_scale_f32 v121, s[12:13], v116, v116, v115
	v_rcp_f32_e32 v122, v121
	s_nop 0
	v_fma_f32 v123, -v121, v122, 1.0
	v_fmac_f32_e32 v122, v123, v122
	v_div_scale_f32 v123, vcc, v115, v116, v115
	v_mul_f32_e32 v124, v123, v122
	v_fma_f32 v125, -v121, v124, v123
	v_fmac_f32_e32 v124, v125, v122
	v_fma_f32 v121, -v121, v124, v123
	v_div_fmas_f32 v121, v121, v122, v124
	v_div_fixup_f32 v115, v121, v116, v115
	v_mul_f32_e32 v115, v117, v115
	v_cvt_pk_bf16_f32 v121, v114, v115
	v_or_b32_e32 v114, 16, v160
	v_ashrrev_i32_e32 v115, 31, v114
	global_store_dwordx4 v[130:131], v[118:121], off offset:256
	s_nop 1
	v_lshlrev_b64 v[118:119], 12, v[114:115]
	v_mad_i64_i32 v[114:115], s[12:13], v114, s75, v[162:163]
	v_lshl_add_u64 v[114:115], v[114:115], 0, v[144:145]
	v_lshl_add_u64 v[120:121], v[114:115], 0, s[26:27]
	v_add_co_u32_e32 v114, vcc, s5, v114
	s_nop 1
	v_addc_co_u32_e32 v115, vcc, 0, v115, vcc
	global_load_dwordx4 v[114:117], v[114:115], off
	s_waitcnt vmcnt(0)
; __device__ __forceinline__ unsigned cvt_pk_bf16(float lo, float hi) { unsigned r; asm volatile("v_cvt_pk_bf16_f32 %0, %1, %2" : "=v"(r) : "v"(lo), "v"(hi)); return r; }
; __device__ __forceinline__ float bflo(unsigned u) { return __uint_as_float(u << 16); }
; __device__ __forceinline__ float bfhi(unsigned u) { return __uint_as_float(u & 0xffff0000u); }
; __device__ __forceinline__ float silu_f(float v) { return v / (1.f + __expf(-v)); }
;     __device__ __forceinline__ void operator()(const pg8::f32x4 (&acc)[2][2][4][2], const pg8::Unit& u, int wr, int wc, int fr, int fq) const {
;     ...
;             for (int m = 0; m < 4; ++m) { const size_t row = (size_t)(row0 + ai * 128 + m * 16);
; #pragma unroll
;                 for (int bj = 0; bj < 2; ++bj) { const pg8::f32x4 v0 = acc[ai][bj][m][0], v1 = acc[ai][bj][m][1];
;                     const u32x4 gz = *(const u32x4*)(Z + row * DIN + goff + col0 + bj * 128); u32x4 w;
;                     w.x = pg8::cvt_pk_bf16(v0[0] * silu_f(bflo(gz.x)), v0[1] * silu_f(bfhi(gz.x))); w.y = pg8::cvt_pk_bf16(v0[2] * silu_f(bflo(gz.y)), v0[3] * silu_f(bfhi(gz.y)));
;                     w.z = pg8::cvt_pk_bf16(v1[0] * silu_f(bflo(gz.z)), v1[1] * silu_f(bfhi(gz.z))); w.w = pg8::cvt_pk_bf16(v1[2] * silu_f(bflo(gz.w)), v1[3] * silu_f(bfhi(gz.w)));
;                     *(u32x4*)(O + row * DM + coff + col0 + bj * 128) = w; } }
	v_lshlrev_b32_e32 v122, 16, v114
	v_mul_f32_e32 v123, 0xbfb8aa3b, v122
	v_exp_f32_e32 v123, v123
	v_and_b32_e32 v114, 0xffff0000, v114
	v_add_f32_e32 v123, 1.0, v123
	v_div_scale_f32 v124, s[12:13], v123, v123, v122
	v_rcp_f32_e32 v125, v124
	s_nop 0
	v_fma_f32 v126, -v124, v125, 1.0
	v_fmac_f32_e32 v125, v126, v125
	v_div_scale_f32 v126, vcc, v122, v123, v122
	v_mul_f32_e32 v127, v126, v125
	v_fma_f32 v128, -v124, v127, v126
	v_fmac_f32_e32 v127, v128, v125
	v_fma_f32 v124, -v124, v127, v126
	v_div_fmas_f32 v124, v124, v125, v127
	v_div_fixup_f32 v122, v124, v123, v122
	v_mul_f32_e32 v110, v110, v122
	v_mul_f32_e32 v122, 0xbfb8aa3b, v114
	v_exp_f32_e32 v122, v122
	s_nop 0
	v_add_f32_e32 v122, 1.0, v122
	v_div_scale_f32 v123, s[12:13], v122, v122, v114
	v_rcp_f32_e32 v124, v123
	s_nop 0
	v_fma_f32 v125, -v123, v124, 1.0
	v_fmac_f32_e32 v124, v125, v124
	v_div_scale_f32 v125, vcc, v114, v122, v114
	v_mul_f32_e32 v126, v125, v124
	v_fma_f32 v127, -v123, v126, v125
	v_fmac_f32_e32 v126, v127, v124
	v_fma_f32 v123, -v123, v126, v125
	v_div_fmas_f32 v123, v123, v124, v126
	v_div_fixup_f32 v114, v123, v122, v114
	v_mul_f32_e32 v111, v111, v114
	v_cvt_pk_bf16_f32 v110, v110, v111
	v_lshlrev_b32_e32 v111, 16, v115
	v_mul_f32_e32 v114, 0xbfb8aa3b, v111
	v_exp_f32_e32 v114, v114
	s_nop 0
	v_add_f32_e32 v114, 1.0, v114
	v_div_scale_f32 v122, s[12:13], v114, v114, v111
	v_rcp_f32_e32 v123, v122
	s_nop 0
	v_fma_f32 v124, -v122, v123, 1.0
	v_fmac_f32_e32 v123, v124, v123
	v_div_scale_f32 v124, vcc, v111, v114, v111
	v_mul_f32_e32 v125, v124, v123
	v_fma_f32 v126, -v122, v125, v124
	v_fmac_f32_e32 v125, v126, v123
	v_fma_f32 v122, -v122, v125, v124
	v_div_fmas_f32 v122, v122, v123, v125
	v_div_fixup_f32 v111, v122, v114, v111
	v_mul_f32_e32 v111, v112, v111
	v_and_b32_e32 v112, 0xffff0000, v115
	v_mul_f32_e32 v114, 0xbfb8aa3b, v112
	v_exp_f32_e32 v114, v114
	s_nop 0
	v_add_f32_e32 v114, 1.0, v114
	v_div_scale_f32 v115, s[12:13], v114, v114, v112
	v_rcp_f32_e32 v122, v115
	s_nop 0
	v_fma_f32 v123, -v115, v122, 1.0
	v_fmac_f32_e32 v122, v123, v122
	v_div_scale_f32 v123, vcc, v112, v114, v112
	v_mul_f32_e32 v124, v123, v122
	v_fma_f32 v125, -v115, v124, v123
	v_fmac_f32_e32 v124, v125, v122
	v_fma_f32 v115, -v115, v124, v123
	v_div_fmas_f32 v115, v115, v122, v124
	v_div_fixup_f32 v112, v115, v114, v112
	v_mul_f32_e32 v112, v113, v112
	v_cvt_pk_bf16_f32 v111, v111, v112
	v_lshlrev_b32_e32 v112, 16, v116
	v_mul_f32_e32 v113, 0xbfb8aa3b, v112
	v_exp_f32_e32 v113, v113
	s_nop 0
	v_add_f32_e32 v113, 1.0, v113
	v_div_scale_f32 v114, s[12:13], v113, v113, v112
	v_rcp_f32_e32 v115, v114
	s_nop 0
	v_fma_f32 v122, -v114, v115, 1.0
	v_fmac_f32_e32 v115, v122, v115
	v_div_scale_f32 v122, vcc, v112, v113, v112
	v_mul_f32_e32 v123, v122, v115
	v_fma_f32 v124, -v114, v123, v122
	v_fmac_f32_e32 v123, v124, v115
	v_fma_f32 v114, -v114, v123, v122
	v_div_fmas_f32 v114, v114, v115, v123
	v_div_fixup_f32 v112, v114, v113, v112
	v_mul_f32_e32 v106, v106, v112
	v_and_b32_e32 v112, 0xffff0000, v116
	v_mul_f32_e32 v113, 0xbfb8aa3b, v112
	v_exp_f32_e32 v113, v113
	s_nop 0
	v_add_f32_e32 v113, 1.0, v113
	v_div_scale_f32 v114, s[12:13], v113, v113, v112
	v_rcp_f32_e32 v115, v114
	s_nop 0
	v_fma_f32 v116, -v114, v115, 1.0
	v_fmac_f32_e32 v115, v116, v115
	v_div_scale_f32 v116, vcc, v112, v113, v112
	v_mul_f32_e32 v122, v116, v115
	v_fma_f32 v123, -v114, v122, v116
	v_fmac_f32_e32 v122, v123, v115
	v_fma_f32 v114, -v114, v122, v116
	v_div_fmas_f32 v114, v114, v115, v122
	v_div_fixup_f32 v112, v114, v113, v112
	v_mul_f32_e32 v107, v107, v112
	v_cvt_pk_bf16_f32 v112, v106, v107
	v_lshlrev_b32_e32 v106, 16, v117
	v_mul_f32_e32 v107, 0xbfb8aa3b, v106
	v_exp_f32_e32 v107, v107
	s_nop 0
	v_add_f32_e32 v107, 1.0, v107
	v_div_scale_f32 v113, s[12:13], v107, v107, v106
	v_rcp_f32_e32 v114, v113
	s_nop 0
	v_fma_f32 v115, -v113, v114, 1.0
	v_fmac_f32_e32 v114, v115, v114
	v_div_scale_f32 v115, vcc, v106, v107, v106
	v_mul_f32_e32 v116, v115, v114
	v_fma_f32 v122, -v113, v116, v115
	v_fmac_f32_e32 v116, v122, v114
	v_fma_f32 v113, -v113, v116, v115
	v_div_fmas_f32 v113, v113, v114, v116
	v_div_fixup_f32 v106, v113, v107, v106
	v_and_b32_e32 v107, 0xffff0000, v117
	v_mul_f32_e32 v106, v108, v106
	v_mul_f32_e32 v108, 0xbfb8aa3b, v107
	v_exp_f32_e32 v108, v108
	s_nop 0
	v_add_f32_e32 v108, 1.0, v108
	v_div_scale_f32 v113, s[12:13], v108, v108, v107
	v_rcp_f32_e32 v114, v113
	s_nop 0
	v_fma_f32 v115, -v113, v114, 1.0
	v_fmac_f32_e32 v114, v115, v114
	v_div_scale_f32 v115, vcc, v107, v108, v107
	v_mul_f32_e32 v116, v115, v114
	v_fma_f32 v117, -v113, v116, v115
	v_fmac_f32_e32 v116, v117, v114
	v_fma_f32 v113, -v113, v116, v115
	v_div_fmas_f32 v113, v113, v114, v116
	v_div_fixup_f32 v107, v113, v108, v107
	v_mul_f32_e32 v107, v109, v107
	v_cvt_pk_bf16_f32 v113, v106, v107
	v_lshl_add_u64 v[106:107], s[72:73], 0, v[118:119]
	v_lshl_add_u64 v[114:115], v[106:107], 0, v[144:145]
	global_store_dwordx4 v[114:115], v[110:113], off
	global_load_dwordx4 v[106:109], v[120:121], off offset:256
	s_waitcnt vmcnt(0)
; __device__ __forceinline__ unsigned cvt_pk_bf16(float lo, float hi) { unsigned r; asm volatile("v_cvt_pk_bf16_f32 %0, %1, %2" : "=v"(r) : "v"(lo), "v"(hi)); return r; }
; __device__ __forceinline__ float bflo(unsigned u) { return __uint_as_float(u << 16); }
; __device__ __forceinline__ float bfhi(unsigned u) { return __uint_as_float(u & 0xffff0000u); }
; __device__ __forceinline__ float silu_f(float v) { return v / (1.f + __expf(-v)); }
;     __device__ __forceinline__ void operator()(const pg8::f32x4 (&acc)[2][2][4][2], const pg8::Unit& u, int wr, int wc, int fr, int fq) const {
;     ...
;             for (int m = 0; m < 4; ++m) { const size_t row = (size_t)(row0 + ai * 128 + m * 16);
; #pragma unroll
;                 for (int bj = 0; bj < 2; ++bj) { const pg8::f32x4 v0 = acc[ai][bj][m][0], v1 = acc[ai][bj][m][1];
;                     const u32x4 gz = *(const u32x4*)(Z + row * DIN + goff + col0 + bj * 128); u32x4 w;
;                     w.x = pg8::cvt_pk_bf16(v0[0] * silu_f(bflo(gz.x)), v0[1] * silu_f(bfhi(gz.x))); w.y = pg8::cvt_pk_bf16(v0[2] * silu_f(bflo(gz.y)), v0[3] * silu_f(bfhi(gz.y)));
;                     w.z = pg8::cvt_pk_bf16(v1[0] * silu_f(bflo(gz.z)), v1[1] * silu_f(bfhi(gz.z))); w.w = pg8::cvt_pk_bf16(v1[2] * silu_f(bflo(gz.w)), v1[3] * silu_f(bfhi(gz.w)));
;                     *(u32x4*)(O + row * DM + coff + col0 + bj * 128) = w; } }
	v_lshlrev_b32_e32 v110, 16, v106
	v_mul_f32_e32 v111, 0xbfb8aa3b, v110
	v_exp_f32_e32 v111, v111
	v_and_b32_e32 v106, 0xffff0000, v106
	v_add_f32_e32 v111, 1.0, v111
	v_div_scale_f32 v112, s[12:13], v111, v111, v110
	v_rcp_f32_e32 v113, v112
	s_nop 0
	v_fma_f32 v116, -v112, v113, 1.0
	v_fmac_f32_e32 v113, v116, v113
	v_div_scale_f32 v116, vcc, v110, v111, v110
	v_mul_f32_e32 v117, v116, v113
	v_fma_f32 v118, -v112, v117, v116
	v_fmac_f32_e32 v117, v118, v113
	v_fma_f32 v112, -v112, v117, v116
	v_div_fmas_f32 v112, v112, v113, v117
	v_div_fixup_f32 v110, v112, v111, v110
	v_mul_f32_e32 v102, v102, v110
	v_mul_f32_e32 v110, 0xbfb8aa3b, v106
	v_exp_f32_e32 v110, v110
	s_nop 0
	v_add_f32_e32 v110, 1.0, v110
	v_div_scale_f32 v111, s[12:13], v110, v110, v106
	v_rcp_f32_e32 v112, v111
	s_nop 0
	v_fma_f32 v113, -v111, v112, 1.0
	v_fmac_f32_e32 v112, v113, v112
	v_div_scale_f32 v113, vcc, v106, v110, v106
	v_mul_f32_e32 v116, v113, v112
	v_fma_f32 v117, -v111, v116, v113
	v_fmac_f32_e32 v116, v117, v112
	v_fma_f32 v111, -v111, v116, v113
	v_div_fmas_f32 v111, v111, v112, v116
	v_div_fixup_f32 v106, v111, v110, v106
	v_mul_f32_e32 v103, v103, v106
	v_cvt_pk_bf16_f32 v102, v102, v103
	v_lshlrev_b32_e32 v103, 16, v107
	v_mul_f32_e32 v106, 0xbfb8aa3b, v103
	v_exp_f32_e32 v106, v106
	s_nop 0
	v_add_f32_e32 v106, 1.0, v106
	v_div_scale_f32 v110, s[12:13], v106, v106, v103
	v_rcp_f32_e32 v111, v110
	s_nop 0
	v_fma_f32 v112, -v110, v111, 1.0
	v_fmac_f32_e32 v111, v112, v111
	v_div_scale_f32 v112, vcc, v103, v106, v103
	v_mul_f32_e32 v113, v112, v111
	v_fma_f32 v116, -v110, v113, v112
	v_fmac_f32_e32 v113, v116, v111
	v_fma_f32 v110, -v110, v113, v112
	v_div_fmas_f32 v110, v110, v111, v113
	v_div_fixup_f32 v103, v110, v106, v103
	v_mul_f32_e32 v103, v104, v103
	v_and_b32_e32 v104, 0xffff0000, v107
	v_mul_f32_e32 v106, 0xbfb8aa3b, v104
	v_exp_f32_e32 v106, v106
	s_nop 0
	v_add_f32_e32 v106, 1.0, v106
	v_div_scale_f32 v107, s[12:13], v106, v106, v104
	v_rcp_f32_e32 v110, v107
	s_nop 0
	v_fma_f32 v111, -v107, v110, 1.0
	v_fmac_f32_e32 v110, v111, v110
	v_div_scale_f32 v111, vcc, v104, v106, v104
	v_mul_f32_e32 v112, v111, v110
	v_fma_f32 v113, -v107, v112, v111
	v_fmac_f32_e32 v112, v113, v110
	v_fma_f32 v107, -v107, v112, v111
	v_div_fmas_f32 v107, v107, v110, v112
	v_div_fixup_f32 v104, v107, v106, v104
	v_mul_f32_e32 v104, v105, v104
	v_cvt_pk_bf16_f32 v103, v103, v104
	v_lshlrev_b32_e32 v104, 16, v108
	v_mul_f32_e32 v105, 0xbfb8aa3b, v104
	v_exp_f32_e32 v105, v105
	s_nop 0
	v_add_f32_e32 v105, 1.0, v105
	v_div_scale_f32 v106, s[12:13], v105, v105, v104
	v_rcp_f32_e32 v107, v106
	s_nop 0
	v_fma_f32 v110, -v106, v107, 1.0
	v_fmac_f32_e32 v107, v110, v107
	v_div_scale_f32 v110, vcc, v104, v105, v104
	v_mul_f32_e32 v111, v110, v107
	v_fma_f32 v112, -v106, v111, v110
	v_fmac_f32_e32 v111, v112, v107
	v_fma_f32 v106, -v106, v111, v110
	v_div_fmas_f32 v106, v106, v107, v111
	v_div_fixup_f32 v104, v106, v105, v104
	v_mul_f32_e32 v98, v98, v104
	v_and_b32_e32 v104, 0xffff0000, v108
	v_mul_f32_e32 v105, 0xbfb8aa3b, v104
	v_exp_f32_e32 v105, v105
	s_nop 0
	v_add_f32_e32 v105, 1.0, v105
	v_div_scale_f32 v106, s[12:13], v105, v105, v104
	v_rcp_f32_e32 v107, v106
	s_nop 0
	v_fma_f32 v108, -v106, v107, 1.0
	v_fmac_f32_e32 v107, v108, v107
	v_div_scale_f32 v108, vcc, v104, v105, v104
	v_mul_f32_e32 v110, v108, v107
	v_fma_f32 v111, -v106, v110, v108
	v_fmac_f32_e32 v110, v111, v107
	v_fma_f32 v106, -v106, v110, v108
	v_div_fmas_f32 v106, v106, v107, v110
	v_div_fixup_f32 v104, v106, v105, v104
	v_mul_f32_e32 v99, v99, v104
	v_cvt_pk_bf16_f32 v104, v98, v99
	v_lshlrev_b32_e32 v98, 16, v109
	v_mul_f32_e32 v99, 0xbfb8aa3b, v98
	v_exp_f32_e32 v99, v99
	s_nop 0
	v_add_f32_e32 v99, 1.0, v99
	v_div_scale_f32 v105, s[12:13], v99, v99, v98
	v_rcp_f32_e32 v106, v105
	s_nop 0
	v_fma_f32 v107, -v105, v106, 1.0
	v_fmac_f32_e32 v106, v107, v106
	v_div_scale_f32 v107, vcc, v98, v99, v98
	v_mul_f32_e32 v108, v107, v106
	v_fma_f32 v110, -v105, v108, v107
	v_fmac_f32_e32 v108, v110, v106
	v_fma_f32 v105, -v105, v108, v107
	v_div_fmas_f32 v105, v105, v106, v108
	v_div_fixup_f32 v98, v105, v99, v98
	v_and_b32_e32 v99, 0xffff0000, v109
	v_mul_f32_e32 v98, v100, v98
	v_mul_f32_e32 v100, 0xbfb8aa3b, v99
	v_exp_f32_e32 v100, v100
	s_nop 0
	v_add_f32_e32 v100, 1.0, v100
	v_div_scale_f32 v105, s[12:13], v100, v100, v99
	v_rcp_f32_e32 v106, v105
	s_nop 0
	v_fma_f32 v107, -v105, v106, 1.0
	v_fmac_f32_e32 v106, v107, v106
	v_div_scale_f32 v107, vcc, v99, v100, v99
	v_mul_f32_e32 v108, v107, v106
	v_fma_f32 v109, -v105, v108, v107
	v_fmac_f32_e32 v108, v109, v106
	v_fma_f32 v105, -v105, v108, v107
	v_div_fmas_f32 v105, v105, v106, v108
	v_div_fixup_f32 v99, v105, v100, v99
	v_mul_f32_e32 v99, v101, v99
	v_cvt_pk_bf16_f32 v105, v98, v99
	v_or_b32_e32 v98, 32, v160
	v_ashrrev_i32_e32 v99, 31, v98
	global_store_dwordx4 v[114:115], v[102:105], off offset:256
	s_nop 1
	v_lshlrev_b64 v[102:103], 12, v[98:99]
	v_mad_i64_i32 v[98:99], s[12:13], v98, s75, v[162:163]
	v_lshl_add_u64 v[98:99], v[98:99], 0, v[144:145]
	v_lshl_add_u64 v[104:105], v[98:99], 0, s[26:27]
	v_add_co_u32_e32 v98, vcc, s5, v98
	s_nop 1
	v_addc_co_u32_e32 v99, vcc, 0, v99, vcc
	global_load_dwordx4 v[98:101], v[98:99], off
	s_waitcnt vmcnt(0)
; __device__ __forceinline__ unsigned cvt_pk_bf16(float lo, float hi) { unsigned r; asm volatile("v_cvt_pk_bf16_f32 %0, %1, %2" : "=v"(r) : "v"(lo), "v"(hi)); return r; }
; __device__ __forceinline__ float bflo(unsigned u) { return __uint_as_float(u << 16); }
; __device__ __forceinline__ float bfhi(unsigned u) { return __uint_as_float(u & 0xffff0000u); }
; __device__ __forceinline__ float silu_f(float v) { return v / (1.f + __expf(-v)); }
;     __device__ __forceinline__ void operator()(const pg8::f32x4 (&acc)[2][2][4][2], const pg8::Unit& u, int wr, int wc, int fr, int fq) const {
;     ...
;             for (int m = 0; m < 4; ++m) { const size_t row = (size_t)(row0 + ai * 128 + m * 16);
; #pragma unroll
;                 for (int bj = 0; bj < 2; ++bj) { const pg8::f32x4 v0 = acc[ai][bj][m][0], v1 = acc[ai][bj][m][1];
;                     const u32x4 gz = *(const u32x4*)(Z + row * DIN + goff + col0 + bj * 128); u32x4 w;
;                     w.x = pg8::cvt_pk_bf16(v0[0] * silu_f(bflo(gz.x)), v0[1] * silu_f(bfhi(gz.x))); w.y = pg8::cvt_pk_bf16(v0[2] * silu_f(bflo(gz.y)), v0[3] * silu_f(bfhi(gz.y)));
;                     w.z = pg8::cvt_pk_bf16(v1[0] * silu_f(bflo(gz.z)), v1[1] * silu_f(bfhi(gz.z))); w.w = pg8::cvt_pk_bf16(v1[2] * silu_f(bflo(gz.w)), v1[3] * silu_f(bfhi(gz.w)));
;                     *(u32x4*)(O + row * DM + coff + col0 + bj * 128) = w; } }
	v_lshlrev_b32_e32 v106, 16, v98
	v_mul_f32_e32 v107, 0xbfb8aa3b, v106
	v_exp_f32_e32 v107, v107
	v_and_b32_e32 v98, 0xffff0000, v98
	v_add_f32_e32 v107, 1.0, v107
	v_div_scale_f32 v108, s[12:13], v107, v107, v106
	v_rcp_f32_e32 v109, v108
	s_nop 0
	v_fma_f32 v110, -v108, v109, 1.0
	v_fmac_f32_e32 v109, v110, v109
	v_div_scale_f32 v110, vcc, v106, v107, v106
	v_mul_f32_e32 v111, v110, v109
	v_fma_f32 v112, -v108, v111, v110
	v_fmac_f32_e32 v111, v112, v109
	v_fma_f32 v108, -v108, v111, v110
	v_div_fmas_f32 v108, v108, v109, v111
	v_div_fixup_f32 v106, v108, v107, v106
	v_mul_f32_e32 v94, v94, v106
	v_mul_f32_e32 v106, 0xbfb8aa3b, v98
	v_exp_f32_e32 v106, v106
	s_nop 0
	v_add_f32_e32 v106, 1.0, v106
	v_div_scale_f32 v107, s[12:13], v106, v106, v98
	v_rcp_f32_e32 v108, v107
	s_nop 0
	v_fma_f32 v109, -v107, v108, 1.0
	v_fmac_f32_e32 v108, v109, v108
	v_div_scale_f32 v109, vcc, v98, v106, v98
	v_mul_f32_e32 v110, v109, v108
	v_fma_f32 v111, -v107, v110, v109
	v_fmac_f32_e32 v110, v111, v108
	v_fma_f32 v107, -v107, v110, v109
	v_div_fmas_f32 v107, v107, v108, v110
	v_div_fixup_f32 v98, v107, v106, v98
	v_mul_f32_e32 v95, v95, v98
	v_cvt_pk_bf16_f32 v94, v94, v95
	v_lshlrev_b32_e32 v95, 16, v99
	v_mul_f32_e32 v98, 0xbfb8aa3b, v95
	v_exp_f32_e32 v98, v98
	s_nop 0
	v_add_f32_e32 v98, 1.0, v98
	v_div_scale_f32 v106, s[12:13], v98, v98, v95
	v_rcp_f32_e32 v107, v106
	s_nop 0
	v_fma_f32 v108, -v106, v107, 1.0
	v_fmac_f32_e32 v107, v108, v107
	v_div_scale_f32 v108, vcc, v95, v98, v95
	v_mul_f32_e32 v109, v108, v107
	v_fma_f32 v110, -v106, v109, v108
	v_fmac_f32_e32 v109, v110, v107
	v_fma_f32 v106, -v106, v109, v108
	v_div_fmas_f32 v106, v106, v107, v109
	v_div_fixup_f32 v95, v106, v98, v95
	v_mul_f32_e32 v95, v96, v95
	v_and_b32_e32 v96, 0xffff0000, v99
	v_mul_f32_e32 v98, 0xbfb8aa3b, v96
	v_exp_f32_e32 v98, v98
	s_nop 0
	v_add_f32_e32 v98, 1.0, v98
	v_div_scale_f32 v99, s[12:13], v98, v98, v96
	v_rcp_f32_e32 v106, v99
	s_nop 0
	v_fma_f32 v107, -v99, v106, 1.0
	v_fmac_f32_e32 v106, v107, v106
	v_div_scale_f32 v107, vcc, v96, v98, v96
	v_mul_f32_e32 v108, v107, v106
	v_fma_f32 v109, -v99, v108, v107
	v_fmac_f32_e32 v108, v109, v106
	v_fma_f32 v99, -v99, v108, v107
	v_div_fmas_f32 v99, v99, v106, v108
	v_div_fixup_f32 v96, v99, v98, v96
	v_mul_f32_e32 v96, v97, v96
	v_cvt_pk_bf16_f32 v95, v95, v96
	v_lshlrev_b32_e32 v96, 16, v100
	v_mul_f32_e32 v97, 0xbfb8aa3b, v96
	v_exp_f32_e32 v97, v97
	s_nop 0
	v_add_f32_e32 v97, 1.0, v97
	v_div_scale_f32 v98, s[12:13], v97, v97, v96
	v_rcp_f32_e32 v99, v98
	s_nop 0
	v_fma_f32 v106, -v98, v99, 1.0
	v_fmac_f32_e32 v99, v106, v99
	v_div_scale_f32 v106, vcc, v96, v97, v96
	v_mul_f32_e32 v107, v106, v99
	v_fma_f32 v108, -v98, v107, v106
	v_fmac_f32_e32 v107, v108, v99
	v_fma_f32 v98, -v98, v107, v106
	v_div_fmas_f32 v98, v98, v99, v107
	v_div_fixup_f32 v96, v98, v97, v96
	v_mul_f32_e32 v90, v90, v96
	v_and_b32_e32 v96, 0xffff0000, v100
	v_mul_f32_e32 v97, 0xbfb8aa3b, v96
	v_exp_f32_e32 v97, v97
	s_nop 0
	v_add_f32_e32 v97, 1.0, v97
	v_div_scale_f32 v98, s[12:13], v97, v97, v96
	v_rcp_f32_e32 v99, v98
	s_nop 0
	v_fma_f32 v100, -v98, v99, 1.0
	v_fmac_f32_e32 v99, v100, v99
	v_div_scale_f32 v100, vcc, v96, v97, v96
	v_mul_f32_e32 v106, v100, v99
	v_fma_f32 v107, -v98, v106, v100
	v_fmac_f32_e32 v106, v107, v99
	v_fma_f32 v98, -v98, v106, v100
	v_div_fmas_f32 v98, v98, v99, v106
	v_div_fixup_f32 v96, v98, v97, v96
	v_mul_f32_e32 v91, v91, v96
	v_cvt_pk_bf16_f32 v96, v90, v91
	v_lshlrev_b32_e32 v90, 16, v101
	v_mul_f32_e32 v91, 0xbfb8aa3b, v90
	v_exp_f32_e32 v91, v91
	s_nop 0
	v_add_f32_e32 v91, 1.0, v91
	v_div_scale_f32 v97, s[12:13], v91, v91, v90
	v_rcp_f32_e32 v98, v97
	s_nop 0
	v_fma_f32 v99, -v97, v98, 1.0
	v_fmac_f32_e32 v98, v99, v98
	v_div_scale_f32 v99, vcc, v90, v91, v90
	v_mul_f32_e32 v100, v99, v98
	v_fma_f32 v106, -v97, v100, v99
	v_fmac_f32_e32 v100, v106, v98
	v_fma_f32 v97, -v97, v100, v99
	v_div_fmas_f32 v97, v97, v98, v100
	v_div_fixup_f32 v90, v97, v91, v90
	v_and_b32_e32 v91, 0xffff0000, v101
	v_mul_f32_e32 v90, v92, v90
	v_mul_f32_e32 v92, 0xbfb8aa3b, v91
	v_exp_f32_e32 v92, v92
	s_nop 0
	v_add_f32_e32 v92, 1.0, v92
	v_div_scale_f32 v97, s[12:13], v92, v92, v91
	v_rcp_f32_e32 v98, v97
	s_nop 0
	v_fma_f32 v99, -v97, v98, 1.0
	v_fmac_f32_e32 v98, v99, v98
	v_div_scale_f32 v99, vcc, v91, v92, v91
	v_mul_f32_e32 v100, v99, v98
	v_fma_f32 v101, -v97, v100, v99
	v_fmac_f32_e32 v100, v101, v98
	v_fma_f32 v97, -v97, v100, v99
	v_div_fmas_f32 v97, v97, v98, v100
	v_div_fixup_f32 v91, v97, v92, v91
	v_mul_f32_e32 v91, v93, v91
	v_cvt_pk_bf16_f32 v97, v90, v91
	v_lshl_add_u64 v[90:91], s[72:73], 0, v[102:103]
	v_lshl_add_u64 v[98:99], v[90:91], 0, v[144:145]
	global_store_dwordx4 v[98:99], v[94:97], off
	global_load_dwordx4 v[90:93], v[104:105], off offset:256
	s_waitcnt vmcnt(0)
; __device__ __forceinline__ unsigned cvt_pk_bf16(float lo, float hi) { unsigned r; asm volatile("v_cvt_pk_bf16_f32 %0, %1, %2" : "=v"(r) : "v"(lo), "v"(hi)); return r; }
; __device__ __forceinline__ float bflo(unsigned u) { return __uint_as_float(u << 16); }
; __device__ __forceinline__ float bfhi(unsigned u) { return __uint_as_float(u & 0xffff0000u); }
; __device__ __forceinline__ float silu_f(float v) { return v / (1.f + __expf(-v)); }
;     __device__ __forceinline__ void operator()(const pg8::f32x4 (&acc)[2][2][4][2], const pg8::Unit& u, int wr, int wc, int fr, int fq) const {
;     ...
;             for (int m = 0; m < 4; ++m) { const size_t row = (size_t)(row0 + ai * 128 + m * 16);
; #pragma unroll
;                 for (int bj = 0; bj < 2; ++bj) { const pg8::f32x4 v0 = acc[ai][bj][m][0], v1 = acc[ai][bj][m][1];
;                     const u32x4 gz = *(const u32x4*)(Z + row * DIN + goff + col0 + bj * 128); u32x4 w;
;                     w.x = pg8::cvt_pk_bf16(v0[0] * silu_f(bflo(gz.x)), v0[1] * silu_f(bfhi(gz.x))); w.y = pg8::cvt_pk_bf16(v0[2] * silu_f(bflo(gz.y)), v0[3] * silu_f(bfhi(gz.y)));
;                     w.z = pg8::cvt_pk_bf16(v1[0] * silu_f(bflo(gz.z)), v1[1] * silu_f(bfhi(gz.z))); w.w = pg8::cvt_pk_bf16(v1[2] * silu_f(bflo(gz.w)), v1[3] * silu_f(bfhi(gz.w)));
;                     *(u32x4*)(O + row * DM + coff + col0 + bj * 128) = w; } }
	v_lshlrev_b32_e32 v94, 16, v90
	v_mul_f32_e32 v95, 0xbfb8aa3b, v94
	v_exp_f32_e32 v95, v95
	v_and_b32_e32 v90, 0xffff0000, v90
	v_add_f32_e32 v95, 1.0, v95
	v_div_scale_f32 v96, s[12:13], v95, v95, v94
	v_rcp_f32_e32 v97, v96
	s_nop 0
	v_fma_f32 v100, -v96, v97, 1.0
	v_fmac_f32_e32 v97, v100, v97
	v_div_scale_f32 v100, vcc, v94, v95, v94
	v_mul_f32_e32 v101, v100, v97
	v_fma_f32 v102, -v96, v101, v100
	v_fmac_f32_e32 v101, v102, v97
	v_fma_f32 v96, -v96, v101, v100
	v_div_fmas_f32 v96, v96, v97, v101
	v_div_fixup_f32 v94, v96, v95, v94
	v_mul_f32_e32 v86, v86, v94
	v_mul_f32_e32 v94, 0xbfb8aa3b, v90
	v_exp_f32_e32 v94, v94
	s_nop 0
	v_add_f32_e32 v94, 1.0, v94
	v_div_scale_f32 v95, s[12:13], v94, v94, v90
	v_rcp_f32_e32 v96, v95
	s_nop 0
	v_fma_f32 v97, -v95, v96, 1.0
	v_fmac_f32_e32 v96, v97, v96
	v_div_scale_f32 v97, vcc, v90, v94, v90
	v_mul_f32_e32 v100, v97, v96
	v_fma_f32 v101, -v95, v100, v97
	v_fmac_f32_e32 v100, v101, v96
	v_fma_f32 v95, -v95, v100, v97
	v_div_fmas_f32 v95, v95, v96, v100
	v_div_fixup_f32 v90, v95, v94, v90
	v_mul_f32_e32 v87, v87, v90
	v_cvt_pk_bf16_f32 v86, v86, v87
	v_lshlrev_b32_e32 v87, 16, v91
	v_mul_f32_e32 v90, 0xbfb8aa3b, v87
	v_exp_f32_e32 v90, v90
	s_nop 0
	v_add_f32_e32 v90, 1.0, v90
	v_div_scale_f32 v94, s[12:13], v90, v90, v87
	v_rcp_f32_e32 v95, v94
	s_nop 0
	v_fma_f32 v96, -v94, v95, 1.0
	v_fmac_f32_e32 v95, v96, v95
	v_div_scale_f32 v96, vcc, v87, v90, v87
	v_mul_f32_e32 v97, v96, v95
	v_fma_f32 v100, -v94, v97, v96
	v_fmac_f32_e32 v97, v100, v95
	v_fma_f32 v94, -v94, v97, v96
	v_div_fmas_f32 v94, v94, v95, v97
	v_div_fixup_f32 v87, v94, v90, v87
	v_mul_f32_e32 v87, v88, v87
	v_and_b32_e32 v88, 0xffff0000, v91
	v_mul_f32_e32 v90, 0xbfb8aa3b, v88
	v_exp_f32_e32 v90, v90
	s_nop 0
	v_add_f32_e32 v90, 1.0, v90
	v_div_scale_f32 v91, s[12:13], v90, v90, v88
	v_rcp_f32_e32 v94, v91
	s_nop 0
	v_fma_f32 v95, -v91, v94, 1.0
	v_fmac_f32_e32 v94, v95, v94
	v_div_scale_f32 v95, vcc, v88, v90, v88
	v_mul_f32_e32 v96, v95, v94
	v_fma_f32 v97, -v91, v96, v95
	v_fmac_f32_e32 v96, v97, v94
	v_fma_f32 v91, -v91, v96, v95
	v_div_fmas_f32 v91, v91, v94, v96
	v_div_fixup_f32 v88, v91, v90, v88
	v_mul_f32_e32 v88, v89, v88
	v_cvt_pk_bf16_f32 v87, v87, v88
	v_lshlrev_b32_e32 v88, 16, v92
	v_mul_f32_e32 v89, 0xbfb8aa3b, v88
	v_exp_f32_e32 v89, v89
	s_nop 0
	v_add_f32_e32 v89, 1.0, v89
	v_div_scale_f32 v90, s[12:13], v89, v89, v88
	v_rcp_f32_e32 v91, v90
	s_nop 0
	v_fma_f32 v94, -v90, v91, 1.0
	v_fmac_f32_e32 v91, v94, v91
	v_div_scale_f32 v94, vcc, v88, v89, v88
	v_mul_f32_e32 v95, v94, v91
	v_fma_f32 v96, -v90, v95, v94
	v_fmac_f32_e32 v95, v96, v91
	v_fma_f32 v90, -v90, v95, v94
	v_div_fmas_f32 v90, v90, v91, v95
	v_div_fixup_f32 v88, v90, v89, v88
	v_mul_f32_e32 v82, v82, v88
	v_and_b32_e32 v88, 0xffff0000, v92
	v_mul_f32_e32 v89, 0xbfb8aa3b, v88
	v_exp_f32_e32 v89, v89
	s_nop 0
	v_add_f32_e32 v89, 1.0, v89
	v_div_scale_f32 v90, s[12:13], v89, v89, v88
	v_rcp_f32_e32 v91, v90
	s_nop 0
	v_fma_f32 v92, -v90, v91, 1.0
	v_fmac_f32_e32 v91, v92, v91
	v_div_scale_f32 v92, vcc, v88, v89, v88
	v_mul_f32_e32 v94, v92, v91
	v_fma_f32 v95, -v90, v94, v92
	v_fmac_f32_e32 v94, v95, v91
	v_fma_f32 v90, -v90, v94, v92
	v_div_fmas_f32 v90, v90, v91, v94
	v_div_fixup_f32 v88, v90, v89, v88
	v_mul_f32_e32 v83, v83, v88
	v_cvt_pk_bf16_f32 v88, v82, v83
	v_lshlrev_b32_e32 v82, 16, v93
	v_mul_f32_e32 v83, 0xbfb8aa3b, v82
	v_exp_f32_e32 v83, v83
	s_nop 0
	v_add_f32_e32 v83, 1.0, v83
	v_div_scale_f32 v89, s[12:13], v83, v83, v82
	v_rcp_f32_e32 v90, v89
	s_nop 0
	v_fma_f32 v91, -v89, v90, 1.0
	v_fmac_f32_e32 v90, v91, v90
	v_div_scale_f32 v91, vcc, v82, v83, v82
	v_mul_f32_e32 v92, v91, v90
	v_fma_f32 v94, -v89, v92, v91
	v_fmac_f32_e32 v92, v94, v90
	v_fma_f32 v89, -v89, v92, v91
	v_div_fmas_f32 v89, v89, v90, v92
	v_div_fixup_f32 v82, v89, v83, v82
	v_and_b32_e32 v83, 0xffff0000, v93
	v_mul_f32_e32 v82, v84, v82
	v_mul_f32_e32 v84, 0xbfb8aa3b, v83
	v_exp_f32_e32 v84, v84
	s_nop 0
	v_add_f32_e32 v84, 1.0, v84
	v_div_scale_f32 v89, s[12:13], v84, v84, v83
	v_rcp_f32_e32 v90, v89
	s_nop 0
	v_fma_f32 v91, -v89, v90, 1.0
	v_fmac_f32_e32 v90, v91, v90
	v_div_scale_f32 v91, vcc, v83, v84, v83
	v_mul_f32_e32 v92, v91, v90
	v_fma_f32 v93, -v89, v92, v91
	v_fmac_f32_e32 v92, v93, v90
	v_fma_f32 v89, -v89, v92, v91
	v_div_fmas_f32 v89, v89, v90, v92
	v_div_fixup_f32 v83, v89, v84, v83
	v_mul_f32_e32 v83, v85, v83
	v_cvt_pk_bf16_f32 v89, v82, v83
	v_or_b32_e32 v82, 48, v160
	v_ashrrev_i32_e32 v83, 31, v82
	global_store_dwordx4 v[98:99], v[86:89], off offset:256
	s_nop 1
	v_lshlrev_b64 v[86:87], 12, v[82:83]
	v_mad_i64_i32 v[82:83], s[12:13], v82, s75, v[162:163]
	v_lshl_add_u64 v[82:83], v[82:83], 0, v[144:145]
	v_lshl_add_u64 v[88:89], v[82:83], 0, s[26:27]
	v_add_co_u32_e32 v82, vcc, s5, v82
	s_nop 1
	v_addc_co_u32_e32 v83, vcc, 0, v83, vcc
	global_load_dwordx4 v[82:85], v[82:83], off
	s_waitcnt vmcnt(0)
; __device__ __forceinline__ unsigned cvt_pk_bf16(float lo, float hi) { unsigned r; asm volatile("v_cvt_pk_bf16_f32 %0, %1, %2" : "=v"(r) : "v"(lo), "v"(hi)); return r; }
; __device__ __forceinline__ float bflo(unsigned u) { return __uint_as_float(u << 16); }
; __device__ __forceinline__ float bfhi(unsigned u) { return __uint_as_float(u & 0xffff0000u); }
; __device__ __forceinline__ float silu_f(float v) { return v / (1.f + __expf(-v)); }
;     __device__ __forceinline__ void operator()(const pg8::f32x4 (&acc)[2][2][4][2], const pg8::Unit& u, int wr, int wc, int fr, int fq) const {
;     ...
;             for (int m = 0; m < 4; ++m) { const size_t row = (size_t)(row0 + ai * 128 + m * 16);
; #pragma unroll
;                 for (int bj = 0; bj < 2; ++bj) { const pg8::f32x4 v0 = acc[ai][bj][m][0], v1 = acc[ai][bj][m][1];
;                     const u32x4 gz = *(const u32x4*)(Z + row * DIN + goff + col0 + bj * 128); u32x4 w;
;                     w.x = pg8::cvt_pk_bf16(v0[0] * silu_f(bflo(gz.x)), v0[1] * silu_f(bfhi(gz.x))); w.y = pg8::cvt_pk_bf16(v0[2] * silu_f(bflo(gz.y)), v0[3] * silu_f(bfhi(gz.y)));
;                     w.z = pg8::cvt_pk_bf16(v1[0] * silu_f(bflo(gz.z)), v1[1] * silu_f(bfhi(gz.z))); w.w = pg8::cvt_pk_bf16(v1[2] * silu_f(bflo(gz.w)), v1[3] * silu_f(bfhi(gz.w)));
;                     *(u32x4*)(O + row * DM + coff + col0 + bj * 128) = w; } }
	v_lshlrev_b32_e32 v90, 16, v82
	v_mul_f32_e32 v91, 0xbfb8aa3b, v90
	v_exp_f32_e32 v91, v91
	v_and_b32_e32 v82, 0xffff0000, v82
	v_add_f32_e32 v91, 1.0, v91
	v_div_scale_f32 v92, s[12:13], v91, v91, v90
	v_rcp_f32_e32 v93, v92
	s_nop 0
	v_fma_f32 v94, -v92, v93, 1.0
	v_fmac_f32_e32 v93, v94, v93
	v_div_scale_f32 v94, vcc, v90, v91, v90
	v_mul_f32_e32 v95, v94, v93
	v_fma_f32 v96, -v92, v95, v94
	v_fmac_f32_e32 v95, v96, v93
	v_fma_f32 v92, -v92, v95, v94
	v_div_fmas_f32 v92, v92, v93, v95
	v_div_fixup_f32 v90, v92, v91, v90
	v_mul_f32_e32 v78, v78, v90
	v_mul_f32_e32 v90, 0xbfb8aa3b, v82
	v_exp_f32_e32 v90, v90
	s_nop 0
	v_add_f32_e32 v90, 1.0, v90
	v_div_scale_f32 v91, s[12:13], v90, v90, v82
	v_rcp_f32_e32 v92, v91
	s_nop 0
	v_fma_f32 v93, -v91, v92, 1.0
	v_fmac_f32_e32 v92, v93, v92
	v_div_scale_f32 v93, vcc, v82, v90, v82
	v_mul_f32_e32 v94, v93, v92
	v_fma_f32 v95, -v91, v94, v93
	v_fmac_f32_e32 v94, v95, v92
	v_fma_f32 v91, -v91, v94, v93
	v_div_fmas_f32 v91, v91, v92, v94
	v_div_fixup_f32 v82, v91, v90, v82
	v_mul_f32_e32 v79, v79, v82
	v_cvt_pk_bf16_f32 v78, v78, v79
	v_lshlrev_b32_e32 v79, 16, v83
	v_mul_f32_e32 v82, 0xbfb8aa3b, v79
	v_exp_f32_e32 v82, v82
	s_nop 0
	v_add_f32_e32 v82, 1.0, v82
	v_div_scale_f32 v90, s[12:13], v82, v82, v79
	v_rcp_f32_e32 v91, v90
	s_nop 0
	v_fma_f32 v92, -v90, v91, 1.0
	v_fmac_f32_e32 v91, v92, v91
	v_div_scale_f32 v92, vcc, v79, v82, v79
	v_mul_f32_e32 v93, v92, v91
	v_fma_f32 v94, -v90, v93, v92
	v_fmac_f32_e32 v93, v94, v91
	v_fma_f32 v90, -v90, v93, v92
	v_div_fmas_f32 v90, v90, v91, v93
	v_div_fixup_f32 v79, v90, v82, v79
	v_mul_f32_e32 v79, v80, v79
	v_and_b32_e32 v80, 0xffff0000, v83
	v_mul_f32_e32 v82, 0xbfb8aa3b, v80
	v_exp_f32_e32 v82, v82
	s_nop 0
	v_add_f32_e32 v82, 1.0, v82
	v_div_scale_f32 v83, s[12:13], v82, v82, v80
	v_rcp_f32_e32 v90, v83
	s_nop 0
	v_fma_f32 v91, -v83, v90, 1.0
	v_fmac_f32_e32 v90, v91, v90
	v_div_scale_f32 v91, vcc, v80, v82, v80
	v_mul_f32_e32 v92, v91, v90
	v_fma_f32 v93, -v83, v92, v91
	v_fmac_f32_e32 v92, v93, v90
	v_fma_f32 v83, -v83, v92, v91
	v_div_fmas_f32 v83, v83, v90, v92
	v_div_fixup_f32 v80, v83, v82, v80
	v_mul_f32_e32 v80, v81, v80
	v_cvt_pk_bf16_f32 v79, v79, v80
	v_lshlrev_b32_e32 v80, 16, v84
	v_mul_f32_e32 v81, 0xbfb8aa3b, v80
	v_exp_f32_e32 v81, v81
	s_nop 0
	v_add_f32_e32 v81, 1.0, v81
	v_div_scale_f32 v82, s[12:13], v81, v81, v80
	v_rcp_f32_e32 v83, v82
	s_nop 0
	v_fma_f32 v90, -v82, v83, 1.0
	v_fmac_f32_e32 v83, v90, v83
	v_div_scale_f32 v90, vcc, v80, v81, v80
	v_mul_f32_e32 v91, v90, v83
	v_fma_f32 v92, -v82, v91, v90
	v_fmac_f32_e32 v91, v92, v83
	v_fma_f32 v82, -v82, v91, v90
	v_div_fmas_f32 v82, v82, v83, v91
	v_div_fixup_f32 v80, v82, v81, v80
	v_mul_f32_e32 v74, v74, v80
	v_and_b32_e32 v80, 0xffff0000, v84
	v_mul_f32_e32 v81, 0xbfb8aa3b, v80
	v_exp_f32_e32 v81, v81
	s_nop 0
	v_add_f32_e32 v81, 1.0, v81
	v_div_scale_f32 v82, s[12:13], v81, v81, v80
	v_rcp_f32_e32 v83, v82
	s_nop 0
	v_fma_f32 v84, -v82, v83, 1.0
	v_fmac_f32_e32 v83, v84, v83
	v_div_scale_f32 v84, vcc, v80, v81, v80
	v_mul_f32_e32 v90, v84, v83
	v_fma_f32 v91, -v82, v90, v84
	v_fmac_f32_e32 v90, v91, v83
	v_fma_f32 v82, -v82, v90, v84
	v_div_fmas_f32 v82, v82, v83, v90
	v_div_fixup_f32 v80, v82, v81, v80
	v_mul_f32_e32 v75, v75, v80
	v_cvt_pk_bf16_f32 v80, v74, v75
	v_lshlrev_b32_e32 v74, 16, v85
	v_mul_f32_e32 v75, 0xbfb8aa3b, v74
	v_exp_f32_e32 v75, v75
	s_nop 0
	v_add_f32_e32 v75, 1.0, v75
	v_div_scale_f32 v81, s[12:13], v75, v75, v74
	v_rcp_f32_e32 v82, v81
	s_nop 0
	v_fma_f32 v83, -v81, v82, 1.0
	v_fmac_f32_e32 v82, v83, v82
	v_div_scale_f32 v83, vcc, v74, v75, v74
	v_mul_f32_e32 v84, v83, v82
	v_fma_f32 v90, -v81, v84, v83
	v_fmac_f32_e32 v84, v90, v82
	v_fma_f32 v81, -v81, v84, v83
	v_div_fmas_f32 v81, v81, v82, v84
	v_div_fixup_f32 v74, v81, v75, v74
	v_and_b32_e32 v75, 0xffff0000, v85
	v_mul_f32_e32 v74, v76, v74
	v_mul_f32_e32 v76, 0xbfb8aa3b, v75
	v_exp_f32_e32 v76, v76
	s_nop 0
	v_add_f32_e32 v76, 1.0, v76
	v_div_scale_f32 v81, s[12:13], v76, v76, v75
	v_rcp_f32_e32 v82, v81
	s_nop 0
	v_fma_f32 v83, -v81, v82, 1.0
	v_fmac_f32_e32 v82, v83, v82
	v_div_scale_f32 v83, vcc, v75, v76, v75
	v_mul_f32_e32 v84, v83, v82
	v_fma_f32 v85, -v81, v84, v83
	v_fmac_f32_e32 v84, v85, v82
	v_fma_f32 v81, -v81, v84, v83
	v_div_fmas_f32 v81, v81, v82, v84
	v_div_fixup_f32 v75, v81, v76, v75
	v_mul_f32_e32 v75, v77, v75
	v_cvt_pk_bf16_f32 v81, v74, v75
	v_lshl_add_u64 v[74:75], s[72:73], 0, v[86:87]
	v_lshl_add_u64 v[82:83], v[74:75], 0, v[144:145]
	global_store_dwordx4 v[82:83], v[78:81], off
	global_load_dwordx4 v[74:77], v[88:89], off offset:256
	s_waitcnt vmcnt(0)
; __device__ __forceinline__ unsigned cvt_pk_bf16(float lo, float hi) { unsigned r; asm volatile("v_cvt_pk_bf16_f32 %0, %1, %2" : "=v"(r) : "v"(lo), "v"(hi)); return r; }
; __device__ __forceinline__ float bflo(unsigned u) { return __uint_as_float(u << 16); }
; __device__ __forceinline__ float bfhi(unsigned u) { return __uint_as_float(u & 0xffff0000u); }
; __device__ __forceinline__ float silu_f(float v) { return v / (1.f + __expf(-v)); }
;     __device__ __forceinline__ void operator()(const pg8::f32x4 (&acc)[2][2][4][2], const pg8::Unit& u, int wr, int wc, int fr, int fq) const {
;     ...
;             for (int m = 0; m < 4; ++m) { const size_t row = (size_t)(row0 + ai * 128 + m * 16);
; #pragma unroll
;                 for (int bj = 0; bj < 2; ++bj) { const pg8::f32x4 v0 = acc[ai][bj][m][0], v1 = acc[ai][bj][m][1];
;                     const u32x4 gz = *(const u32x4*)(Z + row * DIN + goff + col0 + bj * 128); u32x4 w;
;                     w.x = pg8::cvt_pk_bf16(v0[0] * silu_f(bflo(gz.x)), v0[1] * silu_f(bfhi(gz.x))); w.y = pg8::cvt_pk_bf16(v0[2] * silu_f(bflo(gz.y)), v0[3] * silu_f(bfhi(gz.y)));
;                     w.z = pg8::cvt_pk_bf16(v1[0] * silu_f(bflo(gz.z)), v1[1] * silu_f(bfhi(gz.z))); w.w = pg8::cvt_pk_bf16(v1[2] * silu_f(bflo(gz.w)), v1[3] * silu_f(bfhi(gz.w)));
;                     *(u32x4*)(O + row * DM + coff + col0 + bj * 128) = w; } }
	v_lshlrev_b32_e32 v78, 16, v74
	v_mul_f32_e32 v79, 0xbfb8aa3b, v78
	v_exp_f32_e32 v79, v79
	v_and_b32_e32 v74, 0xffff0000, v74
	v_add_f32_e32 v79, 1.0, v79
	v_div_scale_f32 v80, s[12:13], v79, v79, v78
	v_rcp_f32_e32 v81, v80
	s_nop 0
	v_fma_f32 v84, -v80, v81, 1.0
	v_fmac_f32_e32 v81, v84, v81
	v_div_scale_f32 v84, vcc, v78, v79, v78
	v_mul_f32_e32 v85, v84, v81
	v_fma_f32 v86, -v80, v85, v84
	v_fmac_f32_e32 v85, v86, v81
	v_fma_f32 v80, -v80, v85, v84
	v_div_fmas_f32 v80, v80, v81, v85
	v_div_fixup_f32 v78, v80, v79, v78
	v_mul_f32_e32 v70, v70, v78
	v_mul_f32_e32 v78, 0xbfb8aa3b, v74
	v_exp_f32_e32 v78, v78
	s_nop 0
	v_add_f32_e32 v78, 1.0, v78
	v_div_scale_f32 v79, s[12:13], v78, v78, v74
	v_rcp_f32_e32 v80, v79
	s_nop 0
	v_fma_f32 v81, -v79, v80, 1.0
	v_fmac_f32_e32 v80, v81, v80
	v_div_scale_f32 v81, vcc, v74, v78, v74
	v_mul_f32_e32 v84, v81, v80
	v_fma_f32 v85, -v79, v84, v81
	v_fmac_f32_e32 v84, v85, v80
	v_fma_f32 v79, -v79, v84, v81
	v_div_fmas_f32 v79, v79, v80, v84
	v_div_fixup_f32 v74, v79, v78, v74
	v_mul_f32_e32 v71, v71, v74
	v_cvt_pk_bf16_f32 v70, v70, v71
	v_lshlrev_b32_e32 v71, 16, v75
	v_mul_f32_e32 v74, 0xbfb8aa3b, v71
	v_exp_f32_e32 v74, v74
	s_nop 0
	v_add_f32_e32 v74, 1.0, v74
	v_div_scale_f32 v78, s[12:13], v74, v74, v71
	v_rcp_f32_e32 v79, v78
	s_nop 0
	v_fma_f32 v80, -v78, v79, 1.0
	v_fmac_f32_e32 v79, v80, v79
	v_div_scale_f32 v80, vcc, v71, v74, v71
	v_mul_f32_e32 v81, v80, v79
	v_fma_f32 v84, -v78, v81, v80
	v_fmac_f32_e32 v81, v84, v79
	v_fma_f32 v78, -v78, v81, v80
	v_div_fmas_f32 v78, v78, v79, v81
	v_div_fixup_f32 v71, v78, v74, v71
	v_mul_f32_e32 v71, v72, v71
	v_and_b32_e32 v72, 0xffff0000, v75
	v_mul_f32_e32 v74, 0xbfb8aa3b, v72
	v_exp_f32_e32 v74, v74
	s_nop 0
	v_add_f32_e32 v74, 1.0, v74
	v_div_scale_f32 v75, s[12:13], v74, v74, v72
	v_rcp_f32_e32 v78, v75
	s_nop 0
	v_fma_f32 v79, -v75, v78, 1.0
	v_fmac_f32_e32 v78, v79, v78
	v_div_scale_f32 v79, vcc, v72, v74, v72
	v_mul_f32_e32 v80, v79, v78
	v_fma_f32 v81, -v75, v80, v79
	v_fmac_f32_e32 v80, v81, v78
	v_fma_f32 v75, -v75, v80, v79
	v_div_fmas_f32 v75, v75, v78, v80
	v_div_fixup_f32 v72, v75, v74, v72
	v_mul_f32_e32 v72, v73, v72
	v_cvt_pk_bf16_f32 v71, v71, v72
	v_lshlrev_b32_e32 v72, 16, v76
	v_mul_f32_e32 v73, 0xbfb8aa3b, v72
	v_exp_f32_e32 v73, v73
	s_nop 0
	v_add_f32_e32 v73, 1.0, v73
	v_div_scale_f32 v74, s[12:13], v73, v73, v72
	v_rcp_f32_e32 v75, v74
	s_nop 0
	v_fma_f32 v78, -v74, v75, 1.0
	v_fmac_f32_e32 v75, v78, v75
	v_div_scale_f32 v78, vcc, v72, v73, v72
	v_mul_f32_e32 v79, v78, v75
	v_fma_f32 v80, -v74, v79, v78
	v_fmac_f32_e32 v79, v80, v75
	v_fma_f32 v74, -v74, v79, v78
	v_div_fmas_f32 v74, v74, v75, v79
	v_div_fixup_f32 v72, v74, v73, v72
	v_mul_f32_e32 v66, v66, v72
	v_and_b32_e32 v72, 0xffff0000, v76
	v_mul_f32_e32 v73, 0xbfb8aa3b, v72
	v_exp_f32_e32 v73, v73
	s_nop 0
	v_add_f32_e32 v73, 1.0, v73
	v_div_scale_f32 v74, s[12:13], v73, v73, v72
	v_rcp_f32_e32 v75, v74
	s_nop 0
	v_fma_f32 v76, -v74, v75, 1.0
	v_fmac_f32_e32 v75, v76, v75
	v_div_scale_f32 v76, vcc, v72, v73, v72
	v_mul_f32_e32 v78, v76, v75
	v_fma_f32 v79, -v74, v78, v76
	v_fmac_f32_e32 v78, v79, v75
	v_fma_f32 v74, -v74, v78, v76
	v_div_fmas_f32 v74, v74, v75, v78
	v_div_fixup_f32 v72, v74, v73, v72
	v_mul_f32_e32 v67, v67, v72
	v_cvt_pk_bf16_f32 v72, v66, v67
	v_lshlrev_b32_e32 v66, 16, v77
	v_mul_f32_e32 v67, 0xbfb8aa3b, v66
	v_exp_f32_e32 v67, v67
	s_nop 0
	v_add_f32_e32 v67, 1.0, v67
	v_div_scale_f32 v73, s[12:13], v67, v67, v66
	v_rcp_f32_e32 v74, v73
	s_nop 0
	v_fma_f32 v75, -v73, v74, 1.0
	v_fmac_f32_e32 v74, v75, v74
	v_div_scale_f32 v75, vcc, v66, v67, v66
	v_mul_f32_e32 v76, v75, v74
	v_fma_f32 v78, -v73, v76, v75
	v_fmac_f32_e32 v76, v78, v74
	v_fma_f32 v73, -v73, v76, v75
	v_div_fmas_f32 v73, v73, v74, v76
	v_div_fixup_f32 v66, v73, v67, v66
	v_and_b32_e32 v67, 0xffff0000, v77
	v_mul_f32_e32 v66, v68, v66
	v_mul_f32_e32 v68, 0xbfb8aa3b, v67
	v_exp_f32_e32 v68, v68
	s_nop 0
	v_add_f32_e32 v68, 1.0, v68
	v_div_scale_f32 v73, s[12:13], v68, v68, v67
	v_rcp_f32_e32 v74, v73
	s_nop 0
	v_fma_f32 v75, -v73, v74, 1.0
	v_fmac_f32_e32 v74, v75, v74
	v_div_scale_f32 v75, vcc, v67, v68, v67
	v_mul_f32_e32 v76, v75, v74
	v_fma_f32 v77, -v73, v76, v75
	v_fmac_f32_e32 v76, v77, v74
	v_fma_f32 v73, -v73, v76, v75
	v_div_fmas_f32 v73, v73, v74, v76
	v_div_fixup_f32 v67, v73, v68, v67
	v_mul_f32_e32 v67, v69, v67
	v_cvt_pk_bf16_f32 v73, v66, v67
	v_add_u32_e32 v66, 0x80, v160
	v_ashrrev_i32_e32 v67, 31, v66
	global_store_dwordx4 v[82:83], v[70:73], off offset:256
	s_nop 1
	v_lshlrev_b64 v[70:71], 12, v[66:67]
	v_mad_i64_i32 v[66:67], s[12:13], v66, s75, v[162:163]
	v_lshl_add_u64 v[66:67], v[66:67], 0, v[144:145]
	v_lshl_add_u64 v[72:73], v[66:67], 0, s[26:27]
	v_add_co_u32_e32 v66, vcc, s5, v66
	s_nop 1
	v_addc_co_u32_e32 v67, vcc, 0, v67, vcc
	global_load_dwordx4 v[66:69], v[66:67], off
	s_waitcnt vmcnt(0)
; __device__ __forceinline__ unsigned cvt_pk_bf16(float lo, float hi) { unsigned r; asm volatile("v_cvt_pk_bf16_f32 %0, %1, %2" : "=v"(r) : "v"(lo), "v"(hi)); return r; }
; __device__ __forceinline__ float bflo(unsigned u) { return __uint_as_float(u << 16); }
; __device__ __forceinline__ float bfhi(unsigned u) { return __uint_as_float(u & 0xffff0000u); }
; __device__ __forceinline__ float silu_f(float v) { return v / (1.f + __expf(-v)); }
;     __device__ __forceinline__ void operator()(const pg8::f32x4 (&acc)[2][2][4][2], const pg8::Unit& u, int wr, int wc, int fr, int fq) const {
;     ...
;             for (int m = 0; m < 4; ++m) { const size_t row = (size_t)(row0 + ai * 128 + m * 16);
; #pragma unroll
;                 for (int bj = 0; bj < 2; ++bj) { const pg8::f32x4 v0 = acc[ai][bj][m][0], v1 = acc[ai][bj][m][1];
;                     const u32x4 gz = *(const u32x4*)(Z + row * DIN + goff + col0 + bj * 128); u32x4 w;
;                     w.x = pg8::cvt_pk_bf16(v0[0] * silu_f(bflo(gz.x)), v0[1] * silu_f(bfhi(gz.x))); w.y = pg8::cvt_pk_bf16(v0[2] * silu_f(bflo(gz.y)), v0[3] * silu_f(bfhi(gz.y)));
;                     w.z = pg8::cvt_pk_bf16(v1[0] * silu_f(bflo(gz.z)), v1[1] * silu_f(bfhi(gz.z))); w.w = pg8::cvt_pk_bf16(v1[2] * silu_f(bflo(gz.w)), v1[3] * silu_f(bfhi(gz.w)));
;                     *(u32x4*)(O + row * DM + coff + col0 + bj * 128) = w; } }
	v_lshlrev_b32_e32 v74, 16, v66
	v_mul_f32_e32 v75, 0xbfb8aa3b, v74
	v_exp_f32_e32 v75, v75
	v_and_b32_e32 v66, 0xffff0000, v66
	v_add_f32_e32 v75, 1.0, v75
	v_div_scale_f32 v76, s[12:13], v75, v75, v74
	v_rcp_f32_e32 v77, v76
	s_nop 0
	v_fma_f32 v78, -v76, v77, 1.0
	v_fmac_f32_e32 v77, v78, v77
	v_div_scale_f32 v78, vcc, v74, v75, v74
	v_mul_f32_e32 v79, v78, v77
	v_fma_f32 v80, -v76, v79, v78
	v_fmac_f32_e32 v79, v80, v77
	v_fma_f32 v76, -v76, v79, v78
	v_div_fmas_f32 v76, v76, v77, v79
	v_div_fixup_f32 v74, v76, v75, v74
	v_mul_f32_e32 v62, v62, v74
	v_mul_f32_e32 v74, 0xbfb8aa3b, v66
	v_exp_f32_e32 v74, v74
	s_nop 0
	v_add_f32_e32 v74, 1.0, v74
	v_div_scale_f32 v75, s[12:13], v74, v74, v66
	v_rcp_f32_e32 v76, v75
	s_nop 0
	v_fma_f32 v77, -v75, v76, 1.0
	v_fmac_f32_e32 v76, v77, v76
	v_div_scale_f32 v77, vcc, v66, v74, v66
	v_mul_f32_e32 v78, v77, v76
	v_fma_f32 v79, -v75, v78, v77
	v_fmac_f32_e32 v78, v79, v76
	v_fma_f32 v75, -v75, v78, v77
	v_div_fmas_f32 v75, v75, v76, v78
	v_div_fixup_f32 v66, v75, v74, v66
	v_mul_f32_e32 v63, v63, v66
	v_cvt_pk_bf16_f32 v62, v62, v63
	v_lshlrev_b32_e32 v63, 16, v67
	v_mul_f32_e32 v66, 0xbfb8aa3b, v63
	v_exp_f32_e32 v66, v66
	s_nop 0
	v_add_f32_e32 v66, 1.0, v66
	v_div_scale_f32 v74, s[12:13], v66, v66, v63
	v_rcp_f32_e32 v75, v74
	s_nop 0
	v_fma_f32 v76, -v74, v75, 1.0
	v_fmac_f32_e32 v75, v76, v75
	v_div_scale_f32 v76, vcc, v63, v66, v63
	v_mul_f32_e32 v77, v76, v75
	v_fma_f32 v78, -v74, v77, v76
	v_fmac_f32_e32 v77, v78, v75
	v_fma_f32 v74, -v74, v77, v76
	v_div_fmas_f32 v74, v74, v75, v77
	v_div_fixup_f32 v63, v74, v66, v63
	v_mul_f32_e32 v63, v64, v63
	v_and_b32_e32 v64, 0xffff0000, v67
	v_mul_f32_e32 v66, 0xbfb8aa3b, v64
	v_exp_f32_e32 v66, v66
	s_nop 0
	v_add_f32_e32 v66, 1.0, v66
	v_div_scale_f32 v67, s[12:13], v66, v66, v64
	v_rcp_f32_e32 v74, v67
	s_nop 0
	v_fma_f32 v75, -v67, v74, 1.0
	v_fmac_f32_e32 v74, v75, v74
	v_div_scale_f32 v75, vcc, v64, v66, v64
	v_mul_f32_e32 v76, v75, v74
	v_fma_f32 v77, -v67, v76, v75
	v_fmac_f32_e32 v76, v77, v74
	v_fma_f32 v67, -v67, v76, v75
	v_div_fmas_f32 v67, v67, v74, v76
	v_div_fixup_f32 v64, v67, v66, v64
	v_mul_f32_e32 v64, v65, v64
	v_cvt_pk_bf16_f32 v63, v63, v64
	v_lshlrev_b32_e32 v64, 16, v68
	v_mul_f32_e32 v65, 0xbfb8aa3b, v64
	v_exp_f32_e32 v65, v65
	s_nop 0
	v_add_f32_e32 v65, 1.0, v65
	v_div_scale_f32 v66, s[12:13], v65, v65, v64
	v_rcp_f32_e32 v67, v66
	s_nop 0
	v_fma_f32 v74, -v66, v67, 1.0
	v_fmac_f32_e32 v67, v74, v67
	v_div_scale_f32 v74, vcc, v64, v65, v64
	v_mul_f32_e32 v75, v74, v67
	v_fma_f32 v76, -v66, v75, v74
	v_fmac_f32_e32 v75, v76, v67
	v_fma_f32 v66, -v66, v75, v74
	v_div_fmas_f32 v66, v66, v67, v75
	v_div_fixup_f32 v64, v66, v65, v64
	v_mul_f32_e32 v58, v58, v64
	v_and_b32_e32 v64, 0xffff0000, v68
	v_mul_f32_e32 v65, 0xbfb8aa3b, v64
	v_exp_f32_e32 v65, v65
	s_nop 0
	v_add_f32_e32 v65, 1.0, v65
	v_div_scale_f32 v66, s[12:13], v65, v65, v64
	v_rcp_f32_e32 v67, v66
	s_nop 0
	v_fma_f32 v68, -v66, v67, 1.0
	v_fmac_f32_e32 v67, v68, v67
	v_div_scale_f32 v68, vcc, v64, v65, v64
	v_mul_f32_e32 v74, v68, v67
	v_fma_f32 v75, -v66, v74, v68
	v_fmac_f32_e32 v74, v75, v67
	v_fma_f32 v66, -v66, v74, v68
	v_div_fmas_f32 v66, v66, v67, v74
	v_div_fixup_f32 v64, v66, v65, v64
	v_mul_f32_e32 v59, v59, v64
	v_cvt_pk_bf16_f32 v64, v58, v59
	v_lshlrev_b32_e32 v58, 16, v69
	v_mul_f32_e32 v59, 0xbfb8aa3b, v58
	v_exp_f32_e32 v59, v59
	s_nop 0
	v_add_f32_e32 v59, 1.0, v59
	v_div_scale_f32 v65, s[12:13], v59, v59, v58
	v_rcp_f32_e32 v66, v65
	s_nop 0
	v_fma_f32 v67, -v65, v66, 1.0
	v_fmac_f32_e32 v66, v67, v66
	v_div_scale_f32 v67, vcc, v58, v59, v58
	v_mul_f32_e32 v68, v67, v66
	v_fma_f32 v74, -v65, v68, v67
	v_fmac_f32_e32 v68, v74, v66
	v_fma_f32 v65, -v65, v68, v67
	v_div_fmas_f32 v65, v65, v66, v68
	v_div_fixup_f32 v58, v65, v59, v58
	v_and_b32_e32 v59, 0xffff0000, v69
	v_mul_f32_e32 v58, v60, v58
	v_mul_f32_e32 v60, 0xbfb8aa3b, v59
	v_exp_f32_e32 v60, v60
	s_nop 0
	v_add_f32_e32 v60, 1.0, v60
	v_div_scale_f32 v65, s[12:13], v60, v60, v59
	v_rcp_f32_e32 v66, v65
	s_nop 0
	v_fma_f32 v67, -v65, v66, 1.0
	v_fmac_f32_e32 v66, v67, v66
	v_div_scale_f32 v67, vcc, v59, v60, v59
	v_mul_f32_e32 v68, v67, v66
	v_fma_f32 v69, -v65, v68, v67
	v_fmac_f32_e32 v68, v69, v66
	v_fma_f32 v65, -v65, v68, v67
	v_div_fmas_f32 v65, v65, v66, v68
	v_div_fixup_f32 v59, v65, v60, v59
	v_mul_f32_e32 v59, v61, v59
	v_cvt_pk_bf16_f32 v65, v58, v59
	v_lshl_add_u64 v[58:59], s[72:73], 0, v[70:71]
	v_lshl_add_u64 v[66:67], v[58:59], 0, v[144:145]
	global_store_dwordx4 v[66:67], v[62:65], off
	global_load_dwordx4 v[58:61], v[72:73], off offset:256
	s_waitcnt vmcnt(0)
; __device__ __forceinline__ unsigned cvt_pk_bf16(float lo, float hi) { unsigned r; asm volatile("v_cvt_pk_bf16_f32 %0, %1, %2" : "=v"(r) : "v"(lo), "v"(hi)); return r; }
; __device__ __forceinline__ float bflo(unsigned u) { return __uint_as_float(u << 16); }
; __device__ __forceinline__ float bfhi(unsigned u) { return __uint_as_float(u & 0xffff0000u); }
; __device__ __forceinline__ float silu_f(float v) { return v / (1.f + __expf(-v)); }
;     __device__ __forceinline__ void operator()(const pg8::f32x4 (&acc)[2][2][4][2], const pg8::Unit& u, int wr, int wc, int fr, int fq) const {
;     ...
;             for (int m = 0; m < 4; ++m) { const size_t row = (size_t)(row0 + ai * 128 + m * 16);
; #pragma unroll
;                 for (int bj = 0; bj < 2; ++bj) { const pg8::f32x4 v0 = acc[ai][bj][m][0], v1 = acc[ai][bj][m][1];
;                     const u32x4 gz = *(const u32x4*)(Z + row * DIN + goff + col0 + bj * 128); u32x4 w;
;                     w.x = pg8::cvt_pk_bf16(v0[0] * silu_f(bflo(gz.x)), v0[1] * silu_f(bfhi(gz.x))); w.y = pg8::cvt_pk_bf16(v0[2] * silu_f(bflo(gz.y)), v0[3] * silu_f(bfhi(gz.y)));
;                     w.z = pg8::cvt_pk_bf16(v1[0] * silu_f(bflo(gz.z)), v1[1] * silu_f(bfhi(gz.z))); w.w = pg8::cvt_pk_bf16(v1[2] * silu_f(bflo(gz.w)), v1[3] * silu_f(bfhi(gz.w)));
;                     *(u32x4*)(O + row * DM + coff + col0 + bj * 128) = w; } }
	v_lshlrev_b32_e32 v62, 16, v58
	v_mul_f32_e32 v63, 0xbfb8aa3b, v62
	v_exp_f32_e32 v63, v63
	v_and_b32_e32 v58, 0xffff0000, v58
	v_add_f32_e32 v63, 1.0, v63
	v_div_scale_f32 v64, s[12:13], v63, v63, v62
	v_rcp_f32_e32 v65, v64
	s_nop 0
	v_fma_f32 v68, -v64, v65, 1.0
	v_fmac_f32_e32 v65, v68, v65
	v_div_scale_f32 v68, vcc, v62, v63, v62
	v_mul_f32_e32 v69, v68, v65
	v_fma_f32 v70, -v64, v69, v68
	v_fmac_f32_e32 v69, v70, v65
	v_fma_f32 v64, -v64, v69, v68
	v_div_fmas_f32 v64, v64, v65, v69
	v_div_fixup_f32 v62, v64, v63, v62
	v_mul_f32_e32 v54, v54, v62
	v_mul_f32_e32 v62, 0xbfb8aa3b, v58
	v_exp_f32_e32 v62, v62
	s_nop 0
	v_add_f32_e32 v62, 1.0, v62
	v_div_scale_f32 v63, s[12:13], v62, v62, v58
	v_rcp_f32_e32 v64, v63
	s_nop 0
	v_fma_f32 v65, -v63, v64, 1.0
	v_fmac_f32_e32 v64, v65, v64
	v_div_scale_f32 v65, vcc, v58, v62, v58
	v_mul_f32_e32 v68, v65, v64
	v_fma_f32 v69, -v63, v68, v65
	v_fmac_f32_e32 v68, v69, v64
	v_fma_f32 v63, -v63, v68, v65
	v_div_fmas_f32 v63, v63, v64, v68
	v_div_fixup_f32 v58, v63, v62, v58
	v_mul_f32_e32 v55, v55, v58
	v_cvt_pk_bf16_f32 v54, v54, v55
	v_lshlrev_b32_e32 v55, 16, v59
	v_mul_f32_e32 v58, 0xbfb8aa3b, v55
	v_exp_f32_e32 v58, v58
	s_nop 0
	v_add_f32_e32 v58, 1.0, v58
	v_div_scale_f32 v62, s[12:13], v58, v58, v55
	v_rcp_f32_e32 v63, v62
	s_nop 0
	v_fma_f32 v64, -v62, v63, 1.0
	v_fmac_f32_e32 v63, v64, v63
	v_div_scale_f32 v64, vcc, v55, v58, v55
	v_mul_f32_e32 v65, v64, v63
	v_fma_f32 v68, -v62, v65, v64
	v_fmac_f32_e32 v65, v68, v63
	v_fma_f32 v62, -v62, v65, v64
	v_div_fmas_f32 v62, v62, v63, v65
	v_div_fixup_f32 v55, v62, v58, v55
	v_mul_f32_e32 v55, v56, v55
	v_and_b32_e32 v56, 0xffff0000, v59
	v_mul_f32_e32 v58, 0xbfb8aa3b, v56
	v_exp_f32_e32 v58, v58
	s_nop 0
	v_add_f32_e32 v58, 1.0, v58
	v_div_scale_f32 v59, s[12:13], v58, v58, v56
	v_rcp_f32_e32 v62, v59
	s_nop 0
	v_fma_f32 v63, -v59, v62, 1.0
	v_fmac_f32_e32 v62, v63, v62
	v_div_scale_f32 v63, vcc, v56, v58, v56
	v_mul_f32_e32 v64, v63, v62
	v_fma_f32 v65, -v59, v64, v63
	v_fmac_f32_e32 v64, v65, v62
	v_fma_f32 v59, -v59, v64, v63
	v_div_fmas_f32 v59, v59, v62, v64
	v_div_fixup_f32 v56, v59, v58, v56
	v_mul_f32_e32 v56, v57, v56
	v_cvt_pk_bf16_f32 v55, v55, v56
	v_lshlrev_b32_e32 v56, 16, v60
	v_mul_f32_e32 v57, 0xbfb8aa3b, v56
	v_exp_f32_e32 v57, v57
	s_nop 0
	v_add_f32_e32 v57, 1.0, v57
	v_div_scale_f32 v58, s[12:13], v57, v57, v56
	v_rcp_f32_e32 v59, v58
	s_nop 0
	v_fma_f32 v62, -v58, v59, 1.0
	v_fmac_f32_e32 v59, v62, v59
	v_div_scale_f32 v62, vcc, v56, v57, v56
	v_mul_f32_e32 v63, v62, v59
	v_fma_f32 v64, -v58, v63, v62
	v_fmac_f32_e32 v63, v64, v59
	v_fma_f32 v58, -v58, v63, v62
	v_div_fmas_f32 v58, v58, v59, v63
	v_div_fixup_f32 v56, v58, v57, v56
	v_mul_f32_e32 v50, v50, v56
	v_and_b32_e32 v56, 0xffff0000, v60
	v_mul_f32_e32 v57, 0xbfb8aa3b, v56
	v_exp_f32_e32 v57, v57
	s_nop 0
	v_add_f32_e32 v57, 1.0, v57
	v_div_scale_f32 v58, s[12:13], v57, v57, v56
	v_rcp_f32_e32 v59, v58
	s_nop 0
	v_fma_f32 v60, -v58, v59, 1.0
	v_fmac_f32_e32 v59, v60, v59
	v_div_scale_f32 v60, vcc, v56, v57, v56
	v_mul_f32_e32 v62, v60, v59
	v_fma_f32 v63, -v58, v62, v60
	v_fmac_f32_e32 v62, v63, v59
	v_fma_f32 v58, -v58, v62, v60
	v_div_fmas_f32 v58, v58, v59, v62
	v_div_fixup_f32 v56, v58, v57, v56
	v_mul_f32_e32 v51, v51, v56
	v_cvt_pk_bf16_f32 v56, v50, v51
	v_lshlrev_b32_e32 v50, 16, v61
	v_mul_f32_e32 v51, 0xbfb8aa3b, v50
	v_exp_f32_e32 v51, v51
	s_nop 0
	v_add_f32_e32 v51, 1.0, v51
	v_div_scale_f32 v57, s[12:13], v51, v51, v50
	v_rcp_f32_e32 v58, v57
	s_nop 0
	v_fma_f32 v59, -v57, v58, 1.0
	v_fmac_f32_e32 v58, v59, v58
	v_div_scale_f32 v59, vcc, v50, v51, v50
	v_mul_f32_e32 v60, v59, v58
	v_fma_f32 v62, -v57, v60, v59
	v_fmac_f32_e32 v60, v62, v58
	v_fma_f32 v57, -v57, v60, v59
	v_div_fmas_f32 v57, v57, v58, v60
	v_div_fixup_f32 v50, v57, v51, v50
	v_and_b32_e32 v51, 0xffff0000, v61
	v_mul_f32_e32 v50, v52, v50
	v_mul_f32_e32 v52, 0xbfb8aa3b, v51
	v_exp_f32_e32 v52, v52
	s_nop 0
	v_add_f32_e32 v52, 1.0, v52
	v_div_scale_f32 v57, s[12:13], v52, v52, v51
	v_rcp_f32_e32 v58, v57
	s_nop 0
	v_fma_f32 v59, -v57, v58, 1.0
	v_fmac_f32_e32 v58, v59, v58
	v_div_scale_f32 v59, vcc, v51, v52, v51
	v_mul_f32_e32 v60, v59, v58
	v_fma_f32 v61, -v57, v60, v59
	v_fmac_f32_e32 v60, v61, v58
	v_fma_f32 v57, -v57, v60, v59
	v_div_fmas_f32 v57, v57, v58, v60
	v_div_fixup_f32 v51, v57, v52, v51
	v_mul_f32_e32 v51, v53, v51
	v_cvt_pk_bf16_f32 v57, v50, v51
	v_add_u32_e32 v50, 0x90, v160
	v_ashrrev_i32_e32 v51, 31, v50
	global_store_dwordx4 v[66:67], v[54:57], off offset:256
	s_nop 1
	v_lshlrev_b64 v[54:55], 12, v[50:51]
	v_mad_i64_i32 v[50:51], s[12:13], v50, s75, v[162:163]
	v_lshl_add_u64 v[50:51], v[50:51], 0, v[144:145]
	v_lshl_add_u64 v[56:57], v[50:51], 0, s[26:27]
	v_add_co_u32_e32 v50, vcc, s5, v50
	s_nop 1
	v_addc_co_u32_e32 v51, vcc, 0, v51, vcc
	global_load_dwordx4 v[50:53], v[50:51], off
	s_waitcnt vmcnt(0)
; __device__ __forceinline__ unsigned cvt_pk_bf16(float lo, float hi) { unsigned r; asm volatile("v_cvt_pk_bf16_f32 %0, %1, %2" : "=v"(r) : "v"(lo), "v"(hi)); return r; }
; __device__ __forceinline__ float bflo(unsigned u) { return __uint_as_float(u << 16); }
; __device__ __forceinline__ float bfhi(unsigned u) { return __uint_as_float(u & 0xffff0000u); }
; __device__ __forceinline__ float silu_f(float v) { return v / (1.f + __expf(-v)); }
;     __device__ __forceinline__ void operator()(const pg8::f32x4 (&acc)[2][2][4][2], const pg8::Unit& u, int wr, int wc, int fr, int fq) const {
;     ...
;             for (int m = 0; m < 4; ++m) { const size_t row = (size_t)(row0 + ai * 128 + m * 16);
; #pragma unroll
;                 for (int bj = 0; bj < 2; ++bj) { const pg8::f32x4 v0 = acc[ai][bj][m][0], v1 = acc[ai][bj][m][1];
;                     const u32x4 gz = *(const u32x4*)(Z + row * DIN + goff + col0 + bj * 128); u32x4 w;
;                     w.x = pg8::cvt_pk_bf16(v0[0] * silu_f(bflo(gz.x)), v0[1] * silu_f(bfhi(gz.x))); w.y = pg8::cvt_pk_bf16(v0[2] * silu_f(bflo(gz.y)), v0[3] * silu_f(bfhi(gz.y)));
;                     w.z = pg8::cvt_pk_bf16(v1[0] * silu_f(bflo(gz.z)), v1[1] * silu_f(bfhi(gz.z))); w.w = pg8::cvt_pk_bf16(v1[2] * silu_f(bflo(gz.w)), v1[3] * silu_f(bfhi(gz.w)));
;                     *(u32x4*)(O + row * DM + coff + col0 + bj * 128) = w; } }
	v_lshlrev_b32_e32 v58, 16, v50
	v_mul_f32_e32 v59, 0xbfb8aa3b, v58
	v_exp_f32_e32 v59, v59
	v_and_b32_e32 v50, 0xffff0000, v50
	v_add_f32_e32 v59, 1.0, v59
	v_div_scale_f32 v60, s[12:13], v59, v59, v58
	v_rcp_f32_e32 v61, v60
	s_nop 0
	v_fma_f32 v62, -v60, v61, 1.0
	v_fmac_f32_e32 v61, v62, v61
	v_div_scale_f32 v62, vcc, v58, v59, v58
	v_mul_f32_e32 v63, v62, v61
	v_fma_f32 v64, -v60, v63, v62
	v_fmac_f32_e32 v63, v64, v61
	v_fma_f32 v60, -v60, v63, v62
	v_div_fmas_f32 v60, v60, v61, v63
	v_div_fixup_f32 v58, v60, v59, v58
	v_mul_f32_e32 v46, v46, v58
	v_mul_f32_e32 v58, 0xbfb8aa3b, v50
	v_exp_f32_e32 v58, v58
	s_nop 0
	v_add_f32_e32 v58, 1.0, v58
	v_div_scale_f32 v59, s[12:13], v58, v58, v50
	v_rcp_f32_e32 v60, v59
	s_nop 0
	v_fma_f32 v61, -v59, v60, 1.0
	v_fmac_f32_e32 v60, v61, v60
	v_div_scale_f32 v61, vcc, v50, v58, v50
	v_mul_f32_e32 v62, v61, v60
	v_fma_f32 v63, -v59, v62, v61
	v_fmac_f32_e32 v62, v63, v60
	v_fma_f32 v59, -v59, v62, v61
	v_div_fmas_f32 v59, v59, v60, v62
	v_div_fixup_f32 v50, v59, v58, v50
	v_mul_f32_e32 v47, v47, v50
	v_cvt_pk_bf16_f32 v46, v46, v47
	v_lshlrev_b32_e32 v47, 16, v51
	v_mul_f32_e32 v50, 0xbfb8aa3b, v47
	v_exp_f32_e32 v50, v50
	s_nop 0
	v_add_f32_e32 v50, 1.0, v50
	v_div_scale_f32 v58, s[12:13], v50, v50, v47
	v_rcp_f32_e32 v59, v58
	s_nop 0
	v_fma_f32 v60, -v58, v59, 1.0
	v_fmac_f32_e32 v59, v60, v59
	v_div_scale_f32 v60, vcc, v47, v50, v47
	v_mul_f32_e32 v61, v60, v59
	v_fma_f32 v62, -v58, v61, v60
	v_fmac_f32_e32 v61, v62, v59
	v_fma_f32 v58, -v58, v61, v60
	v_div_fmas_f32 v58, v58, v59, v61
	v_div_fixup_f32 v47, v58, v50, v47
	v_mul_f32_e32 v47, v48, v47
	v_and_b32_e32 v48, 0xffff0000, v51
	v_mul_f32_e32 v50, 0xbfb8aa3b, v48
	v_exp_f32_e32 v50, v50
	s_nop 0
	v_add_f32_e32 v50, 1.0, v50
	v_div_scale_f32 v51, s[12:13], v50, v50, v48
	v_rcp_f32_e32 v58, v51
	s_nop 0
	v_fma_f32 v59, -v51, v58, 1.0
	v_fmac_f32_e32 v58, v59, v58
	v_div_scale_f32 v59, vcc, v48, v50, v48
	v_mul_f32_e32 v60, v59, v58
	v_fma_f32 v61, -v51, v60, v59
	v_fmac_f32_e32 v60, v61, v58
	v_fma_f32 v51, -v51, v60, v59
	v_div_fmas_f32 v51, v51, v58, v60
	v_div_fixup_f32 v48, v51, v50, v48
	v_mul_f32_e32 v48, v49, v48
	v_cvt_pk_bf16_f32 v47, v47, v48
	v_lshlrev_b32_e32 v48, 16, v52
	v_mul_f32_e32 v49, 0xbfb8aa3b, v48
	v_exp_f32_e32 v49, v49
	s_nop 0
	v_add_f32_e32 v49, 1.0, v49
	v_div_scale_f32 v50, s[12:13], v49, v49, v48
	v_rcp_f32_e32 v51, v50
	s_nop 0
	v_fma_f32 v58, -v50, v51, 1.0
	v_fmac_f32_e32 v51, v58, v51
	v_div_scale_f32 v58, vcc, v48, v49, v48
	v_mul_f32_e32 v59, v58, v51
	v_fma_f32 v60, -v50, v59, v58
	v_fmac_f32_e32 v59, v60, v51
	v_fma_f32 v50, -v50, v59, v58
	v_div_fmas_f32 v50, v50, v51, v59
	v_div_fixup_f32 v48, v50, v49, v48
	v_mul_f32_e32 v42, v42, v48
	v_and_b32_e32 v48, 0xffff0000, v52
	v_mul_f32_e32 v49, 0xbfb8aa3b, v48
	v_exp_f32_e32 v49, v49
	s_nop 0
	v_add_f32_e32 v49, 1.0, v49
	v_div_scale_f32 v50, s[12:13], v49, v49, v48
	v_rcp_f32_e32 v51, v50
	s_nop 0
	v_fma_f32 v52, -v50, v51, 1.0
	v_fmac_f32_e32 v51, v52, v51
	v_div_scale_f32 v52, vcc, v48, v49, v48
	v_mul_f32_e32 v58, v52, v51
	v_fma_f32 v59, -v50, v58, v52
	v_fmac_f32_e32 v58, v59, v51
	v_fma_f32 v50, -v50, v58, v52
	v_div_fmas_f32 v50, v50, v51, v58
	v_div_fixup_f32 v48, v50, v49, v48
	v_mul_f32_e32 v43, v43, v48
	v_cvt_pk_bf16_f32 v48, v42, v43
	v_lshlrev_b32_e32 v42, 16, v53
	v_mul_f32_e32 v43, 0xbfb8aa3b, v42
	v_exp_f32_e32 v43, v43
	s_nop 0
	v_add_f32_e32 v43, 1.0, v43
	v_div_scale_f32 v49, s[12:13], v43, v43, v42
	v_rcp_f32_e32 v50, v49
	s_nop 0
	v_fma_f32 v51, -v49, v50, 1.0
	v_fmac_f32_e32 v50, v51, v50
	v_div_scale_f32 v51, vcc, v42, v43, v42
	v_mul_f32_e32 v52, v51, v50
	v_fma_f32 v58, -v49, v52, v51
	v_fmac_f32_e32 v52, v58, v50
	v_fma_f32 v49, -v49, v52, v51
	v_div_fmas_f32 v49, v49, v50, v52
	v_div_fixup_f32 v42, v49, v43, v42
	v_and_b32_e32 v43, 0xffff0000, v53
	v_mul_f32_e32 v42, v44, v42
	v_mul_f32_e32 v44, 0xbfb8aa3b, v43
	v_exp_f32_e32 v44, v44
	s_nop 0
	v_add_f32_e32 v44, 1.0, v44
	v_div_scale_f32 v49, s[12:13], v44, v44, v43
	v_rcp_f32_e32 v50, v49
	s_nop 0
	v_fma_f32 v51, -v49, v50, 1.0
	v_fmac_f32_e32 v50, v51, v50
	v_div_scale_f32 v51, vcc, v43, v44, v43
	v_mul_f32_e32 v52, v51, v50
	v_fma_f32 v53, -v49, v52, v51
	v_fmac_f32_e32 v52, v53, v50
	v_fma_f32 v49, -v49, v52, v51
	v_div_fmas_f32 v49, v49, v50, v52
	v_div_fixup_f32 v43, v49, v44, v43
	v_mul_f32_e32 v43, v45, v43
	v_cvt_pk_bf16_f32 v49, v42, v43
	v_lshl_add_u64 v[42:43], s[72:73], 0, v[54:55]
	v_lshl_add_u64 v[50:51], v[42:43], 0, v[144:145]
	global_store_dwordx4 v[50:51], v[46:49], off
	global_load_dwordx4 v[42:45], v[56:57], off offset:256
	s_waitcnt vmcnt(0)
; __device__ __forceinline__ unsigned cvt_pk_bf16(float lo, float hi) { unsigned r; asm volatile("v_cvt_pk_bf16_f32 %0, %1, %2" : "=v"(r) : "v"(lo), "v"(hi)); return r; }
; __device__ __forceinline__ float bflo(unsigned u) { return __uint_as_float(u << 16); }
; __device__ __forceinline__ float bfhi(unsigned u) { return __uint_as_float(u & 0xffff0000u); }
; __device__ __forceinline__ float silu_f(float v) { return v / (1.f + __expf(-v)); }
;     __device__ __forceinline__ void operator()(const pg8::f32x4 (&acc)[2][2][4][2], const pg8::Unit& u, int wr, int wc, int fr, int fq) const {
;     ...
;             for (int m = 0; m < 4; ++m) { const size_t row = (size_t)(row0 + ai * 128 + m * 16);
; #pragma unroll
;                 for (int bj = 0; bj < 2; ++bj) { const pg8::f32x4 v0 = acc[ai][bj][m][0], v1 = acc[ai][bj][m][1];
;                     const u32x4 gz = *(const u32x4*)(Z + row * DIN + goff + col0 + bj * 128); u32x4 w;
;                     w.x = pg8::cvt_pk_bf16(v0[0] * silu_f(bflo(gz.x)), v0[1] * silu_f(bfhi(gz.x))); w.y = pg8::cvt_pk_bf16(v0[2] * silu_f(bflo(gz.y)), v0[3] * silu_f(bfhi(gz.y)));
;                     w.z = pg8::cvt_pk_bf16(v1[0] * silu_f(bflo(gz.z)), v1[1] * silu_f(bfhi(gz.z))); w.w = pg8::cvt_pk_bf16(v1[2] * silu_f(bflo(gz.w)), v1[3] * silu_f(bfhi(gz.w)));
;                     *(u32x4*)(O + row * DM + coff + col0 + bj * 128) = w; } }
	v_lshlrev_b32_e32 v46, 16, v42
	v_mul_f32_e32 v47, 0xbfb8aa3b, v46
	v_exp_f32_e32 v47, v47
	v_and_b32_e32 v42, 0xffff0000, v42
	v_add_f32_e32 v47, 1.0, v47
	v_div_scale_f32 v48, s[12:13], v47, v47, v46
	v_rcp_f32_e32 v49, v48
	s_nop 0
	v_fma_f32 v52, -v48, v49, 1.0
	v_fmac_f32_e32 v49, v52, v49
	v_div_scale_f32 v52, vcc, v46, v47, v46
	v_mul_f32_e32 v53, v52, v49
	v_fma_f32 v54, -v48, v53, v52
	v_fmac_f32_e32 v53, v54, v49
	v_fma_f32 v48, -v48, v53, v52
	v_div_fmas_f32 v48, v48, v49, v53
	v_div_fixup_f32 v46, v48, v47, v46
	v_mul_f32_e32 v38, v38, v46
	v_mul_f32_e32 v46, 0xbfb8aa3b, v42
	v_exp_f32_e32 v46, v46
	s_nop 0
	v_add_f32_e32 v46, 1.0, v46
	v_div_scale_f32 v47, s[12:13], v46, v46, v42
	v_rcp_f32_e32 v48, v47
	s_nop 0
	v_fma_f32 v49, -v47, v48, 1.0
	v_fmac_f32_e32 v48, v49, v48
	v_div_scale_f32 v49, vcc, v42, v46, v42
	v_mul_f32_e32 v52, v49, v48
	v_fma_f32 v53, -v47, v52, v49
	v_fmac_f32_e32 v52, v53, v48
	v_fma_f32 v47, -v47, v52, v49
	v_div_fmas_f32 v47, v47, v48, v52
	v_div_fixup_f32 v42, v47, v46, v42
	v_mul_f32_e32 v39, v39, v42
	v_cvt_pk_bf16_f32 v38, v38, v39
	v_lshlrev_b32_e32 v39, 16, v43
	v_mul_f32_e32 v42, 0xbfb8aa3b, v39
	v_exp_f32_e32 v42, v42
	s_nop 0
	v_add_f32_e32 v42, 1.0, v42
	v_div_scale_f32 v46, s[12:13], v42, v42, v39
	v_rcp_f32_e32 v47, v46
	s_nop 0
	v_fma_f32 v48, -v46, v47, 1.0
	v_fmac_f32_e32 v47, v48, v47
	v_div_scale_f32 v48, vcc, v39, v42, v39
	v_mul_f32_e32 v49, v48, v47
	v_fma_f32 v52, -v46, v49, v48
	v_fmac_f32_e32 v49, v52, v47
	v_fma_f32 v46, -v46, v49, v48
	v_div_fmas_f32 v46, v46, v47, v49
	v_div_fixup_f32 v39, v46, v42, v39
	v_mul_f32_e32 v39, v40, v39
	v_and_b32_e32 v40, 0xffff0000, v43
	v_mul_f32_e32 v42, 0xbfb8aa3b, v40
	v_exp_f32_e32 v42, v42
	s_nop 0
	v_add_f32_e32 v42, 1.0, v42
	v_div_scale_f32 v43, s[12:13], v42, v42, v40
	v_rcp_f32_e32 v46, v43
	s_nop 0
	v_fma_f32 v47, -v43, v46, 1.0
	v_fmac_f32_e32 v46, v47, v46
	v_div_scale_f32 v47, vcc, v40, v42, v40
	v_mul_f32_e32 v48, v47, v46
	v_fma_f32 v49, -v43, v48, v47
	v_fmac_f32_e32 v48, v49, v46
	v_fma_f32 v43, -v43, v48, v47
	v_div_fmas_f32 v43, v43, v46, v48
	v_div_fixup_f32 v40, v43, v42, v40
	v_mul_f32_e32 v40, v41, v40
	v_cvt_pk_bf16_f32 v39, v39, v40
	v_lshlrev_b32_e32 v40, 16, v44
	v_mul_f32_e32 v41, 0xbfb8aa3b, v40
	v_exp_f32_e32 v41, v41
	s_nop 0
	v_add_f32_e32 v41, 1.0, v41
	v_div_scale_f32 v42, s[12:13], v41, v41, v40
	v_rcp_f32_e32 v43, v42
	s_nop 0
	v_fma_f32 v46, -v42, v43, 1.0
	v_fmac_f32_e32 v43, v46, v43
	v_div_scale_f32 v46, vcc, v40, v41, v40
	v_mul_f32_e32 v47, v46, v43
	v_fma_f32 v48, -v42, v47, v46
	v_fmac_f32_e32 v47, v48, v43
	v_fma_f32 v42, -v42, v47, v46
	v_div_fmas_f32 v42, v42, v43, v47
	v_div_fixup_f32 v40, v42, v41, v40
	v_mul_f32_e32 v34, v34, v40
	v_and_b32_e32 v40, 0xffff0000, v44
	v_mul_f32_e32 v41, 0xbfb8aa3b, v40
	v_exp_f32_e32 v41, v41
	s_nop 0
	v_add_f32_e32 v41, 1.0, v41
	v_div_scale_f32 v42, s[12:13], v41, v41, v40
	v_rcp_f32_e32 v43, v42
	s_nop 0
	v_fma_f32 v44, -v42, v43, 1.0
	v_fmac_f32_e32 v43, v44, v43
	v_div_scale_f32 v44, vcc, v40, v41, v40
	v_mul_f32_e32 v46, v44, v43
	v_fma_f32 v47, -v42, v46, v44
	v_fmac_f32_e32 v46, v47, v43
	v_fma_f32 v42, -v42, v46, v44
	v_div_fmas_f32 v42, v42, v43, v46
	v_div_fixup_f32 v40, v42, v41, v40
	v_mul_f32_e32 v35, v35, v40
	v_cvt_pk_bf16_f32 v40, v34, v35
	v_lshlrev_b32_e32 v34, 16, v45
	v_mul_f32_e32 v35, 0xbfb8aa3b, v34
	v_exp_f32_e32 v35, v35
	s_nop 0
	v_add_f32_e32 v35, 1.0, v35
	v_div_scale_f32 v41, s[12:13], v35, v35, v34
	v_rcp_f32_e32 v42, v41
	s_nop 0
	v_fma_f32 v43, -v41, v42, 1.0
	v_fmac_f32_e32 v42, v43, v42
	v_div_scale_f32 v43, vcc, v34, v35, v34
	v_mul_f32_e32 v44, v43, v42
	v_fma_f32 v46, -v41, v44, v43
	v_fmac_f32_e32 v44, v46, v42
	v_fma_f32 v41, -v41, v44, v43
	v_div_fmas_f32 v41, v41, v42, v44
	v_div_fixup_f32 v34, v41, v35, v34
	v_and_b32_e32 v35, 0xffff0000, v45
	v_mul_f32_e32 v34, v36, v34
	v_mul_f32_e32 v36, 0xbfb8aa3b, v35
	v_exp_f32_e32 v36, v36
	s_nop 0
	v_add_f32_e32 v36, 1.0, v36
	v_div_scale_f32 v41, s[12:13], v36, v36, v35
	v_rcp_f32_e32 v42, v41
	s_nop 0
	v_fma_f32 v43, -v41, v42, 1.0
	v_fmac_f32_e32 v42, v43, v42
	v_div_scale_f32 v43, vcc, v35, v36, v35
	v_mul_f32_e32 v44, v43, v42
	v_fma_f32 v45, -v41, v44, v43
	v_fmac_f32_e32 v44, v45, v42
	v_fma_f32 v41, -v41, v44, v43
	v_div_fmas_f32 v41, v41, v42, v44
	v_div_fixup_f32 v35, v41, v36, v35
	v_mul_f32_e32 v35, v37, v35
	v_cvt_pk_bf16_f32 v41, v34, v35
	v_add_u32_e32 v34, 0xa0, v160
	v_ashrrev_i32_e32 v35, 31, v34
	global_store_dwordx4 v[50:51], v[38:41], off offset:256
	s_nop 1
	v_lshlrev_b64 v[38:39], 12, v[34:35]
	v_mad_i64_i32 v[34:35], s[12:13], v34, s75, v[162:163]
	v_lshl_add_u64 v[34:35], v[34:35], 0, v[144:145]
	v_lshl_add_u64 v[40:41], v[34:35], 0, s[26:27]
	v_add_co_u32_e32 v34, vcc, s5, v34
	s_nop 1
	v_addc_co_u32_e32 v35, vcc, 0, v35, vcc
	global_load_dwordx4 v[34:37], v[34:35], off
	s_waitcnt vmcnt(0)
; __device__ __forceinline__ unsigned cvt_pk_bf16(float lo, float hi) { unsigned r; asm volatile("v_cvt_pk_bf16_f32 %0, %1, %2" : "=v"(r) : "v"(lo), "v"(hi)); return r; }
; __device__ __forceinline__ float bflo(unsigned u) { return __uint_as_float(u << 16); }
; __device__ __forceinline__ float bfhi(unsigned u) { return __uint_as_float(u & 0xffff0000u); }
; __device__ __forceinline__ float silu_f(float v) { return v / (1.f + __expf(-v)); }
;     __device__ __forceinline__ void operator()(const pg8::f32x4 (&acc)[2][2][4][2], const pg8::Unit& u, int wr, int wc, int fr, int fq) const {
;     ...
;             for (int m = 0; m < 4; ++m) { const size_t row = (size_t)(row0 + ai * 128 + m * 16);
; #pragma unroll
;                 for (int bj = 0; bj < 2; ++bj) { const pg8::f32x4 v0 = acc[ai][bj][m][0], v1 = acc[ai][bj][m][1];
;                     const u32x4 gz = *(const u32x4*)(Z + row * DIN + goff + col0 + bj * 128); u32x4 w;
;                     w.x = pg8::cvt_pk_bf16(v0[0] * silu_f(bflo(gz.x)), v0[1] * silu_f(bfhi(gz.x))); w.y = pg8::cvt_pk_bf16(v0[2] * silu_f(bflo(gz.y)), v0[3] * silu_f(bfhi(gz.y)));
;                     w.z = pg8::cvt_pk_bf16(v1[0] * silu_f(bflo(gz.z)), v1[1] * silu_f(bfhi(gz.z))); w.w = pg8::cvt_pk_bf16(v1[2] * silu_f(bflo(gz.w)), v1[3] * silu_f(bfhi(gz.w)));
;                     *(u32x4*)(O + row * DM + coff + col0 + bj * 128) = w; } }
	v_lshlrev_b32_e32 v42, 16, v34
	v_mul_f32_e32 v43, 0xbfb8aa3b, v42
	v_exp_f32_e32 v43, v43
	v_and_b32_e32 v34, 0xffff0000, v34
	v_add_f32_e32 v43, 1.0, v43
	v_div_scale_f32 v44, s[12:13], v43, v43, v42
	v_rcp_f32_e32 v45, v44
	s_nop 0
	v_fma_f32 v46, -v44, v45, 1.0
	v_fmac_f32_e32 v45, v46, v45
	v_div_scale_f32 v46, vcc, v42, v43, v42
	v_mul_f32_e32 v47, v46, v45
	v_fma_f32 v48, -v44, v47, v46
	v_fmac_f32_e32 v47, v48, v45
	v_fma_f32 v44, -v44, v47, v46
	v_div_fmas_f32 v44, v44, v45, v47
	v_div_fixup_f32 v42, v44, v43, v42
	v_mul_f32_e32 v30, v30, v42
	v_mul_f32_e32 v42, 0xbfb8aa3b, v34
	v_exp_f32_e32 v42, v42
	s_nop 0
	v_add_f32_e32 v42, 1.0, v42
	v_div_scale_f32 v43, s[12:13], v42, v42, v34
	v_rcp_f32_e32 v44, v43
	s_nop 0
	v_fma_f32 v45, -v43, v44, 1.0
	v_fmac_f32_e32 v44, v45, v44
	v_div_scale_f32 v45, vcc, v34, v42, v34
	v_mul_f32_e32 v46, v45, v44
	v_fma_f32 v47, -v43, v46, v45
	v_fmac_f32_e32 v46, v47, v44
	v_fma_f32 v43, -v43, v46, v45
	v_div_fmas_f32 v43, v43, v44, v46
	v_div_fixup_f32 v34, v43, v42, v34
	v_mul_f32_e32 v31, v31, v34
	v_cvt_pk_bf16_f32 v30, v30, v31
	v_lshlrev_b32_e32 v31, 16, v35
	v_mul_f32_e32 v34, 0xbfb8aa3b, v31
	v_exp_f32_e32 v34, v34
	s_nop 0
	v_add_f32_e32 v34, 1.0, v34
	v_div_scale_f32 v42, s[12:13], v34, v34, v31
	v_rcp_f32_e32 v43, v42
	s_nop 0
	v_fma_f32 v44, -v42, v43, 1.0
	v_fmac_f32_e32 v43, v44, v43
	v_div_scale_f32 v44, vcc, v31, v34, v31
	v_mul_f32_e32 v45, v44, v43
	v_fma_f32 v46, -v42, v45, v44
	v_fmac_f32_e32 v45, v46, v43
	v_fma_f32 v42, -v42, v45, v44
	v_div_fmas_f32 v42, v42, v43, v45
	v_div_fixup_f32 v31, v42, v34, v31
	v_mul_f32_e32 v31, v32, v31
	v_and_b32_e32 v32, 0xffff0000, v35
	v_mul_f32_e32 v34, 0xbfb8aa3b, v32
	v_exp_f32_e32 v34, v34
	s_nop 0
	v_add_f32_e32 v34, 1.0, v34
	v_div_scale_f32 v35, s[12:13], v34, v34, v32
	v_rcp_f32_e32 v42, v35
	s_nop 0
	v_fma_f32 v43, -v35, v42, 1.0
	v_fmac_f32_e32 v42, v43, v42
	v_div_scale_f32 v43, vcc, v32, v34, v32
	v_mul_f32_e32 v44, v43, v42
	v_fma_f32 v45, -v35, v44, v43
	v_fmac_f32_e32 v44, v45, v42
	v_fma_f32 v35, -v35, v44, v43
	v_div_fmas_f32 v35, v35, v42, v44
	v_div_fixup_f32 v32, v35, v34, v32
	v_mul_f32_e32 v32, v33, v32
	v_cvt_pk_bf16_f32 v31, v31, v32
	v_lshlrev_b32_e32 v32, 16, v36
	v_mul_f32_e32 v33, 0xbfb8aa3b, v32
	v_exp_f32_e32 v33, v33
	s_nop 0
	v_add_f32_e32 v33, 1.0, v33
	v_div_scale_f32 v34, s[12:13], v33, v33, v32
	v_rcp_f32_e32 v35, v34
	s_nop 0
	v_fma_f32 v42, -v34, v35, 1.0
	v_fmac_f32_e32 v35, v42, v35
	v_div_scale_f32 v42, vcc, v32, v33, v32
	v_mul_f32_e32 v43, v42, v35
	v_fma_f32 v44, -v34, v43, v42
	v_fmac_f32_e32 v43, v44, v35
	v_fma_f32 v34, -v34, v43, v42
	v_div_fmas_f32 v34, v34, v35, v43
	v_div_fixup_f32 v32, v34, v33, v32
	v_mul_f32_e32 v26, v26, v32
	v_and_b32_e32 v32, 0xffff0000, v36
	v_mul_f32_e32 v33, 0xbfb8aa3b, v32
	v_exp_f32_e32 v33, v33
	s_nop 0
	v_add_f32_e32 v33, 1.0, v33
	v_div_scale_f32 v34, s[12:13], v33, v33, v32
	v_rcp_f32_e32 v35, v34
	s_nop 0
	v_fma_f32 v36, -v34, v35, 1.0
	v_fmac_f32_e32 v35, v36, v35
	v_div_scale_f32 v36, vcc, v32, v33, v32
	v_mul_f32_e32 v42, v36, v35
	v_fma_f32 v43, -v34, v42, v36
	v_fmac_f32_e32 v42, v43, v35
	v_fma_f32 v34, -v34, v42, v36
	v_div_fmas_f32 v34, v34, v35, v42
	v_div_fixup_f32 v32, v34, v33, v32
	v_mul_f32_e32 v27, v27, v32
	v_cvt_pk_bf16_f32 v32, v26, v27
	v_lshlrev_b32_e32 v26, 16, v37
	v_mul_f32_e32 v27, 0xbfb8aa3b, v26
	v_exp_f32_e32 v27, v27
	s_nop 0
	v_add_f32_e32 v27, 1.0, v27
	v_div_scale_f32 v33, s[12:13], v27, v27, v26
	v_rcp_f32_e32 v34, v33
	s_nop 0
	v_fma_f32 v35, -v33, v34, 1.0
	v_fmac_f32_e32 v34, v35, v34
	v_div_scale_f32 v35, vcc, v26, v27, v26
	v_mul_f32_e32 v36, v35, v34
	v_fma_f32 v42, -v33, v36, v35
	v_fmac_f32_e32 v36, v42, v34
	v_fma_f32 v33, -v33, v36, v35
	v_div_fmas_f32 v33, v33, v34, v36
	v_div_fixup_f32 v26, v33, v27, v26
	v_and_b32_e32 v27, 0xffff0000, v37
	v_mul_f32_e32 v26, v28, v26
	v_mul_f32_e32 v28, 0xbfb8aa3b, v27
	v_exp_f32_e32 v28, v28
	s_nop 0
	v_add_f32_e32 v28, 1.0, v28
	v_div_scale_f32 v33, s[12:13], v28, v28, v27
	v_rcp_f32_e32 v34, v33
	s_nop 0
	v_fma_f32 v35, -v33, v34, 1.0
	v_fmac_f32_e32 v34, v35, v34
	v_div_scale_f32 v35, vcc, v27, v28, v27
	v_mul_f32_e32 v36, v35, v34
	v_fma_f32 v37, -v33, v36, v35
	v_fmac_f32_e32 v36, v37, v34
	v_fma_f32 v33, -v33, v36, v35
	v_div_fmas_f32 v33, v33, v34, v36
	v_div_fixup_f32 v27, v33, v28, v27
	v_mul_f32_e32 v27, v29, v27
	v_cvt_pk_bf16_f32 v33, v26, v27
	v_lshl_add_u64 v[26:27], s[72:73], 0, v[38:39]
	v_lshl_add_u64 v[34:35], v[26:27], 0, v[144:145]
	global_store_dwordx4 v[34:35], v[30:33], off
	global_load_dwordx4 v[26:29], v[40:41], off offset:256
	s_waitcnt vmcnt(0)
; __device__ __forceinline__ unsigned cvt_pk_bf16(float lo, float hi) { unsigned r; asm volatile("v_cvt_pk_bf16_f32 %0, %1, %2" : "=v"(r) : "v"(lo), "v"(hi)); return r; }
; __device__ __forceinline__ float bflo(unsigned u) { return __uint_as_float(u << 16); }
; __device__ __forceinline__ float bfhi(unsigned u) { return __uint_as_float(u & 0xffff0000u); }
; __device__ __forceinline__ float silu_f(float v) { return v / (1.f + __expf(-v)); }
;     __device__ __forceinline__ void operator()(const pg8::f32x4 (&acc)[2][2][4][2], const pg8::Unit& u, int wr, int wc, int fr, int fq) const {
;     ...
;             for (int m = 0; m < 4; ++m) { const size_t row = (size_t)(row0 + ai * 128 + m * 16);
; #pragma unroll
;                 for (int bj = 0; bj < 2; ++bj) { const pg8::f32x4 v0 = acc[ai][bj][m][0], v1 = acc[ai][bj][m][1];
;                     const u32x4 gz = *(const u32x4*)(Z + row * DIN + goff + col0 + bj * 128); u32x4 w;
;                     w.x = pg8::cvt_pk_bf16(v0[0] * silu_f(bflo(gz.x)), v0[1] * silu_f(bfhi(gz.x))); w.y = pg8::cvt_pk_bf16(v0[2] * silu_f(bflo(gz.y)), v0[3] * silu_f(bfhi(gz.y)));
;                     w.z = pg8::cvt_pk_bf16(v1[0] * silu_f(bflo(gz.z)), v1[1] * silu_f(bfhi(gz.z))); w.w = pg8::cvt_pk_bf16(v1[2] * silu_f(bflo(gz.w)), v1[3] * silu_f(bfhi(gz.w)));
;                     *(u32x4*)(O + row * DM + coff + col0 + bj * 128) = w; } }
	v_lshlrev_b32_e32 v30, 16, v26
	v_mul_f32_e32 v31, 0xbfb8aa3b, v30
	v_exp_f32_e32 v31, v31
	v_and_b32_e32 v26, 0xffff0000, v26
	v_add_f32_e32 v31, 1.0, v31
	v_div_scale_f32 v32, s[12:13], v31, v31, v30
	v_rcp_f32_e32 v33, v32
	s_nop 0
	v_fma_f32 v36, -v32, v33, 1.0
	v_fmac_f32_e32 v33, v36, v33
	v_div_scale_f32 v36, vcc, v30, v31, v30
	v_mul_f32_e32 v37, v36, v33
	v_fma_f32 v38, -v32, v37, v36
	v_fmac_f32_e32 v37, v38, v33
	v_fma_f32 v32, -v32, v37, v36
	v_div_fmas_f32 v32, v32, v33, v37
	v_div_fixup_f32 v30, v32, v31, v30
	v_mul_f32_e32 v22, v22, v30
	v_mul_f32_e32 v30, 0xbfb8aa3b, v26
	v_exp_f32_e32 v30, v30
	s_nop 0
	v_add_f32_e32 v30, 1.0, v30
	v_div_scale_f32 v31, s[12:13], v30, v30, v26
	v_rcp_f32_e32 v32, v31
	s_nop 0
	v_fma_f32 v33, -v31, v32, 1.0
	v_fmac_f32_e32 v32, v33, v32
	v_div_scale_f32 v33, vcc, v26, v30, v26
	v_mul_f32_e32 v36, v33, v32
	v_fma_f32 v37, -v31, v36, v33
	v_fmac_f32_e32 v36, v37, v32
	v_fma_f32 v31, -v31, v36, v33
	v_div_fmas_f32 v31, v31, v32, v36
	v_div_fixup_f32 v26, v31, v30, v26
	v_mul_f32_e32 v23, v23, v26
	v_cvt_pk_bf16_f32 v22, v22, v23
	v_lshlrev_b32_e32 v23, 16, v27
	v_mul_f32_e32 v26, 0xbfb8aa3b, v23
	v_exp_f32_e32 v26, v26
	s_nop 0
	v_add_f32_e32 v26, 1.0, v26
	v_div_scale_f32 v30, s[12:13], v26, v26, v23
	v_rcp_f32_e32 v31, v30
	s_nop 0
	v_fma_f32 v32, -v30, v31, 1.0
	v_fmac_f32_e32 v31, v32, v31
	v_div_scale_f32 v32, vcc, v23, v26, v23
	v_mul_f32_e32 v33, v32, v31
	v_fma_f32 v36, -v30, v33, v32
	v_fmac_f32_e32 v33, v36, v31
	v_fma_f32 v30, -v30, v33, v32
	v_div_fmas_f32 v30, v30, v31, v33
	v_div_fixup_f32 v23, v30, v26, v23
	v_mul_f32_e32 v23, v24, v23
	v_and_b32_e32 v24, 0xffff0000, v27
	v_mul_f32_e32 v26, 0xbfb8aa3b, v24
	v_exp_f32_e32 v26, v26
	s_nop 0
	v_add_f32_e32 v26, 1.0, v26
	v_div_scale_f32 v27, s[12:13], v26, v26, v24
	v_rcp_f32_e32 v30, v27
	s_nop 0
	v_fma_f32 v31, -v27, v30, 1.0
	v_fmac_f32_e32 v30, v31, v30
	v_div_scale_f32 v31, vcc, v24, v26, v24
	v_mul_f32_e32 v32, v31, v30
	v_fma_f32 v33, -v27, v32, v31
	v_fmac_f32_e32 v32, v33, v30
	v_fma_f32 v27, -v27, v32, v31
	v_div_fmas_f32 v27, v27, v30, v32
	v_div_fixup_f32 v24, v27, v26, v24
	v_mul_f32_e32 v24, v25, v24
	v_cvt_pk_bf16_f32 v23, v23, v24
	v_lshlrev_b32_e32 v24, 16, v28
	v_mul_f32_e32 v25, 0xbfb8aa3b, v24
	v_exp_f32_e32 v25, v25
	s_nop 0
	v_add_f32_e32 v25, 1.0, v25
	v_div_scale_f32 v26, s[12:13], v25, v25, v24
	v_rcp_f32_e32 v27, v26
	s_nop 0
	v_fma_f32 v30, -v26, v27, 1.0
	v_fmac_f32_e32 v27, v30, v27
	v_div_scale_f32 v30, vcc, v24, v25, v24
	v_mul_f32_e32 v31, v30, v27
	v_fma_f32 v32, -v26, v31, v30
	v_fmac_f32_e32 v31, v32, v27
	v_fma_f32 v26, -v26, v31, v30
	v_div_fmas_f32 v26, v26, v27, v31
	v_div_fixup_f32 v24, v26, v25, v24
	v_mul_f32_e32 v18, v18, v24
	v_and_b32_e32 v24, 0xffff0000, v28
	v_mul_f32_e32 v25, 0xbfb8aa3b, v24
	v_exp_f32_e32 v25, v25
	s_nop 0
	v_add_f32_e32 v25, 1.0, v25
	v_div_scale_f32 v26, s[12:13], v25, v25, v24
	v_rcp_f32_e32 v27, v26
	s_nop 0
	v_fma_f32 v28, -v26, v27, 1.0
	v_fmac_f32_e32 v27, v28, v27
	v_div_scale_f32 v28, vcc, v24, v25, v24
	v_mul_f32_e32 v30, v28, v27
	v_fma_f32 v31, -v26, v30, v28
	v_fmac_f32_e32 v30, v31, v27
	v_fma_f32 v26, -v26, v30, v28
	v_div_fmas_f32 v26, v26, v27, v30
	v_div_fixup_f32 v24, v26, v25, v24
	v_mul_f32_e32 v19, v19, v24
	v_cvt_pk_bf16_f32 v24, v18, v19
	v_lshlrev_b32_e32 v18, 16, v29
	v_mul_f32_e32 v19, 0xbfb8aa3b, v18
	v_exp_f32_e32 v19, v19
	s_nop 0
	v_add_f32_e32 v19, 1.0, v19
	v_div_scale_f32 v25, s[12:13], v19, v19, v18
	v_rcp_f32_e32 v26, v25
	s_nop 0
	v_fma_f32 v27, -v25, v26, 1.0
	v_fmac_f32_e32 v26, v27, v26
	v_div_scale_f32 v27, vcc, v18, v19, v18
	v_mul_f32_e32 v28, v27, v26
	v_fma_f32 v30, -v25, v28, v27
	v_fmac_f32_e32 v28, v30, v26
	v_fma_f32 v25, -v25, v28, v27
	v_div_fmas_f32 v25, v25, v26, v28
	v_div_fixup_f32 v18, v25, v19, v18
	v_and_b32_e32 v19, 0xffff0000, v29
	v_mul_f32_e32 v18, v20, v18
	v_mul_f32_e32 v20, 0xbfb8aa3b, v19
	v_exp_f32_e32 v20, v20
	s_nop 0
	v_add_f32_e32 v20, 1.0, v20
	v_div_scale_f32 v25, s[12:13], v20, v20, v19
	v_rcp_f32_e32 v26, v25
	s_nop 0
	v_fma_f32 v27, -v25, v26, 1.0
	v_fmac_f32_e32 v26, v27, v26
	v_div_scale_f32 v27, vcc, v19, v20, v19
	v_mul_f32_e32 v28, v27, v26
	v_fma_f32 v29, -v25, v28, v27
	v_fmac_f32_e32 v28, v29, v26
	v_fma_f32 v25, -v25, v28, v27
	v_div_fmas_f32 v25, v25, v26, v28
	v_div_fixup_f32 v19, v25, v20, v19
	v_mul_f32_e32 v19, v21, v19
	v_cvt_pk_bf16_f32 v25, v18, v19
	v_add_u32_e32 v18, 0xb0, v160
	v_ashrrev_i32_e32 v19, 31, v18
	global_store_dwordx4 v[34:35], v[22:25], off offset:256
	s_nop 1
	v_lshlrev_b64 v[22:23], 12, v[18:19]
	v_mad_i64_i32 v[18:19], s[12:13], v18, s75, v[162:163]
	v_lshl_add_u64 v[18:19], v[18:19], 0, v[144:145]
	v_lshl_add_u64 v[24:25], v[18:19], 0, s[26:27]
	v_add_co_u32_e32 v18, vcc, s5, v18
	s_nop 1
	v_addc_co_u32_e32 v19, vcc, 0, v19, vcc
	global_load_dwordx4 v[18:21], v[18:19], off
	s_waitcnt vmcnt(0)
; __device__ __forceinline__ unsigned cvt_pk_bf16(float lo, float hi) { unsigned r; asm volatile("v_cvt_pk_bf16_f32 %0, %1, %2" : "=v"(r) : "v"(lo), "v"(hi)); return r; }
; __device__ __forceinline__ float bflo(unsigned u) { return __uint_as_float(u << 16); }
; __device__ __forceinline__ float bfhi(unsigned u) { return __uint_as_float(u & 0xffff0000u); }
; __device__ __forceinline__ float silu_f(float v) { return v / (1.f + __expf(-v)); }
;     __device__ __forceinline__ void operator()(const pg8::f32x4 (&acc)[2][2][4][2], const pg8::Unit& u, int wr, int wc, int fr, int fq) const {
;     ...
;             for (int m = 0; m < 4; ++m) { const size_t row = (size_t)(row0 + ai * 128 + m * 16);
; #pragma unroll
;                 for (int bj = 0; bj < 2; ++bj) { const pg8::f32x4 v0 = acc[ai][bj][m][0], v1 = acc[ai][bj][m][1];
;                     const u32x4 gz = *(const u32x4*)(Z + row * DIN + goff + col0 + bj * 128); u32x4 w;
;                     w.x = pg8::cvt_pk_bf16(v0[0] * silu_f(bflo(gz.x)), v0[1] * silu_f(bfhi(gz.x))); w.y = pg8::cvt_pk_bf16(v0[2] * silu_f(bflo(gz.y)), v0[3] * silu_f(bfhi(gz.y)));
;                     w.z = pg8::cvt_pk_bf16(v1[0] * silu_f(bflo(gz.z)), v1[1] * silu_f(bfhi(gz.z))); w.w = pg8::cvt_pk_bf16(v1[2] * silu_f(bflo(gz.w)), v1[3] * silu_f(bfhi(gz.w)));
;                     *(u32x4*)(O + row * DM + coff + col0 + bj * 128) = w; } }
	v_lshlrev_b32_e32 v26, 16, v18
	v_mul_f32_e32 v27, 0xbfb8aa3b, v26
	v_exp_f32_e32 v27, v27
	v_and_b32_e32 v18, 0xffff0000, v18
	v_add_f32_e32 v27, 1.0, v27
	v_div_scale_f32 v28, s[12:13], v27, v27, v26
	v_rcp_f32_e32 v29, v28
	s_nop 0
	v_fma_f32 v30, -v28, v29, 1.0
	v_fmac_f32_e32 v29, v30, v29
	v_div_scale_f32 v30, vcc, v26, v27, v26
	v_mul_f32_e32 v31, v30, v29
	v_fma_f32 v32, -v28, v31, v30
	v_fmac_f32_e32 v31, v32, v29
	v_fma_f32 v28, -v28, v31, v30
	v_div_fmas_f32 v28, v28, v29, v31
	v_div_fixup_f32 v26, v28, v27, v26
	v_mul_f32_e32 v14, v14, v26
	v_mul_f32_e32 v26, 0xbfb8aa3b, v18
	v_exp_f32_e32 v26, v26
	s_nop 0
	v_add_f32_e32 v26, 1.0, v26
	v_div_scale_f32 v27, s[12:13], v26, v26, v18
	v_rcp_f32_e32 v28, v27
	s_nop 0
	v_fma_f32 v29, -v27, v28, 1.0
	v_fmac_f32_e32 v28, v29, v28
	v_div_scale_f32 v29, vcc, v18, v26, v18
	v_mul_f32_e32 v30, v29, v28
	v_fma_f32 v31, -v27, v30, v29
	v_fmac_f32_e32 v30, v31, v28
	v_fma_f32 v27, -v27, v30, v29
	v_div_fmas_f32 v27, v27, v28, v30
	v_div_fixup_f32 v18, v27, v26, v18
	v_mul_f32_e32 v15, v15, v18
	v_cvt_pk_bf16_f32 v14, v14, v15
	v_lshlrev_b32_e32 v15, 16, v19
	v_mul_f32_e32 v18, 0xbfb8aa3b, v15
	v_exp_f32_e32 v18, v18
	s_nop 0
	v_add_f32_e32 v18, 1.0, v18
	v_div_scale_f32 v26, s[12:13], v18, v18, v15
	v_rcp_f32_e32 v27, v26
	s_nop 0
	v_fma_f32 v28, -v26, v27, 1.0
	v_fmac_f32_e32 v27, v28, v27
	v_div_scale_f32 v28, vcc, v15, v18, v15
	v_mul_f32_e32 v29, v28, v27
	v_fma_f32 v30, -v26, v29, v28
	v_fmac_f32_e32 v29, v30, v27
	v_fma_f32 v26, -v26, v29, v28
	v_div_fmas_f32 v26, v26, v27, v29
	v_div_fixup_f32 v15, v26, v18, v15
	v_mul_f32_e32 v15, v16, v15
	v_and_b32_e32 v16, 0xffff0000, v19
	v_mul_f32_e32 v18, 0xbfb8aa3b, v16
	v_exp_f32_e32 v18, v18
	s_nop 0
	v_add_f32_e32 v18, 1.0, v18
	v_div_scale_f32 v19, s[12:13], v18, v18, v16
	v_rcp_f32_e32 v26, v19
	s_nop 0
	v_fma_f32 v27, -v19, v26, 1.0
	v_fmac_f32_e32 v26, v27, v26
	v_div_scale_f32 v27, vcc, v16, v18, v16
	v_mul_f32_e32 v28, v27, v26
	v_fma_f32 v29, -v19, v28, v27
	v_fmac_f32_e32 v28, v29, v26
	v_fma_f32 v19, -v19, v28, v27
	v_div_fmas_f32 v19, v19, v26, v28
	v_div_fixup_f32 v16, v19, v18, v16
	v_mul_f32_e32 v16, v17, v16
	v_cvt_pk_bf16_f32 v15, v15, v16
	v_lshlrev_b32_e32 v16, 16, v20
	v_mul_f32_e32 v17, 0xbfb8aa3b, v16
	v_exp_f32_e32 v17, v17
	s_nop 0
	v_add_f32_e32 v17, 1.0, v17
	v_div_scale_f32 v18, s[12:13], v17, v17, v16
	v_rcp_f32_e32 v19, v18
	s_nop 0
	v_fma_f32 v26, -v18, v19, 1.0
	v_fmac_f32_e32 v19, v26, v19
	v_div_scale_f32 v26, vcc, v16, v17, v16
	v_mul_f32_e32 v27, v26, v19
	v_fma_f32 v28, -v18, v27, v26
	v_fmac_f32_e32 v27, v28, v19
	v_fma_f32 v18, -v18, v27, v26
	v_div_fmas_f32 v18, v18, v19, v27
	v_div_fixup_f32 v16, v18, v17, v16
	v_mul_f32_e32 v10, v10, v16
	v_and_b32_e32 v16, 0xffff0000, v20
	v_mul_f32_e32 v17, 0xbfb8aa3b, v16
	v_exp_f32_e32 v17, v17
	s_nop 0
	v_add_f32_e32 v17, 1.0, v17
	v_div_scale_f32 v18, s[12:13], v17, v17, v16
	v_rcp_f32_e32 v19, v18
	s_nop 0
	v_fma_f32 v20, -v18, v19, 1.0
	v_fmac_f32_e32 v19, v20, v19
	v_div_scale_f32 v20, vcc, v16, v17, v16
	v_mul_f32_e32 v26, v20, v19
	v_fma_f32 v27, -v18, v26, v20
	v_fmac_f32_e32 v26, v27, v19
	v_fma_f32 v18, -v18, v26, v20
	v_div_fmas_f32 v18, v18, v19, v26
	v_div_fixup_f32 v16, v18, v17, v16
	v_mul_f32_e32 v11, v11, v16
	v_cvt_pk_bf16_f32 v16, v10, v11
	v_lshlrev_b32_e32 v10, 16, v21
	v_mul_f32_e32 v11, 0xbfb8aa3b, v10
	v_exp_f32_e32 v11, v11
	s_nop 0
	v_add_f32_e32 v11, 1.0, v11
	v_div_scale_f32 v17, s[12:13], v11, v11, v10
	v_rcp_f32_e32 v18, v17
	s_nop 0
	v_fma_f32 v19, -v17, v18, 1.0
	v_fmac_f32_e32 v18, v19, v18
	v_div_scale_f32 v19, vcc, v10, v11, v10
	v_mul_f32_e32 v20, v19, v18
	v_fma_f32 v26, -v17, v20, v19
	v_fmac_f32_e32 v20, v26, v18
	v_fma_f32 v17, -v17, v20, v19
	v_div_fmas_f32 v17, v17, v18, v20
	v_div_fixup_f32 v10, v17, v11, v10
	v_and_b32_e32 v11, 0xffff0000, v21
	v_mul_f32_e32 v10, v12, v10
	v_mul_f32_e32 v12, 0xbfb8aa3b, v11
	v_exp_f32_e32 v12, v12
	s_nop 0
	v_add_f32_e32 v12, 1.0, v12
	v_div_scale_f32 v17, s[12:13], v12, v12, v11
	v_rcp_f32_e32 v18, v17
	s_nop 0
	v_fma_f32 v19, -v17, v18, 1.0
	v_fmac_f32_e32 v18, v19, v18
	v_div_scale_f32 v19, vcc, v11, v12, v11
	v_mul_f32_e32 v20, v19, v18
	v_fma_f32 v21, -v17, v20, v19
	v_fmac_f32_e32 v20, v21, v18
	v_fma_f32 v17, -v17, v20, v19
	v_div_fmas_f32 v17, v17, v18, v20
	v_div_fixup_f32 v11, v17, v12, v11
	v_mul_f32_e32 v11, v13, v11
	v_cvt_pk_bf16_f32 v17, v10, v11
	v_lshl_add_u64 v[10:11], s[72:73], 0, v[22:23]
	v_lshl_add_u64 v[18:19], v[10:11], 0, v[144:145]
	global_store_dwordx4 v[18:19], v[14:17], off
	global_load_dwordx4 v[10:13], v[24:25], off offset:256
	s_waitcnt vmcnt(0)
; __device__ __forceinline__ unsigned cvt_pk_bf16(float lo, float hi) { unsigned r; asm volatile("v_cvt_pk_bf16_f32 %0, %1, %2" : "=v"(r) : "v"(lo), "v"(hi)); return r; }
; #define PG8_BAR __builtin_amdgcn_s_barrier()
; __device__ __forceinline__ float bflo(unsigned u) { return __uint_as_float(u << 16); }
; __device__ __forceinline__ float bfhi(unsigned u) { return __uint_as_float(u & 0xffff0000u); }
; __device__ __forceinline__ float silu_f(float v) { return v / (1.f + __expf(-v)); }
; template <class Epi, class Sched, bool ALIGN_EPI>
; __device__ __forceinline__ void gemm_phase(PG8_LAS unsigned char* lds, const Gemm g, const Sched& S, const Epi& E) {
;     ...
;         if constexpr (ALIGN_EPI) { if (wr == 0) PG8_BAR; }
;         E(acc, cur, wr, wc, fr, fq);
;         if (!has_next) break;
; #pragma unroll
;         for (int a = 0; a < 2; ++a)
; #pragma unroll
;             for (int b = 0; b < 2; ++b)
; #pragma unroll
;                 for (int m = 0; m < 4; ++m)
; #pragma unroll
;                     for (int n = 0; n < 2; ++n) acc[a][b][m][n] = (f32x4){0.f, 0.f, 0.f, 0.f};
;         cur = nxt; cA = nA; cB = nB; ++ui;
;         if constexpr (ALIGN_EPI) { if (wr == 1) PG8_BAR; }
;     __device__ __forceinline__ void operator()(const pg8::f32x4 (&acc)[2][2][4][2], const pg8::Unit& u, int wr, int wc, int fr, int fq) const {
;     ...
;             for (int m = 0; m < 4; ++m) { const size_t row = (size_t)(row0 + ai * 128 + m * 16);
; #pragma unroll
;                 for (int bj = 0; bj < 2; ++bj) { const pg8::f32x4 v0 = acc[ai][bj][m][0], v1 = acc[ai][bj][m][1];
;                     const u32x4 gz = *(const u32x4*)(Z + row * DIN + goff + col0 + bj * 128); u32x4 w;
;                     w.x = pg8::cvt_pk_bf16(v0[0] * silu_f(bflo(gz.x)), v0[1] * silu_f(bfhi(gz.x))); w.y = pg8::cvt_pk_bf16(v0[2] * silu_f(bflo(gz.y)), v0[3] * silu_f(bfhi(gz.y)));
;                     w.z = pg8::cvt_pk_bf16(v1[0] * silu_f(bflo(gz.z)), v1[1] * silu_f(bfhi(gz.z))); w.w = pg8::cvt_pk_bf16(v1[2] * silu_f(bflo(gz.w)), v1[3] * silu_f(bfhi(gz.w)));
;                     *(u32x4*)(O + row * DM + coff + col0 + bj * 128) = w; } }
	v_lshlrev_b32_e32 v14, 16, v10
	v_mul_f32_e32 v15, 0xbfb8aa3b, v14
	v_exp_f32_e32 v15, v15
	v_and_b32_e32 v10, 0xffff0000, v10
	v_add_f32_e32 v15, 1.0, v15
	v_div_scale_f32 v16, s[12:13], v15, v15, v14
	v_rcp_f32_e32 v17, v16
	s_nop 0
	v_fma_f32 v20, -v16, v17, 1.0
	v_fmac_f32_e32 v17, v20, v17
	v_div_scale_f32 v20, vcc, v14, v15, v14
	v_mul_f32_e32 v21, v20, v17
	v_fma_f32 v22, -v16, v21, v20
	v_fmac_f32_e32 v21, v22, v17
	v_fma_f32 v16, -v16, v21, v20
	v_div_fmas_f32 v16, v16, v17, v21
	v_div_fixup_f32 v14, v16, v15, v14
	v_mul_f32_e32 v6, v6, v14
	v_mul_f32_e32 v14, 0xbfb8aa3b, v10
	v_exp_f32_e32 v14, v14
	s_nop 0
	v_add_f32_e32 v14, 1.0, v14
	v_div_scale_f32 v15, s[12:13], v14, v14, v10
	v_rcp_f32_e32 v16, v15
	s_nop 0
	v_fma_f32 v17, -v15, v16, 1.0
	v_fmac_f32_e32 v16, v17, v16
	v_div_scale_f32 v17, vcc, v10, v14, v10
	v_mul_f32_e32 v20, v17, v16
	v_fma_f32 v21, -v15, v20, v17
	v_fmac_f32_e32 v20, v21, v16
	v_fma_f32 v15, -v15, v20, v17
	v_div_fmas_f32 v15, v15, v16, v20
	v_div_fixup_f32 v10, v15, v14, v10
	v_mul_f32_e32 v7, v7, v10
	v_cvt_pk_bf16_f32 v6, v6, v7
	v_lshlrev_b32_e32 v7, 16, v11
	v_mul_f32_e32 v10, 0xbfb8aa3b, v7
	v_exp_f32_e32 v10, v10
	s_nop 0
	v_add_f32_e32 v10, 1.0, v10
	v_div_scale_f32 v14, s[12:13], v10, v10, v7
	v_rcp_f32_e32 v15, v14
	s_nop 0
	v_fma_f32 v16, -v14, v15, 1.0
	v_fmac_f32_e32 v15, v16, v15
	v_div_scale_f32 v16, vcc, v7, v10, v7
	v_mul_f32_e32 v17, v16, v15
	v_fma_f32 v20, -v14, v17, v16
	v_fmac_f32_e32 v17, v20, v15
	v_fma_f32 v14, -v14, v17, v16
	v_div_fmas_f32 v14, v14, v15, v17
	v_div_fixup_f32 v7, v14, v10, v7
	v_mul_f32_e32 v7, v8, v7
	v_and_b32_e32 v8, 0xffff0000, v11
	v_mul_f32_e32 v10, 0xbfb8aa3b, v8
	v_exp_f32_e32 v10, v10
	s_nop 0
	v_add_f32_e32 v10, 1.0, v10
	v_div_scale_f32 v11, s[12:13], v10, v10, v8
	v_rcp_f32_e32 v14, v11
	s_nop 0
	v_fma_f32 v15, -v11, v14, 1.0
	v_fmac_f32_e32 v14, v15, v14
	v_div_scale_f32 v15, vcc, v8, v10, v8
	v_mul_f32_e32 v16, v15, v14
	v_fma_f32 v17, -v11, v16, v15
	v_fmac_f32_e32 v16, v17, v14
	v_fma_f32 v11, -v11, v16, v15
	v_div_fmas_f32 v11, v11, v14, v16
	v_div_fixup_f32 v8, v11, v10, v8
	v_mul_f32_e32 v8, v9, v8
	v_cvt_pk_bf16_f32 v7, v7, v8
	v_lshlrev_b32_e32 v8, 16, v12
	v_mul_f32_e32 v9, 0xbfb8aa3b, v8
	v_exp_f32_e32 v9, v9
	s_nop 0
	v_add_f32_e32 v9, 1.0, v9
	v_div_scale_f32 v10, s[12:13], v9, v9, v8
	v_rcp_f32_e32 v11, v10
	s_nop 0
	v_fma_f32 v14, -v10, v11, 1.0
	v_fmac_f32_e32 v11, v14, v11
	v_div_scale_f32 v14, vcc, v8, v9, v8
	v_mul_f32_e32 v15, v14, v11
	v_fma_f32 v16, -v10, v15, v14
	v_fmac_f32_e32 v15, v16, v11
	v_fma_f32 v10, -v10, v15, v14
	v_div_fmas_f32 v10, v10, v11, v15
	v_div_fixup_f32 v8, v10, v9, v8
	v_mul_f32_e32 v2, v2, v8
	v_and_b32_e32 v8, 0xffff0000, v12
	v_mul_f32_e32 v9, 0xbfb8aa3b, v8
	v_exp_f32_e32 v9, v9
	s_nop 0
	v_add_f32_e32 v9, 1.0, v9
	v_div_scale_f32 v10, s[12:13], v9, v9, v8
	v_rcp_f32_e32 v11, v10
	s_nop 0
	v_fma_f32 v12, -v10, v11, 1.0
	v_fmac_f32_e32 v11, v12, v11
	v_div_scale_f32 v12, vcc, v8, v9, v8
	v_mul_f32_e32 v14, v12, v11
	v_fma_f32 v15, -v10, v14, v12
	v_fmac_f32_e32 v14, v15, v11
	v_fma_f32 v10, -v10, v14, v12
	v_div_fmas_f32 v10, v10, v11, v14
	v_div_fixup_f32 v8, v10, v9, v8
	v_mul_f32_e32 v3, v3, v8
	v_cvt_pk_bf16_f32 v8, v2, v3
	v_lshlrev_b32_e32 v2, 16, v13
	v_mul_f32_e32 v3, 0xbfb8aa3b, v2
	v_exp_f32_e32 v3, v3
	s_nop 0
	v_add_f32_e32 v3, 1.0, v3
	v_div_scale_f32 v9, s[12:13], v3, v3, v2
	v_rcp_f32_e32 v10, v9
	s_nop 0
	v_fma_f32 v11, -v9, v10, 1.0
	v_fmac_f32_e32 v10, v11, v10
	v_div_scale_f32 v11, vcc, v2, v3, v2
	v_mul_f32_e32 v12, v11, v10
	v_fma_f32 v14, -v9, v12, v11
	v_fmac_f32_e32 v12, v14, v10
	v_fma_f32 v9, -v9, v12, v11
	v_div_fmas_f32 v9, v9, v10, v12
	v_div_fixup_f32 v2, v9, v3, v2
	v_and_b32_e32 v3, 0xffff0000, v13
	v_mul_f32_e32 v2, v4, v2
	v_mul_f32_e32 v4, 0xbfb8aa3b, v3
	v_exp_f32_e32 v4, v4
	s_nop 0
	v_add_f32_e32 v4, 1.0, v4
	v_div_scale_f32 v9, s[12:13], v4, v4, v3
	v_rcp_f32_e32 v10, v9
	s_nop 0
	v_fma_f32 v11, -v9, v10, 1.0
	v_fmac_f32_e32 v10, v11, v10
	v_div_scale_f32 v11, vcc, v3, v4, v3
	v_mul_f32_e32 v12, v11, v10
	v_fma_f32 v13, -v9, v12, v11
	v_fmac_f32_e32 v12, v13, v10
	v_fma_f32 v9, -v9, v12, v11
	v_div_fmas_f32 v9, v9, v10, v12
	v_div_fixup_f32 v3, v9, v4, v3
	s_andn2_b64 vcc, exec, s[40:41]
	v_mul_f32_e32 v3, v5, v3
	v_cvt_pk_bf16_f32 v9, v2, v3
	global_store_dwordx4 v[18:19], v[6:9], off offset:256
	s_cbranch_vccnz .LBB0_544
	s_andn2_b64 vcc, exec, s[36:37]
	s_cbranch_vccnz .LBB0_543
	s_barrier
	s_branch .LBB0_543

; __device__ __forceinline__ unsigned pk2(float lo, float hi) { return f2bf(lo) | (f2bf(hi) << 16); }
; __device__ __forceinline__ float bflo(unsigned u) { return __uint_as_float(u << 16); }
; __device__ __forceinline__ float bfhi(unsigned u) { return __uint_as_float(u & 0xffff0000u); }
; __device__ __forceinline__ float silu_f(float v) { return v / (1.f + __expf(-v)); }
; __device__ __forceinline__ void ph_combine(const Params& p_) {
;     ...
;         for (int u = 0; u < 2; ++u) if (act[u]) { f32x4 s = ce[u];
;             if (use_so[u]) s = (kv[u] <= 2048) ? s - so[u] : s + so[u];
;             const float alt = (kv[u] & 1) ? -1.f : 1.f;
; #pragma unroll
;             for (int j = 0; j < 4; ++j) s[j] += alt * pv[u][j];
;             u32x2 w; w.x = pk2(s[0] * silu_f(bflo(gz[u].x)), s[1] * silu_f(bfhi(gz[u].x))); w.y = pk2(s[2] * silu_f(bflo(gz[u].y)), s[3] * silu_f(bfhi(gz[u].y)));
;             *(u32x2*)(CAT + (size_t)rowv[u] * DM + c4v[u]) = w; }
.LBB0_662:
	s_or_b64 exec, exec, s[38:39]
	v_lshlrev_b32_e32 v0, 16, v30
	v_lshlrev_b32_e32 v6, 16, v32
	v_lshlrev_b32_e32 v10, 16, v31
	v_lshlrev_b32_e32 v11, 16, v33
	v_lshlrev_b32_e32 v13, 16, v26
	v_cndmask_b32_e64 v7, -v6, v6, s[42:43]
	v_cndmask_b32_e64 v6, -v0, v0, s[42:43]
	v_mov_b32_e32 v8, v2
	v_mov_b32_e32 v9, v4
	v_and_b32_e32 v15, 0xffff0000, v26
	v_pk_add_f32 v[6:7], v[6:7], v[8:9]
	v_cndmask_b32_e64 v9, -v11, v11, s[42:43]
	v_cndmask_b32_e64 v8, -v10, v10, s[42:43]
	v_mov_b32_e32 v4, v3
	v_mul_f32_e32 v0, 0xbfb8aa3b, v13
	v_lshlrev_b32_e32 v12, 16, v27
	v_pk_add_f32 v[2:3], v[8:9], v[4:5]
	v_exp_f32_e32 v4, v0
	v_mul_f32_e32 v0, 0xbfb8aa3b, v15
	v_exp_f32_e32 v8, v0
	v_mul_f32_e32 v0, 0xbfb8aa3b, v12
	v_exp_f32_e32 v5, v0
	v_and_b32_e32 v14, 0xffff0000, v27
	v_ashrrev_i32_e32 v19, 31, v18
	v_pk_add_f32 v[4:5], v[4:5], 1.0 op_sel_hi:[1,0]
	s_nop 0
	v_div_scale_f32 v0, s[12:13], v5, v5, v12
	v_rcp_f32_e32 v9, v0
	s_nop 0
	v_fma_f32 v10, -v0, v9, 1.0
	v_fmac_f32_e32 v9, v10, v9
	v_div_scale_f32 v10, vcc, v12, v5, v12
	v_mul_f32_e32 v11, v10, v9
	v_fma_f32 v16, -v0, v11, v10
	v_fmac_f32_e32 v11, v16, v9
	v_fma_f32 v0, -v0, v11, v10
	v_div_fmas_f32 v0, v0, v9, v11
	v_div_fixup_f32 v5, v0, v5, v12
	v_div_scale_f32 v0, s[12:13], v4, v4, v13
	v_rcp_f32_e32 v9, v0
	s_nop 0
	v_fma_f32 v10, -v0, v9, 1.0
	v_fmac_f32_e32 v9, v10, v9
	v_div_scale_f32 v10, vcc, v13, v4, v13
	v_mul_f32_e32 v11, v10, v9
	v_fma_f32 v12, -v0, v11, v10
	v_fmac_f32_e32 v11, v12, v9
	v_fma_f32 v0, -v0, v11, v10
	v_div_fmas_f32 v0, v0, v9, v11
	v_div_fixup_f32 v4, v0, v4, v13
	v_mul_f32_e32 v0, 0xbfb8aa3b, v14
	v_exp_f32_e32 v9, v0
	v_pk_mul_f32 v[4:5], v[4:5], v[6:7]
	v_pk_add_f32 v[6:7], v[8:9], 1.0 op_sel_hi:[1,0]
	s_nop 0
	v_div_scale_f32 v0, s[12:13], v7, v7, v14
	v_rcp_f32_e32 v8, v0
	s_nop 0
	v_fma_f32 v9, -v0, v8, 1.0
	v_fmac_f32_e32 v8, v9, v8
	v_div_scale_f32 v9, vcc, v14, v7, v14
	v_mul_f32_e32 v10, v9, v8
	v_fma_f32 v11, -v0, v10, v9
	v_fmac_f32_e32 v10, v11, v8
	v_fma_f32 v0, -v0, v10, v9
	v_div_fmas_f32 v0, v0, v8, v10
	v_div_fixup_f32 v7, v0, v7, v14
	v_div_scale_f32 v0, s[12:13], v6, v6, v15
	v_rcp_f32_e32 v8, v0
	s_nop 0
	v_fma_f32 v9, -v0, v8, 1.0
	v_fmac_f32_e32 v8, v9, v8
	v_div_scale_f32 v9, vcc, v15, v6, v15
	v_mul_f32_e32 v10, v9, v8
	v_fma_f32 v11, -v0, v10, v9
	v_fmac_f32_e32 v10, v11, v8
	v_fma_f32 v0, -v0, v10, v9
	v_div_fmas_f32 v0, v0, v8, v10
	v_div_fixup_f32 v6, v0, v6, v15
	v_pk_mul_f32 v[2:3], v[6:7], v[2:3]
	v_and_b32_sdwa v6, v4, v179 dst_sel:DWORD dst_unused:UNUSED_PAD src0_sel:WORD_1 src1_sel:DWORD
	v_and_b32_sdwa v0, v5, v179 dst_sel:DWORD dst_unused:UNUSED_PAD src0_sel:WORD_1 src1_sel:DWORD
	v_add3_u32 v4, v4, v6, s14
	v_and_b32_sdwa v6, v2, v179 dst_sel:DWORD dst_unused:UNUSED_PAD src0_sel:WORD_1 src1_sel:DWORD
	v_add3_u32 v0, v5, v0, s14
	v_and_b32_sdwa v5, v3, v179 dst_sel:DWORD dst_unused:UNUSED_PAD src0_sel:WORD_1 src1_sel:DWORD
	v_add3_u32 v2, v2, v6, s14
	v_add3_u32 v3, v3, v5, s14
	v_and_b32_e32 v2, 0xffff0000, v2
	v_and_b32_e32 v3, 0xffff0000, v3
	v_or_b32_sdwa v2, v2, v4 dst_sel:DWORD dst_unused:UNUSED_PAD src0_sel:DWORD src1_sel:WORD_1
	v_lshlrev_b64 v[4:5], 12, v[18:19]
	v_or_b32_sdwa v3, v3, v0 dst_sel:DWORD dst_unused:UNUSED_PAD src0_sel:DWORD src1_sel:WORD_1
	v_lshl_add_u64 v[4:5], s[56:57], 0, v[4:5]
	v_lshlrev_b32_e32 v0, 1, v20
	v_lshl_add_u64 v[4:5], v[4:5], 0, v[0:1]
	global_store_dwordx2 v[4:5], v[2:3], off offset:3072

; __device__ __forceinline__ unsigned pk2(float lo, float hi) { return f2bf(lo) | (f2bf(hi) << 16); }
; __device__ __forceinline__ float bf2f(bf16 b) { return __uint_as_float((unsigned)b << 16); }
; __device__ __forceinline__ float bflo(unsigned u) { return __uint_as_float(u << 16); }
; __device__ __forceinline__ float bfhi(unsigned u) { return __uint_as_float(u & 0xffff0000u); }
; __device__ __forceinline__ float silu_f(float v) { return v / (1.f + __expf(-v)); }
; __device__ __forceinline__ void ph_combine(const Params& p_) {
;     ...
;         for (int u = 0; u < 2; ++u) { const int e = e0 + u * nth; act[u] = e < MTOK * DG / 4; const int ee = act[u] ? e : e0;
;             const int row = ee >> 7, c4 = (ee & 127) * 4, b = row >> 12, k = row & 4095, kk = (k <= 2048) ? k : 4096 - k;
;             rowv[u] = row; c4v[u] = c4; kv[u] = k; use_so[u] = (kk != 0 && kk != 2048);
;             ce[u] = (kk == 2048) ? *(const f32x4*)(Ce + (size_t)(2 * 2304 + 2 * 2048) * 512 + b * 512 + c4) : *(const f32x4*)(Ce + ((size_t)b * 2304 + kk) * 512 + c4);
;             so[u] = *(const f32x4*)(So + ((size_t)b * 2048 + (use_so[u] ? kk : 1)) * 512 + c4);
;             gz[u] = *(const u32x2*)(Z + (size_t)row * DIN + DG + c4);
; #pragma unroll
;             for (int j = 0; j < 4; ++j) pv[u][j] = bf2f(PQ[((size_t)(b * 512 + c4 + j) * 2) * 4096 + 2048]); }
;         asm volatile("" ::: "memory");
; #pragma unroll
;         for (int u = 0; u < 2; ++u) if (act[u]) { f32x4 s = ce[u];
;             if (use_so[u]) s = (kv[u] <= 2048) ? s - so[u] : s + so[u];
;             const float alt = (kv[u] & 1) ? -1.f : 1.f;
; #pragma unroll
;             for (int j = 0; j < 4; ++j) s[j] += alt * pv[u][j];
;             u32x2 w; w.x = pk2(s[0] * silu_f(bflo(gz[u].x)), s[1] * silu_f(bfhi(gz[u].x))); w.y = pk2(s[2] * silu_f(bflo(gz[u].y)), s[3] * silu_f(bfhi(gz[u].y)));
;             *(u32x2*)(CAT + (size_t)rowv[u] * DM + c4v[u]) = w; }
.LBB0_678:
	s_or_b64 exec, exec, s[44:45]
	s_waitcnt vmcnt(0)
	v_cndmask_b32_e64 v35, v200, v204, s[26:27]
	v_cndmask_b32_e64 v34, v201, v205, s[26:27]
	v_cndmask_b32_e64 v37, v202, v206, s[26:27]
	v_cndmask_b32_e64 v36, v203, v207, s[26:27]
	v_cndmask_b32_e64 v30, v200, v204, s[54:55]
	v_cndmask_b32_e64 v31, v201, v205, s[54:55]
	v_cndmask_b32_e64 v32, v202, v206, s[54:55]
	v_cndmask_b32_e64 v33, v203, v207, s[54:55]
	v_and_b32_e32 v15, 0x80, v19
	v_lshlrev_b32_e32 v0, 16, v35
	v_lshlrev_b32_e32 v14, 16, v37
	v_cmp_eq_u32_e64 s[42:43], 0, v15
	v_lshlrev_b32_e32 v34, 16, v34
	v_lshlrev_b32_e32 v35, 16, v36
	v_lshlrev_b32_e32 v36, 16, v28
	v_cndmask_b32_e64 v15, -v14, v14, s[42:43]
	v_cndmask_b32_e64 v14, -v0, v0, s[42:43]
	v_mov_b32_e32 v16, v10
	v_mov_b32_e32 v17, v12
	v_and_b32_e32 v28, 0xffff0000, v28
	v_pk_add_f32 v[14:15], v[14:15], v[16:17]
	v_cndmask_b32_e64 v17, -v35, v35, s[42:43]
	v_cndmask_b32_e64 v16, -v34, v34, s[42:43]
	v_mov_b32_e32 v12, v11
	v_mul_f32_e32 v0, 0xbfb8aa3b, v36
	v_lshlrev_b32_e32 v19, 16, v29
	v_pk_add_f32 v[10:11], v[16:17], v[12:13]
	v_exp_f32_e32 v12, v0
	v_mul_f32_e32 v0, 0xbfb8aa3b, v28
	v_exp_f32_e32 v16, v0
	v_mul_f32_e32 v0, 0xbfb8aa3b, v19
	v_exp_f32_e32 v13, v0
	v_and_b32_e32 v29, 0xffff0000, v29
	v_ashrrev_i32_e32 v25, 31, v24
	v_pk_add_f32 v[12:13], v[12:13], 1.0 op_sel_hi:[1,0]
	s_nop 0
	v_div_scale_f32 v0, s[12:13], v13, v13, v19
	v_rcp_f32_e32 v17, v0
	s_nop 0
	v_fma_f32 v34, -v0, v17, 1.0
	v_fmac_f32_e32 v17, v34, v17
	v_div_scale_f32 v34, vcc, v19, v13, v19
	v_mul_f32_e32 v35, v34, v17
	v_fma_f32 v37, -v0, v35, v34
	v_fmac_f32_e32 v35, v37, v17
	v_fma_f32 v0, -v0, v35, v34
	v_div_fmas_f32 v0, v0, v17, v35
	v_div_fixup_f32 v13, v0, v13, v19
	v_div_scale_f32 v0, s[12:13], v12, v12, v36
	v_rcp_f32_e32 v17, v0
	s_nop 0
	v_fma_f32 v19, -v0, v17, 1.0
	v_fmac_f32_e32 v17, v19, v17
	v_div_scale_f32 v19, vcc, v36, v12, v36
	v_mul_f32_e32 v34, v19, v17
	v_fma_f32 v35, -v0, v34, v19
	v_fmac_f32_e32 v34, v35, v17
	v_fma_f32 v0, -v0, v34, v19
	v_div_fmas_f32 v0, v0, v17, v34
	v_div_fixup_f32 v12, v0, v12, v36
	v_mul_f32_e32 v0, 0xbfb8aa3b, v29
	v_exp_f32_e32 v17, v0
	v_pk_mul_f32 v[12:13], v[12:13], v[14:15]
	v_pk_add_f32 v[14:15], v[16:17], 1.0 op_sel_hi:[1,0]
	s_nop 0
	v_div_scale_f32 v0, s[12:13], v15, v15, v29
	v_rcp_f32_e32 v16, v0
	s_nop 0
	v_fma_f32 v17, -v0, v16, 1.0
	v_fmac_f32_e32 v16, v17, v16
	v_div_scale_f32 v17, vcc, v29, v15, v29
	v_mul_f32_e32 v19, v17, v16
	v_fma_f32 v34, -v0, v19, v17
	v_fmac_f32_e32 v19, v34, v16
	v_fma_f32 v0, -v0, v19, v17
	v_div_fmas_f32 v0, v0, v16, v19
	v_div_fixup_f32 v15, v0, v15, v29
	v_div_scale_f32 v0, s[12:13], v14, v14, v28
	v_rcp_f32_e32 v16, v0
	s_nop 0
	v_fma_f32 v17, -v0, v16, 1.0
	v_fmac_f32_e32 v16, v17, v16
	v_div_scale_f32 v17, vcc, v28, v14, v28
	v_mul_f32_e32 v19, v17, v16
	v_fma_f32 v29, -v0, v19, v17
	v_fmac_f32_e32 v19, v29, v16
	v_fma_f32 v0, -v0, v19, v17
	v_div_fmas_f32 v0, v0, v16, v19
	v_div_fixup_f32 v14, v0, v14, v28
	v_pk_mul_f32 v[10:11], v[14:15], v[10:11]
	v_and_b32_sdwa v14, v12, v179 dst_sel:DWORD dst_unused:UNUSED_PAD src0_sel:WORD_1 src1_sel:DWORD
	v_and_b32_sdwa v0, v13, v179 dst_sel:DWORD dst_unused:UNUSED_PAD src0_sel:WORD_1 src1_sel:DWORD
	v_add3_u32 v12, v12, v14, s14
	v_and_b32_sdwa v14, v10, v179 dst_sel:DWORD dst_unused:UNUSED_PAD src0_sel:WORD_1 src1_sel:DWORD
	v_add3_u32 v0, v13, v0, s14
	v_and_b32_sdwa v13, v11, v179 dst_sel:DWORD dst_unused:UNUSED_PAD src0_sel:WORD_1 src1_sel:DWORD
	v_add3_u32 v10, v10, v14, s14
	v_add3_u32 v11, v11, v13, s14
	v_and_b32_e32 v10, 0xffff0000, v10
	v_and_b32_e32 v11, 0xffff0000, v11
	v_or_b32_sdwa v10, v10, v12 dst_sel:DWORD dst_unused:UNUSED_PAD src0_sel:DWORD src1_sel:WORD_1
	v_lshlrev_b64 v[12:13], 12, v[24:25]
	v_or_b32_sdwa v11, v11, v0 dst_sel:DWORD dst_unused:UNUSED_PAD src0_sel:DWORD src1_sel:WORD_1
	v_lshl_add_u64 v[12:13], s[56:57], 0, v[12:13]
	v_lshlrev_b32_e32 v0, 1, v22
	v_lshl_add_u64 v[12:13], v[12:13], 0, v[0:1]
	global_store_dwordx2 v[12:13], v[10:11], off offset:3072
	s_and_saveexec_b64 s[44:45], s[38:39]
	s_cbranch_execz .LBB0_663
	s_and_saveexec_b64 s[38:39], s[40:41]
	s_cbranch_execz .LBB0_662
	s_and_saveexec_b64 s[12:13], s[36:37]
	s_xor_b64 s[36:37], exec, s[12:13]
	v_pk_add_f32 v[4:5], v[4:5], v[8:9]
	v_pk_add_f32 v[2:3], v[2:3], v[6:7]
	s_andn2_saveexec_b64 s[36:37], s[36:37]
	s_cbranch_execz .LBB0_661
	v_sub_f32_e32 v5, v5, v9
	v_sub_f32_e32 v4, v4, v8
	v_sub_f32_e32 v3, v3, v7
	v_sub_f32_e32 v2, v2, v6
	s_branch .LBB0_661

; __device__ __forceinline__ unsigned xb_ld(unsigned* p)              { return __hip_atomic_load(p, __ATOMIC_RELAXED, __HIP_MEMORY_SCOPE_AGENT); }
; __device__ __forceinline__ unsigned xb_add(unsigned* p, unsigned v) { return __hip_atomic_fetch_add(p, v, __ATOMIC_RELAXED, __HIP_MEMORY_SCOPE_AGENT); }
; #define XB_SPIN(cond, bar) do { unsigned _sp = 0; while (cond) { __builtin_amdgcn_s_sleep(1); \
;     if ((++_sp & 255u) == 0u) { if (xb_ld(&(bar)[XB_TMO])) break; if (_sp > XB_SPIN_CAP) { atomicAdd(&(bar)[XB_TMO], 1u); break; } } } } while (0)
; __device__ __forceinline__ void xcd_barrier(const XcdBarrier& b) {
;     ...
;         const unsigned old = xb_add(&bar[XB_XSUB(b.x)], 1u);
;         const unsigned gen = old / nloc;
;         if (old + 1u == (gen + 1u) * nloc) {
;             __builtin_amdgcn_fence(__ATOMIC_RELEASE, "agent");
;             asm volatile("s_waitcnt vmcnt(0)" ::: "memory");
;             const unsigned og = xb_add(&bar[XB_TOP], 1u);
;             const unsigned tg = og / nx;
;             if (og + 1u == (tg + 1u) * nx) xb_add(&bar[XB_TOPGEN], 1u);
;             else XB_SPIN(xb_ld(&bar[XB_TOPGEN]) == tg, bar);
;             __builtin_amdgcn_fence(__ATOMIC_ACQUIRE, "agent");
;             xb_add(&bar[XB_XGEN(b.x)], 1u);
;             asm volatile("s_waitcnt vmcnt(0)" ::: "memory");
;         } else {
;             XB_SPIN(xb_ld(&bar[XB_XGEN(b.x)]) == gen, bar);
.LBB0_703:
	s_or_b64 exec, exec, s[38:39]
	v_cvt_f32_u32_e32 v5, v3
	s_waitcnt vmcnt(0)
	v_readfirstlane_b32 s6, v4
	v_sub_u32_e32 v4, 0, v3
	v_rcp_iflag_f32_e32 v5, v5
	v_add_u32_e32 v6, s6, v0
	v_mul_f32_e32 v5, 0x4f7ffffe, v5
	v_cvt_u32_f32_e32 v5, v5
	v_mul_lo_u32 v0, v4, v5
	v_mul_hi_u32 v0, v5, v0
	v_add_u32_e32 v0, v5, v0
	v_mul_hi_u32 v0, v6, v0
	v_mul_lo_u32 v4, v0, v3
	v_sub_u32_e32 v4, v6, v4
	v_add_u32_e32 v5, 1, v0
	v_cmp_ge_u32_e32 vcc, v4, v3
	s_nop 1
	v_cndmask_b32_e32 v0, v0, v5, vcc
	v_sub_u32_e32 v5, v4, v3
	v_cndmask_b32_e32 v4, v4, v5, vcc
	v_add_u32_e32 v5, 1, v0
	v_cmp_ge_u32_e32 vcc, v4, v3
	v_add_u32_e32 v4, 1, v6
	s_nop 0
	v_cndmask_b32_e32 v0, v0, v5, vcc
	v_mul_lo_u32 v5, v3, v0
	v_add_u32_e32 v3, v5, v3
	v_cmp_ne_u32_e32 vcc, v4, v3
	s_mov_b32 s13, -1
	s_nop 0
	v_writelane_b32 v255, s13, 47
	s_and_saveexec_b64 s[12:13], vcc
	s_xor_b64 s[38:39], exec, s[12:13]
	s_cbranch_execz .LBB0_717
	buffer_inv sc1
	v_readlane_b32 s12, v255, 10
	v_readlane_b32 s13, v255, 11
	s_waitcnt lgkmcnt(0)
	s_nop 3
	global_load_dword v2, v1, s[12:13] sc1
	s_waitcnt vmcnt(0)
	v_cmp_eq_u32_e32 vcc, v2, v0
	v_readfirstlane_b32 s27, v0
	s_nop 1
	v_writelane_b32 v255, s27, 47
	s_mov_b64 vcc, 0
	s_and_saveexec_b64 s[40:41], vcc
	s_cbranch_execz .LBB0_716
	s_mov_b32 s9, 1
	s_mov_b64 s[42:43], 0
	s_branch .LBB0_707

; __device__ __forceinline__ unsigned xb_ld(unsigned* p)              { return __hip_atomic_load(p, __ATOMIC_RELAXED, __HIP_MEMORY_SCOPE_AGENT); }
; __device__ __forceinline__ unsigned xb_add(unsigned* p, unsigned v) { return __hip_atomic_fetch_add(p, v, __ATOMIC_RELAXED, __HIP_MEMORY_SCOPE_AGENT); }
; #define XB_SPIN(cond, bar) do { unsigned _sp = 0; while (cond) { __builtin_amdgcn_s_sleep(1); \
;     if ((++_sp & 255u) == 0u) { if (xb_ld(&(bar)[XB_TMO])) break; if (_sp > XB_SPIN_CAP) { atomicAdd(&(bar)[XB_TMO], 1u); break; } } } } while (0)
; __device__ __forceinline__ void xcd_barrier(const XcdBarrier& b) {
;     ...
;             const unsigned og = xb_add(&bar[XB_TOP], 1u);
;             const unsigned tg = og / nx;
;             if (og + 1u == (tg + 1u) * nx) xb_add(&bar[XB_TOPGEN], 1u);
;             else XB_SPIN(xb_ld(&bar[XB_TOPGEN]) == tg, bar);
.LBB0_720:
	s_or_b64 exec, exec, s[40:41]
	s_waitcnt vmcnt(0)
	v_readfirstlane_b32 s6, v3
	v_sub_u32_e32 v4, 0, v2
	v_readlane_b32 s12, v255, 14
	v_add_u32_e32 v3, s6, v0
	v_cvt_f32_u32_e32 v0, v2
	v_readlane_b32 s13, v255, 15
	s_mov_b64 s[40:41], -1
	v_rcp_iflag_f32_e32 v0, v0
	s_nop 0
	v_mul_f32_e32 v0, 0x4f7ffffe, v0
	v_cvt_u32_f32_e32 v0, v0
	v_mul_lo_u32 v4, v4, v0
	v_mul_hi_u32 v4, v0, v4
	v_add_u32_e32 v0, v0, v4
	v_mul_hi_u32 v0, v3, v0
	v_mul_lo_u32 v4, v0, v2
	v_sub_u32_e32 v4, v3, v4
	v_cmp_ge_u32_e32 vcc, v4, v2
	v_add_u32_e32 v5, 1, v0
	v_add_u32_e32 v3, 1, v3
	v_cndmask_b32_e32 v0, v0, v5, vcc
	v_sub_u32_e32 v5, v4, v2
	v_cndmask_b32_e32 v4, v4, v5, vcc
	v_cmp_ge_u32_e32 vcc, v4, v2
	v_add_u32_e32 v4, 1, v0
	s_nop 0
	v_cndmask_b32_e32 v0, v0, v4, vcc
	v_mul_lo_u32 v4, v2, v0
	v_add_u32_e32 v2, v4, v2
	v_cmp_ne_u32_e32 vcc, v3, v2
	v_mov_b64_e32 v[2:3], s[12:13]
	s_and_saveexec_b64 s[38:39], vcc
	s_cbranch_execz .LBB0_732
	v_readlane_b32 s12, v255, 14
	v_readlane_b32 s13, v255, 15
	s_mov_b64 s[42:43], 0
	s_nop 3
	global_load_dword v2, v1, s[12:13] sc1
	s_waitcnt vmcnt(0)
	v_cmp_eq_u32_e32 vcc, v2, v0
	v_readfirstlane_b32 s27, v0
	s_nop 1
	v_writelane_b32 v255, s27, 47
	s_mov_b64 vcc, 0
	s_and_saveexec_b64 s[40:41], vcc
	s_cbranch_execz .LBB0_731
	s_mov_b32 s9, 1
	s_branch .LBB0_724

; #define PG8_STAGE(bufoff, gbase, voff) do { _Pragma("unroll") for (int _i = 0; _i < 2; ++_i) \
;         __builtin_amdgcn_global_load_lds((const unsigned*)((const char*)(gbase) + (voff)[_i]), (PG8_LAS unsigned*)(lds + (bufoff) + ldsw + _i * 8192), 16, 0, 0); } while (0)
; #define PG8_LDA(dst, b, h) do { _Pragma("unroll") for (int m = 0; m < 4; ++m) _Pragma("unroll") for (int k = 0; k < 2; ++k) dst[m][k] = *(const PG8_LAS bf16x8*)(lds + PG8_SA(b, h) + aoff + m * 2048 + k * 1024); } while (0)
; #define PG8_LDB(dst, b, h) do { _Pragma("unroll") for (int n = 0; n < 2; ++n) _Pragma("unroll") for (int k = 0; k < 2; ++k) dst[n][k] = *(const PG8_LAS bf16x8*)(lds + PG8_SB(b, h) + boff + n * 2048 + k * 1024); } while (0)
; #define PG8_MMA(ai, bj, At, Bt) do { __builtin_amdgcn_s_setprio(1); _Pragma("unroll") for (int m = 0; m < 4; ++m) _Pragma("unroll") for (int n = 0; n < 2; ++n) _Pragma("unroll") for (int k = 0; k < 2; ++k) \
;         acc[ai][bj][m][n] = __builtin_amdgcn_mfma_f32_16x16x32_bf16(Bt[n][k], At[m][k], acc[ai][bj][m][n], 0, 0, 0); __builtin_amdgcn_s_setprio(0); } while (0)
; #define PG8_WAIT_V(n) asm volatile("s_waitcnt vmcnt(" #n ")" ::: "memory")
; #define PG8_WAIT_L(n) asm volatile("s_waitcnt lgkmcnt(" #n ")" ::: "memory")
; #define PG8_BAR __builtin_amdgcn_s_barrier()
; #define PG8_SCHED __builtin_amdgcn_sched_barrier(0)
; template <class Epi, class Sched, bool ALIGN_EPI>
; __device__ __forceinline__ void gemm_phase(PG8_LAS unsigned char* lds, const Gemm g, const Sched& S, const Epi& E) {
;     ...
;         for (int t = 0; t < nt; t += 2) {
;             const bool last = (t == nt - 2);
;             const char* a1 = cA + (size_t)(t + 1) * kstep;
;             const char* a2 = last ? nA : cA + (size_t)(t + 2) * kstep; const char* b2 = last ? nB : cB + (size_t)(t + 2) * kstep;
;             const char* a3 = a2 + kstep; const char* b3 = b2 + kstep;
;             PG8_LDB(B0, 0, 0); PG8_LDB(B1, 0, 1); PG8_SCHED; PG8_LDA(At, 0, 0); PG8_STAGE(PG8_SA(1, 1), a1 + hA, voffA);
;             PG8_WAIT_V(8); PG8_WAIT_L(0); PG8_BAR; PG8_MMA(0, 0, At, B0); PG8_MMA(0, 1, At, B1); PG8_BAR; PG8_SCHED;
;             PG8_LDA(At, 0, 1); PG8_STAGE(PG8_SB(0, 0), b2, voffB); PG8_STAGE(PG8_SB(0, 1), b2 + hB, voffB); PG8_STAGE(PG8_SA(0, 0), a2, voffA);
;             PG8_WAIT_V(8); PG8_WAIT_L(0); PG8_BAR; PG8_MMA(1, 0, At, B0); PG8_MMA(1, 1, At, B1); PG8_BAR; PG8_SCHED;
.LBB0_760:
	s_cmp_eq_u32 s54, 18
	s_cbranch_scc0 .Lp6_a
	v_cmp_gt_u32_e32 vcc, 64, v147
	s_nop 4
	s_cbranch_vccz .Lp6_a
	v_readlane_b32 s98, v255, 14
	v_readlane_b32 s99, v255, 15
	s_nop 4
	global_load_dword v248, v1, s[98:99] sc1
.Lp6_a:
	s_cmp_eq_u32 s54, 20
	s_cbranch_scc0 .Lp6_b
	v_cmp_gt_u32_e32 vcc, 64, v147
	s_nop 4
	s_cbranch_vccz .Lp6_b
	v_readlane_b32 s32, v255, 47
	s_waitcnt vmcnt(8)
	v_readfirstlane_b32 s98, v248
	s_nop 0
	s_cmp_lg_u32 s98, s32
	s_cbranch_scc1 .Lp6_ok
	v_readlane_b32 s98, v255, 14
	v_readlane_b32 s99, v255, 15
	s_mov_b32 vcc_hi, 0
	s_nop 3
.Lp6_spin:
	global_load_dword v248, v1, s[98:99] sc1
	s_waitcnt vmcnt(0)
	v_readfirstlane_b32 vcc_lo, v248
	s_nop 0
	s_cmp_lg_u32 vcc_lo, s32
	s_cbranch_scc1 .Lp6_ok
	s_sleep 1
	s_add_i32 vcc_hi, vcc_hi, 1
	s_cmpk_lt_u32 vcc_hi, 0x4000
	s_cbranch_scc1 .Lp6_spin
.Lp6_ok:
	buffer_inv sc1
	s_waitcnt vmcnt(0)
.Lp6_b:
	s_add_u32 s6, s60, 0xfff80080
	s_addc_u32 s26, s61, -1
	s_add_i32 s27, 0, 0x10000
	s_cmp_eq_u32 s54, 28
	s_cselect_b32 s93, s51, s26
	s_cselect_b32 s92, s50, s6
	s_cselect_b32 s63, s53, s49
	s_cselect_b32 s62, s52, s47
	s_add_i32 s6, 0, 0x14000
	v_add_u32_e32 v142, s27, v173
	v_add_u32_e32 v170, s6, v173
	ds_read_b128 v[126:129], v142
	ds_read_b128 v[130:133], v142 offset:1024
	ds_read_b128 v[134:137], v142 offset:2048
	ds_read_b128 v[142:145], v142 offset:3072
	ds_read_b128 v[166:169], v170
	ds_read_b128 v[198:201], v170 offset:1024
	ds_read_b128 v[202:205], v170 offset:2048
	ds_read_b128 v[206:209], v170 offset:3072
	v_lshl_add_u64 v[170:171], s[60:61], 0, v[162:163]
	s_add_i32 m0, s59, 0xc000
	ds_read_b128 v[210:213], v175
	ds_read_b128 v[214:217], v175 offset:1024
	ds_read_b128 v[218:221], v175 offset:2048
	ds_read_b128 v[222:225], v175 offset:3072
	ds_read_b128 v[226:229], v175 offset:4096
	ds_read_b128 v[230:233], v175 offset:5120
	ds_read_b128 v[234:237], v175 offset:6144
	ds_read_b128 v[238:241], v175 offset:7168
	global_load_lds_dwordx4 v[170:171], off
	v_lshl_add_u64 v[170:171], s[60:61], 0, v[164:165]
	s_add_i32 m0, s59, 0xe000
	s_nop 0
	global_load_lds_dwordx4 v[170:171], off
	s_waitcnt vmcnt(8)
	s_waitcnt lgkmcnt(0)
	s_barrier
	s_setprio 1
	s_waitcnt lgkmcnt(0)
	v_mfma_f32_16x16x32_bf16 v[138:141], v[126:129], v[210:213], v[138:141]
	v_mfma_f32_16x16x32_bf16 v[122:125], v[134:137], v[210:213], v[122:125]
	v_mfma_f32_16x16x32_bf16 v[110:113], v[126:129], v[218:221], v[110:113]
	v_mfma_f32_16x16x32_bf16 v[106:109], v[134:137], v[218:221], v[106:109]
	v_mfma_f32_16x16x32_bf16 v[94:97], v[126:129], v[226:229], v[94:97]
	v_mfma_f32_16x16x32_bf16 v[90:93], v[134:137], v[226:229], v[90:93]
	v_mfma_f32_16x16x32_bf16 v[78:81], v[126:129], v[234:237], v[78:81]
	v_mfma_f32_16x16x32_bf16 v[74:77], v[134:137], v[234:237], v[74:77]
	v_mfma_f32_16x16x32_bf16 v[138:141], v[130:133], v[214:217], v[138:141]
	v_mfma_f32_16x16x32_bf16 v[122:125], v[142:145], v[214:217], v[122:125]
	v_mfma_f32_16x16x32_bf16 v[110:113], v[130:133], v[222:225], v[110:113]
	v_mfma_f32_16x16x32_bf16 v[106:109], v[142:145], v[222:225], v[106:109]
	v_mfma_f32_16x16x32_bf16 v[94:97], v[130:133], v[230:233], v[94:97]
	v_mfma_f32_16x16x32_bf16 v[90:93], v[142:145], v[230:233], v[90:93]
	v_mfma_f32_16x16x32_bf16 v[78:81], v[130:133], v[238:241], v[78:81]
	v_mfma_f32_16x16x32_bf16 v[74:77], v[142:145], v[238:241], v[74:77]
	s_setprio 0
	s_setprio 1
	v_mfma_f32_16x16x32_bf16 v[118:121], v[166:169], v[210:213], v[118:121]
	v_mfma_f32_16x16x32_bf16 v[114:117], v[202:205], v[210:213], v[114:117]
	v_mfma_f32_16x16x32_bf16 v[102:105], v[166:169], v[218:221], v[102:105]
	v_mfma_f32_16x16x32_bf16 v[98:101], v[202:205], v[218:221], v[98:101]
	v_mfma_f32_16x16x32_bf16 v[86:89], v[166:169], v[226:229], v[86:89]
	v_mfma_f32_16x16x32_bf16 v[82:85], v[202:205], v[226:229], v[82:85]
	v_mfma_f32_16x16x32_bf16 v[70:73], v[166:169], v[234:237], v[70:73]
	v_mfma_f32_16x16x32_bf16 v[66:69], v[202:205], v[234:237], v[66:69]
	v_mfma_f32_16x16x32_bf16 v[118:121], v[198:201], v[214:217], v[118:121]
	v_mfma_f32_16x16x32_bf16 v[114:117], v[206:209], v[214:217], v[114:117]
	v_mfma_f32_16x16x32_bf16 v[102:105], v[198:201], v[222:225], v[102:105]
	v_mfma_f32_16x16x32_bf16 v[98:101], v[206:209], v[222:225], v[98:101]
	v_mfma_f32_16x16x32_bf16 v[86:89], v[198:201], v[230:233], v[86:89]
	v_mfma_f32_16x16x32_bf16 v[82:85], v[206:209], v[230:233], v[82:85]
	v_mfma_f32_16x16x32_bf16 v[70:73], v[198:201], v[238:241], v[70:73]
	v_mfma_f32_16x16x32_bf16 v[66:69], v[206:209], v[238:241], v[66:69]
	s_setprio 0
	s_barrier
	s_add_i32 s26, s27, s24
	v_lshl_add_u64 v[170:171], s[62:63], 0, v[0:1]
	s_mov_b32 m0, s26
	ds_read_b128 v[210:213], v175 offset:16384
	ds_read_b128 v[214:217], v175 offset:17408
	ds_read_b128 v[218:221], v175 offset:18432
	ds_read_b128 v[222:225], v175 offset:19456
	ds_read_b128 v[226:229], v175 offset:20480
	ds_read_b128 v[230:233], v175 offset:21504
	ds_read_b128 v[234:237], v175 offset:22528
	ds_read_b128 v[238:241], v175 offset:23552
	global_load_lds_dwordx4 v[170:171], off
	s_add_i32 m0, s26, 0x2000
	s_add_u32 s26, s62, 0x80000
	v_lshl_add_u64 v[176:177], s[62:63], 0, v[160:161]
	s_addc_u32 s27, s63, 0
	s_add_i32 s6, s6, s24
	global_load_lds_dwordx4 v[176:177], off
	v_lshl_add_u64 v[242:243], s[26:27], 0, v[0:1]
	s_mov_b32 m0, s6
	v_lshl_add_u64 v[244:245], s[92:93], 0, v[160:161]
	global_load_lds_dwordx4 v[242:243], off
	v_lshl_add_u64 v[242:243], s[26:27], 0, v[160:161]
	s_add_i32 m0, s6, 0x2000
	s_nop 0
	global_load_lds_dwordx4 v[242:243], off
	v_lshl_add_u64 v[242:243], s[92:93], 0, v[0:1]
	s_mov_b32 m0, s59
	s_nop 0
	global_load_lds_dwordx4 v[242:243], off
	s_mov_b32 m0, s71
	s_nop 0
	global_load_lds_dwordx4 v[244:245], off
	s_waitcnt vmcnt(8)
	s_waitcnt lgkmcnt(0)
	s_barrier
; #define PG8_STAGE(bufoff, gbase, voff) do { _Pragma("unroll") for (int _i = 0; _i < 2; ++_i) \
;         __builtin_amdgcn_global_load_lds((const unsigned*)((const char*)(gbase) + (voff)[_i]), (PG8_LAS unsigned*)(lds + (bufoff) + ldsw + _i * 8192), 16, 0, 0); } while (0)
; #define PG8_LDA(dst, b, h) do { _Pragma("unroll") for (int m = 0; m < 4; ++m) _Pragma("unroll") for (int k = 0; k < 2; ++k) dst[m][k] = *(const PG8_LAS bf16x8*)(lds + PG8_SA(b, h) + aoff + m * 2048 + k * 1024); } while (0)
; #define PG8_LDB(dst, b, h) do { _Pragma("unroll") for (int n = 0; n < 2; ++n) _Pragma("unroll") for (int k = 0; k < 2; ++k) dst[n][k] = *(const PG8_LAS bf16x8*)(lds + PG8_SB(b, h) + boff + n * 2048 + k * 1024); } while (0)
; #define PG8_MMA(ai, bj, At, Bt) do { __builtin_amdgcn_s_setprio(1); _Pragma("unroll") for (int m = 0; m < 4; ++m) _Pragma("unroll") for (int n = 0; n < 2; ++n) _Pragma("unroll") for (int k = 0; k < 2; ++k) \
;         acc[ai][bj][m][n] = __builtin_amdgcn_mfma_f32_16x16x32_bf16(Bt[n][k], At[m][k], acc[ai][bj][m][n], 0, 0, 0); __builtin_amdgcn_s_setprio(0); } while (0)
; #define PG8_WAIT_V(n) asm volatile("s_waitcnt vmcnt(" #n ")" ::: "memory")
; #define PG8_WAIT_L(n) asm volatile("s_waitcnt lgkmcnt(" #n ")" ::: "memory")
; #define PG8_BAR __builtin_amdgcn_s_barrier()
; #define PG8_SCHED __builtin_amdgcn_sched_barrier(0)
; template <class Epi, class Sched, bool ALIGN_EPI>
; __device__ __forceinline__ void gemm_phase(PG8_LAS unsigned char* lds, const Gemm g, const Sched& S, const Epi& E) {
;     ...
;             PG8_WAIT_V(8); PG8_WAIT_L(0); PG8_BAR; PG8_MMA(1, 0, At, B0); PG8_MMA(1, 1, At, B1); PG8_BAR; PG8_SCHED;
;             PG8_LDB(B0, 1, 0); PG8_LDB(B1, 1, 1); PG8_SCHED; PG8_LDA(At, 1, 0); PG8_STAGE(PG8_SA(0, 1), a2 + hA, voffA);
;             PG8_WAIT_V(8); PG8_WAIT_L(0); PG8_BAR; PG8_MMA(0, 0, At, B0); PG8_MMA(0, 1, At, B1); PG8_BAR; PG8_SCHED;
	s_setprio 1
	s_waitcnt lgkmcnt(0)
	v_mfma_f32_16x16x32_bf16 v[62:65], v[126:129], v[210:213], v[62:65]
	v_mfma_f32_16x16x32_bf16 v[58:61], v[134:137], v[210:213], v[58:61]
	v_mfma_f32_16x16x32_bf16 v[46:49], v[126:129], v[218:221], v[46:49]
	v_mfma_f32_16x16x32_bf16 v[42:45], v[134:137], v[218:221], v[42:45]
	v_mfma_f32_16x16x32_bf16 v[30:33], v[126:129], v[226:229], v[30:33]
	v_mfma_f32_16x16x32_bf16 v[26:29], v[134:137], v[226:229], v[26:29]
	v_mfma_f32_16x16x32_bf16 v[14:17], v[126:129], v[234:237], v[14:17]
	v_mfma_f32_16x16x32_bf16 v[10:13], v[134:137], v[234:237], v[10:13]
	v_mfma_f32_16x16x32_bf16 v[62:65], v[130:133], v[214:217], v[62:65]
	v_mfma_f32_16x16x32_bf16 v[58:61], v[142:145], v[214:217], v[58:61]
	v_mfma_f32_16x16x32_bf16 v[46:49], v[130:133], v[222:225], v[46:49]
	v_mfma_f32_16x16x32_bf16 v[42:45], v[142:145], v[222:225], v[42:45]
	v_mfma_f32_16x16x32_bf16 v[30:33], v[130:133], v[230:233], v[30:33]
	v_mfma_f32_16x16x32_bf16 v[26:29], v[142:145], v[230:233], v[26:29]
	v_mfma_f32_16x16x32_bf16 v[14:17], v[130:133], v[238:241], v[14:17]
	v_mfma_f32_16x16x32_bf16 v[10:13], v[142:145], v[238:241], v[10:13]
	s_setprio 0
	s_setprio 1
	v_mfma_f32_16x16x32_bf16 v[54:57], v[166:169], v[210:213], v[54:57]
	v_mfma_f32_16x16x32_bf16 v[50:53], v[202:205], v[210:213], v[50:53]
	v_mfma_f32_16x16x32_bf16 v[38:41], v[166:169], v[218:221], v[38:41]
	v_mfma_f32_16x16x32_bf16 v[34:37], v[202:205], v[218:221], v[34:37]
	v_mfma_f32_16x16x32_bf16 v[22:25], v[166:169], v[226:229], v[22:25]
	v_mfma_f32_16x16x32_bf16 v[18:21], v[202:205], v[226:229], v[18:21]
	v_mfma_f32_16x16x32_bf16 v[6:9], v[166:169], v[234:237], v[6:9]
	v_mfma_f32_16x16x32_bf16 v[2:5], v[202:205], v[234:237], v[2:5]
	v_mfma_f32_16x16x32_bf16 v[54:57], v[198:201], v[214:217], v[54:57]
	v_mfma_f32_16x16x32_bf16 v[50:53], v[206:209], v[214:217], v[50:53]
	v_mfma_f32_16x16x32_bf16 v[38:41], v[198:201], v[222:225], v[38:41]
	v_mfma_f32_16x16x32_bf16 v[34:37], v[206:209], v[222:225], v[34:37]
	v_mfma_f32_16x16x32_bf16 v[22:25], v[198:201], v[230:233], v[22:25]
	v_mfma_f32_16x16x32_bf16 v[18:21], v[206:209], v[230:233], v[18:21]
	v_mfma_f32_16x16x32_bf16 v[6:9], v[198:201], v[238:241], v[6:9]
	v_mfma_f32_16x16x32_bf16 v[2:5], v[206:209], v[238:241], v[2:5]
	s_setprio 0
	s_barrier
	s_add_i32 s6, 0, 0x18000
	s_add_i32 s55, 0, 0x1c000
	v_add_u32_e32 v142, s6, v173
	v_add_u32_e32 v197, s55, v173
	ds_read_b128 v[126:129], v142
	ds_read_b128 v[130:133], v142 offset:1024
	ds_read_b128 v[134:137], v142 offset:2048
	ds_read_b128 v[142:145], v142 offset:3072
	ds_read_b128 v[166:169], v197
	ds_read_b128 v[198:201], v197 offset:1024
	ds_read_b128 v[202:205], v197 offset:2048
	ds_read_b128 v[206:209], v197 offset:3072
	s_add_u32 s26, s92, 0x80000
	s_addc_u32 s27, s93, 0
	s_mov_b32 m0, s94
	v_lshl_add_u64 v[246:247], s[26:27], 0, v[0:1]
	ds_read_b128 v[210:213], v175 offset:32768
	ds_read_b128 v[214:217], v175 offset:33792
	ds_read_b128 v[218:221], v175 offset:34816
	ds_read_b128 v[222:225], v175 offset:35840
	ds_read_b128 v[226:229], v175 offset:36864
	ds_read_b128 v[230:233], v175 offset:37888
	ds_read_b128 v[234:237], v175 offset:38912
	ds_read_b128 v[238:241], v175 offset:39936
	global_load_lds_dwordx4 v[246:247], off
	v_lshl_add_u64 v[246:247], s[26:27], 0, v[160:161]
	s_mov_b32 m0, s95
	s_nop 0
	global_load_lds_dwordx4 v[246:247], off
	s_waitcnt vmcnt(8)
	s_waitcnt lgkmcnt(0)
	s_barrier
	s_setprio 1
	s_waitcnt lgkmcnt(0)
	v_mfma_f32_16x16x32_bf16 v[138:141], v[126:129], v[210:213], v[138:141]
	v_mfma_f32_16x16x32_bf16 v[122:125], v[134:137], v[210:213], v[122:125]
	v_mfma_f32_16x16x32_bf16 v[110:113], v[126:129], v[218:221], v[110:113]
	v_mfma_f32_16x16x32_bf16 v[106:109], v[134:137], v[218:221], v[106:109]
	v_mfma_f32_16x16x32_bf16 v[94:97], v[126:129], v[226:229], v[94:97]
	v_mfma_f32_16x16x32_bf16 v[90:93], v[134:137], v[226:229], v[90:93]
	v_mfma_f32_16x16x32_bf16 v[78:81], v[126:129], v[234:237], v[78:81]
	v_mfma_f32_16x16x32_bf16 v[74:77], v[134:137], v[234:237], v[74:77]
	v_mfma_f32_16x16x32_bf16 v[138:141], v[130:133], v[214:217], v[138:141]
	v_mfma_f32_16x16x32_bf16 v[122:125], v[142:145], v[214:217], v[122:125]
	v_mfma_f32_16x16x32_bf16 v[110:113], v[130:133], v[222:225], v[110:113]
	v_mfma_f32_16x16x32_bf16 v[106:109], v[142:145], v[222:225], v[106:109]
	v_mfma_f32_16x16x32_bf16 v[94:97], v[130:133], v[230:233], v[94:97]
	v_mfma_f32_16x16x32_bf16 v[90:93], v[142:145], v[230:233], v[90:93]
	v_mfma_f32_16x16x32_bf16 v[78:81], v[130:133], v[238:241], v[78:81]
	v_mfma_f32_16x16x32_bf16 v[74:77], v[142:145], v[238:241], v[74:77]
	s_setprio 0
	s_setprio 1
	v_mfma_f32_16x16x32_bf16 v[118:121], v[166:169], v[210:213], v[118:121]
	v_mfma_f32_16x16x32_bf16 v[114:117], v[202:205], v[210:213], v[114:117]
	v_mfma_f32_16x16x32_bf16 v[102:105], v[166:169], v[218:221], v[102:105]
	v_mfma_f32_16x16x32_bf16 v[98:101], v[202:205], v[218:221], v[98:101]
	v_mfma_f32_16x16x32_bf16 v[86:89], v[166:169], v[226:229], v[86:89]
	v_mfma_f32_16x16x32_bf16 v[82:85], v[202:205], v[226:229], v[82:85]
	v_mfma_f32_16x16x32_bf16 v[70:73], v[166:169], v[234:237], v[70:73]
	v_mfma_f32_16x16x32_bf16 v[66:69], v[202:205], v[234:237], v[66:69]
	v_mfma_f32_16x16x32_bf16 v[118:121], v[198:201], v[214:217], v[118:121]
	v_mfma_f32_16x16x32_bf16 v[114:117], v[206:209], v[214:217], v[114:117]
	v_mfma_f32_16x16x32_bf16 v[102:105], v[198:201], v[222:225], v[102:105]
	v_mfma_f32_16x16x32_bf16 v[98:101], v[206:209], v[222:225], v[98:101]
	v_mfma_f32_16x16x32_bf16 v[86:89], v[198:201], v[230:233], v[86:89]
	v_mfma_f32_16x16x32_bf16 v[82:85], v[206:209], v[230:233], v[82:85]
	v_mfma_f32_16x16x32_bf16 v[70:73], v[198:201], v[238:241], v[70:73]
	v_mfma_f32_16x16x32_bf16 v[66:69], v[206:209], v[238:241], v[66:69]
	s_setprio 0
	s_barrier
; #define PG8_STAGE(bufoff, gbase, voff) do { _Pragma("unroll") for (int _i = 0; _i < 2; ++_i) \
;         __builtin_amdgcn_global_load_lds((const unsigned*)((const char*)(gbase) + (voff)[_i]), (PG8_LAS unsigned*)(lds + (bufoff) + ldsw + _i * 8192), 16, 0, 0); } while (0)
; #define PG8_LDA(dst, b, h) do { _Pragma("unroll") for (int m = 0; m < 4; ++m) _Pragma("unroll") for (int k = 0; k < 2; ++k) dst[m][k] = *(const PG8_LAS bf16x8*)(lds + PG8_SA(b, h) + aoff + m * 2048 + k * 1024); } while (0)
; #define PG8_MMA(ai, bj, At, Bt) do { __builtin_amdgcn_s_setprio(1); _Pragma("unroll") for (int m = 0; m < 4; ++m) _Pragma("unroll") for (int n = 0; n < 2; ++n) _Pragma("unroll") for (int k = 0; k < 2; ++k) \
;         acc[ai][bj][m][n] = __builtin_amdgcn_mfma_f32_16x16x32_bf16(Bt[n][k], At[m][k], acc[ai][bj][m][n], 0, 0, 0); __builtin_amdgcn_s_setprio(0); } while (0)
; #define PG8_WAIT_V(n) asm volatile("s_waitcnt vmcnt(" #n ")" ::: "memory")
; #define PG8_WAIT_L(n) asm volatile("s_waitcnt lgkmcnt(" #n ")" ::: "memory")
; #define PG8_BAR __builtin_amdgcn_s_barrier()
; #define PG8_SCHED __builtin_amdgcn_sched_barrier(0)
; template <class Epi, class Sched, bool ALIGN_EPI>
; __device__ __forceinline__ void gemm_phase(PG8_LAS unsigned char* lds, const Gemm g, const Sched& S, const Epi& E) {
;     ...
;             PG8_LDA(At, 1, 1); PG8_STAGE(PG8_SB(1, 0), b3, voffB); PG8_STAGE(PG8_SB(1, 1), b3 + hB, voffB); PG8_STAGE(PG8_SA(1, 0), a3, voffA);
;             PG8_WAIT_V(8); PG8_WAIT_L(0); PG8_BAR; PG8_MMA(1, 0, At, B0); PG8_MMA(1, 1, At, B1); PG8_BAR; PG8_SCHED;
;         }
;         if constexpr (ALIGN_EPI) { if (wr == 0) PG8_BAR; }
	s_add_i32 s6, s6, s24
	v_lshl_add_u64 v[170:171], v[170:171], 0, s[16:17]
	s_mov_b32 m0, s6
	ds_read_b128 v[210:213], v175 offset:49152
	ds_read_b128 v[214:217], v175 offset:50176
	ds_read_b128 v[218:221], v175 offset:51200
	ds_read_b128 v[222:225], v175 offset:52224
	ds_read_b128 v[226:229], v175 offset:53248
	ds_read_b128 v[230:233], v175 offset:54272
	ds_read_b128 v[234:237], v175 offset:55296
	ds_read_b128 v[238:241], v175 offset:56320
	global_load_lds_dwordx4 v[170:171], off
	s_add_i32 m0, s6, 0x2000
	s_add_u32 s26, s62, 0x80080
	v_lshl_add_u64 v[170:171], v[176:177], 0, s[16:17]
	s_addc_u32 s27, s63, 0
	s_add_i32 s6, s55, s24
	global_load_lds_dwordx4 v[170:171], off
	v_lshl_add_u64 v[170:171], s[26:27], 0, v[0:1]
	s_mov_b32 m0, s6
	s_nop 0
	global_load_lds_dwordx4 v[170:171], off
	v_lshl_add_u64 v[170:171], s[26:27], 0, v[160:161]
	s_add_i32 m0, s6, 0x2000
	s_nop 0
	global_load_lds_dwordx4 v[170:171], off
	v_lshl_add_u64 v[170:171], v[242:243], 0, s[16:17]
	s_mov_b32 m0, s9
	s_nop 0
	global_load_lds_dwordx4 v[170:171], off
	v_lshl_add_u64 v[170:171], v[244:245], 0, s[16:17]
	s_mov_b32 m0, s12
	s_nop 0
	global_load_lds_dwordx4 v[170:171], off
	s_waitcnt vmcnt(8)
	s_waitcnt lgkmcnt(0)
	s_barrier
	s_setprio 1
	s_waitcnt lgkmcnt(0)
	v_mfma_f32_16x16x32_bf16 v[62:65], v[126:129], v[210:213], v[62:65]
	v_mfma_f32_16x16x32_bf16 v[58:61], v[134:137], v[210:213], v[58:61]
	v_mfma_f32_16x16x32_bf16 v[46:49], v[126:129], v[218:221], v[46:49]
	v_mfma_f32_16x16x32_bf16 v[42:45], v[134:137], v[218:221], v[42:45]
	v_mfma_f32_16x16x32_bf16 v[30:33], v[126:129], v[226:229], v[30:33]
	v_mfma_f32_16x16x32_bf16 v[26:29], v[134:137], v[226:229], v[26:29]
	v_mfma_f32_16x16x32_bf16 v[14:17], v[126:129], v[234:237], v[14:17]
	v_mfma_f32_16x16x32_bf16 v[10:13], v[134:137], v[234:237], v[10:13]
	v_mfma_f32_16x16x32_bf16 v[62:65], v[130:133], v[214:217], v[62:65]
	v_mfma_f32_16x16x32_bf16 v[58:61], v[142:145], v[214:217], v[58:61]
	v_mfma_f32_16x16x32_bf16 v[46:49], v[130:133], v[222:225], v[46:49]
	v_mfma_f32_16x16x32_bf16 v[42:45], v[142:145], v[222:225], v[42:45]
	v_mfma_f32_16x16x32_bf16 v[30:33], v[130:133], v[230:233], v[30:33]
	v_mfma_f32_16x16x32_bf16 v[26:29], v[142:145], v[230:233], v[26:29]
	v_mfma_f32_16x16x32_bf16 v[14:17], v[130:133], v[238:241], v[14:17]
	v_mfma_f32_16x16x32_bf16 v[10:13], v[142:145], v[238:241], v[10:13]
	s_setprio 0
	s_setprio 1
	v_mfma_f32_16x16x32_bf16 v[54:57], v[166:169], v[210:213], v[54:57]
	v_mfma_f32_16x16x32_bf16 v[50:53], v[202:205], v[210:213], v[50:53]
	v_mfma_f32_16x16x32_bf16 v[38:41], v[166:169], v[218:221], v[38:41]
	v_mfma_f32_16x16x32_bf16 v[34:37], v[202:205], v[218:221], v[34:37]
	v_mfma_f32_16x16x32_bf16 v[22:25], v[166:169], v[226:229], v[22:25]
	v_mfma_f32_16x16x32_bf16 v[18:21], v[202:205], v[226:229], v[18:21]
	v_mfma_f32_16x16x32_bf16 v[6:9], v[166:169], v[234:237], v[6:9]
	v_mfma_f32_16x16x32_bf16 v[2:5], v[202:205], v[234:237], v[2:5]
	v_mfma_f32_16x16x32_bf16 v[54:57], v[198:201], v[214:217], v[54:57]
	v_mfma_f32_16x16x32_bf16 v[50:53], v[206:209], v[214:217], v[50:53]
	v_mfma_f32_16x16x32_bf16 v[38:41], v[198:201], v[222:225], v[38:41]
	v_mfma_f32_16x16x32_bf16 v[34:37], v[206:209], v[222:225], v[34:37]
	v_mfma_f32_16x16x32_bf16 v[22:25], v[198:201], v[230:233], v[22:25]
	v_mfma_f32_16x16x32_bf16 v[18:21], v[206:209], v[230:233], v[18:21]
	v_mfma_f32_16x16x32_bf16 v[6:9], v[198:201], v[238:241], v[6:9]
	v_mfma_f32_16x16x32_bf16 v[2:5], v[206:209], v[238:241], v[2:5]
	s_setprio 0
	s_barrier
	s_add_i32 s54, s54, 2
	s_add_u32 s60, s60, 0x100
	s_addc_u32 s61, s61, 0
	s_add_u32 s47, s47, 0x100
	s_addc_u32 s49, s49, 0
	s_cmp_gt_u32 s54, 29
	s_cbranch_scc0 .LBB0_760
	s_and_b64 vcc, exec, s[44:45]
	s_cbranch_vccz .LBB0_763
	s_barrier
